# adds LayerNorm-epilogue gamma/beta and dequant-scale load batching, up-GEMM table fill load batching
# speedup vs baseline: 1.0228x; 1.0064x over previous
.LBB0_415:
	s_lshl_b32 s0, s3, 10
	s_lshl_b64 s[8:9], s[0:1], 2
	v_readlane_b32 s3, v253, 4
	s_add_u32 s8, s3, s8
	v_readlane_b32 s3, v253, 5
	s_addc_u32 s9, s3, s9
	v_lshl_add_u64 v[20:21], v[160:161], 2, s[8:9]
	global_load_dwordx4 v[196:199], v[20:21], off
	global_load_dwordx4 v[200:203], v[20:21], off offset:64
	global_load_dwordx4 v[204:207], v[20:21], off offset:512
	global_load_dwordx4 v[208:211], v[20:21], off offset:576
	s_mov_b32 s8, 0x3a800000
	s_lshl_b32 s10, s23, 5
	v_readlane_b32 s3, v254, 17
	s_add_i32 s3, s3, s10
	s_lshl_b32 s11, s34, 2
	v_cmp_gt_u32_e32 vcc, 16, v178
	s_waitcnt vmcnt(0)
	v_pk_mul_f32 v[174:175], v[196:197], s[8:9] op_sel_hi:[1,0]
	v_pk_mul_f32 v[176:177], v[198:199], s[8:9] op_sel_hi:[1,0]
	v_pk_mul_f32 v[170:171], v[200:201], s[8:9] op_sel_hi:[1,0]
	v_pk_mul_f32 v[172:173], v[202:203], s[8:9] op_sel_hi:[1,0]
	v_pk_mul_f32 v[166:167], v[204:205], s[8:9] op_sel_hi:[1,0]
	v_pk_mul_f32 v[168:169], v[206:207], s[8:9] op_sel_hi:[1,0]
	v_mbcnt_lo_u32_b32 v30, -1, 0
	v_mbcnt_hi_u32_b32 v30, -1, v30
	v_pk_mul_f32 v[162:163], v[208:209], s[8:9] op_sel_hi:[1,0]
	v_pk_mul_f32 v[164:165], v[210:211], s[8:9] op_sel_hi:[1,0]
	v_ashrrev_i32_e32 v31, 5, v30
	v_add_u32_e32 v16, s3, v31
	v_and_b32_e32 v180, 31, v30
	v_ashrrev_i32_e32 v17, 31, v16
	v_readlane_b32 s8, v253, 47
	v_lshlrev_b64 v[16:17], 11, v[16:17]
	v_readlane_b32 s9, v253, 48
	s_lshl_b32 s3, s23, 14
	v_bitop3_b32 v18, v31, v180, 15 bitop3:0x6c
	v_lshl_add_u64 v[16:17], s[8:9], 0, v[16:17]
	s_add_i32 s3, s3, 0
	v_lshlrev_b32_e32 v230, 4, v18
	v_lshl_add_u64 v[18:19], v[16:17], 0, v[230:231]
	s_mov_b32 m0, s3
	s_mov_b64 s[8:9], 0x1000
	global_load_lds_dwordx4 v[18:19], off
	v_lshl_add_u64 v[18:19], v[16:17], 0, s[8:9]
	v_add_u32_e32 v16, 2, v31
	v_bitop3_b32 v16, v16, v180, 15 bitop3:0x6c
	v_lshlrev_b32_e32 v16, 4, v16
	v_mov_b32_e32 v17, v231
	s_add_i32 m0, s3, 0x400
	v_lshl_add_u64 v[20:21], v[18:19], 0, v[16:17]
	global_load_lds_dwordx4 v[20:21], off
	v_lshl_add_u64 v[20:21], v[18:19], 0, s[8:9]
	v_add_u32_e32 v18, 4, v31
	v_bitop3_b32 v18, v18, v180, 15 bitop3:0x6c
	v_lshlrev_b32_e32 v18, 4, v18
	v_mov_b32_e32 v19, v231
	s_add_i32 m0, s3, 0x800
	v_lshl_add_u64 v[22:23], v[20:21], 0, v[18:19]
	global_load_lds_dwordx4 v[22:23], off
	v_lshl_add_u64 v[22:23], v[20:21], 0, s[8:9]
	v_add_u32_e32 v20, 6, v31
	v_bitop3_b32 v20, v20, v180, 15 bitop3:0x6c
	v_lshlrev_b32_e32 v20, 4, v20
	v_mov_b32_e32 v21, v231
	s_add_i32 m0, s3, 0xc00
	v_lshl_add_u64 v[24:25], v[22:23], 0, v[20:21]
	global_load_lds_dwordx4 v[24:25], off
	v_lshl_add_u64 v[24:25], v[22:23], 0, s[8:9]
	v_xor_b32_e32 v22, 0x80, v230
	v_mov_b32_e32 v23, v231
	s_add_i32 m0, s3, 0x1000
	v_lshl_add_u64 v[26:27], v[24:25], 0, v[22:23]
	global_load_lds_dwordx4 v[26:27], off
	v_lshl_add_u64 v[26:27], v[24:25], 0, s[8:9]
	v_add_u32_e32 v24, 10, v31
	v_bitop3_b32 v24, v24, v180, 15 bitop3:0x6c
	v_lshlrev_b32_e32 v24, 4, v24
	v_mov_b32_e32 v25, v231
	s_add_i32 m0, s3, 0x1400
	v_lshl_add_u64 v[28:29], v[26:27], 0, v[24:25]
	global_load_lds_dwordx4 v[28:29], off
	v_add_u32_e32 v28, 12, v31
	v_lshl_add_u64 v[26:27], v[26:27], 0, s[8:9]
	v_bitop3_b32 v28, v28, v180, 15 bitop3:0x6c
	v_lshlrev_b32_e32 v28, 4, v28
	v_mov_b32_e32 v29, v231
	v_add_u32_e32 v181, 14, v31
	v_lshl_add_u64 v[182:183], v[26:27], 0, v[28:29]
	s_add_i32 m0, s3, 0x1800
	v_lshl_add_u64 v[26:27], v[26:27], 0, s[8:9]
	v_bitop3_b32 v180, v181, v180, 15 bitop3:0x6c
	global_load_lds_dwordx4 v[182:183], off
	v_lshlrev_b32_e32 v180, 4, v180
	v_mov_b32_e32 v181, v231
	v_lshl_add_u64 v[182:183], v[26:27], 0, v[180:181]
	s_add_i32 m0, s3, 0x1c00
	v_lshl_add_u64 v[26:27], v[26:27], 0, s[8:9]
	global_load_lds_dwordx4 v[182:183], off
	s_add_i32 m0, s3, 0x2000
	v_lshl_add_u64 v[182:183], v[26:27], 0, v[230:231]
	v_lshl_add_u64 v[26:27], v[26:27], 0, s[8:9]
	global_load_lds_dwordx4 v[182:183], off
	s_add_i32 m0, s3, 0x2400
	v_lshl_add_u64 v[16:17], v[26:27], 0, v[16:17]
	global_load_lds_dwordx4 v[16:17], off
	v_lshl_add_u64 v[16:17], v[26:27], 0, s[8:9]
	s_add_i32 m0, s3, 0x2800
	v_lshl_add_u64 v[18:19], v[16:17], 0, v[18:19]
	v_lshl_add_u64 v[16:17], v[16:17], 0, s[8:9]
	global_load_lds_dwordx4 v[18:19], off
	s_add_i32 m0, s3, 0x2c00
	v_lshl_add_u64 v[18:19], v[16:17], 0, v[20:21]
	v_lshl_add_u64 v[16:17], v[16:17], 0, s[8:9]
	global_load_lds_dwordx4 v[18:19], off
	s_add_i32 m0, s3, 0x3000
	v_lshl_add_u64 v[18:19], v[16:17], 0, v[22:23]
	v_lshl_add_u64 v[16:17], v[16:17], 0, s[8:9]
	global_load_lds_dwordx4 v[18:19], off
	s_add_i32 m0, s3, 0x3400
	v_lshl_add_u64 v[18:19], v[16:17], 0, v[24:25]
	v_lshl_add_u64 v[16:17], v[16:17], 0, s[8:9]
	global_load_lds_dwordx4 v[18:19], off
	s_add_i32 m0, s3, 0x3800
	v_lshl_add_u64 v[18:19], v[16:17], 0, v[28:29]
	v_lshl_add_u64 v[16:17], v[16:17], 0, s[8:9]
	global_load_lds_dwordx4 v[18:19], off
	s_add_i32 m0, s3, 0x3c00
	v_lshl_add_u64 v[18:19], v[16:17], 0, v[180:181]
	v_lshl_add_u64 v[16:17], v[16:17], 0, s[8:9]
	global_load_lds_dwordx4 v[18:19], off
	v_lshrrev_b32_e32 v18, 1, v30
	v_lshlrev_b32_e32 v17, 9, v30
	v_and_b32_e32 v17, 0x200, v17
	v_and_b32_e32 v18, 8, v18
	v_add_u32_e32 v28, s11, v31
	v_and_b32_e32 v16, 15, v30
	v_add3_u32 v183, 0, v17, v18
	v_add_u32_e32 v17, 16, v28
	v_bitop3_b32 v17, v17, v30, 15 bitop3:0x78
	s_lshl_b32 s3, s22, 15
	v_lshlrev_b32_e32 v16, 9, v16
	v_lshlrev_b32_e32 v180, 4, v17
	v_or_b32_e32 v184, s3, v16
	v_mov_b32_e32 v17, s3
	s_movk_i32 s3, 0x9c00
	v_bitop3_b32 v16, v16, s3, v17 bitop3:0xc8
	v_add_u32_e32 v181, v183, v16
	v_bitop3_b32 v16, v28, v30, 15 bitop3:0x78
	v_lshlrev_b32_e32 v182, 4, v16
	s_waitcnt vmcnt(0)
	s_barrier
	v_add_u32_e32 v185, v181, v182
	ds_read_b64 v[16:17], v185
	s_mov_b32 s8, 0x3fd744fd
	s_lshl_b32 s3, s34, 3
	s_add_i32 s12, s3, 0
	s_waitcnt lgkmcnt(0)
	v_cvt_f32_f16_e32 v18, v16
	v_cvt_f32_f16_sdwa v19, v16 dst_sel:DWORD dst_unused:UNUSED_PAD src0_sel:WORD_1
	v_cvt_f32_f16_e32 v16, v17
	v_cvt_f32_f16_sdwa v17, v17 dst_sel:DWORD dst_unused:UNUSED_PAD src0_sel:WORD_1
	v_pk_mul_f32 v[20:21], v[18:19], s[8:9] op_sel_hi:[1,0]
	v_pk_mul_f32 v[16:17], v[16:17], s[8:9] op_sel_hi:[1,0]
	s_nop 0
	v_pk_fma_f32 v[18:19], v[158:159], v[176:177], v[16:17]
	v_pk_fma_f32 v[16:17], v[156:157], v[174:175], v[20:21]
	v_add_u32_e32 v20, 2, v28
	v_bitop3_b32 v20, v20, v30, 15 bitop3:0x78
	v_lshlrev_b32_e32 v156, 4, v20
	v_add_u32_e32 v157, v181, v156
	ds_read_b64 v[20:21], v157
	s_waitcnt lgkmcnt(0)
	v_cvt_f32_f16_e32 v22, v20
	v_cvt_f32_f16_sdwa v23, v20 dst_sel:DWORD dst_unused:UNUSED_PAD src0_sel:WORD_1
	v_cvt_f32_f16_e32 v20, v21
	v_cvt_f32_f16_sdwa v21, v21 dst_sel:DWORD dst_unused:UNUSED_PAD src0_sel:WORD_1
	v_pk_mul_f32 v[22:23], v[22:23], s[8:9] op_sel_hi:[1,0]
	s_nop 0
	v_pk_fma_f32 v[24:25], v[152:153], v[170:171], v[22:23]
	v_pk_mul_f32 v[20:21], v[20:21], s[8:9] op_sel_hi:[1,0]
	v_add_u32_e32 v153, v181, v180
	v_pk_fma_f32 v[26:27], v[154:155], v[172:173], v[20:21]
	ds_read_b64 v[20:21], v153
	s_waitcnt lgkmcnt(0)
	v_cvt_f32_f16_e32 v22, v20
	v_cvt_f32_f16_sdwa v23, v20 dst_sel:DWORD dst_unused:UNUSED_PAD src0_sel:WORD_1
	v_cvt_f32_f16_e32 v20, v21
	v_cvt_f32_f16_sdwa v21, v21 dst_sel:DWORD dst_unused:UNUSED_PAD src0_sel:WORD_1
	v_pk_mul_f32 v[22:23], v[22:23], s[8:9] op_sel_hi:[1,0]
	s_nop 0
	v_pk_fma_f32 v[148:149], v[148:149], v[166:167], v[22:23]
	v_pk_mul_f32 v[20:21], v[20:21], s[8:9] op_sel_hi:[1,0]
	s_nop 0
	v_pk_fma_f32 v[150:151], v[150:151], v[168:169], v[20:21]
	v_add_u32_e32 v20, 18, v28
	v_bitop3_b32 v20, v20, v30, 15 bitop3:0x78
	v_lshlrev_b32_e32 v152, 4, v20
	v_add_u32_e32 v154, v181, v152
	ds_read_b64 v[20:21], v154
	s_waitcnt lgkmcnt(0)
	v_cvt_f32_f16_e32 v22, v20
	v_cvt_f32_f16_sdwa v23, v20 dst_sel:DWORD dst_unused:UNUSED_PAD src0_sel:WORD_1
	v_cvt_f32_f16_e32 v20, v21
	v_cvt_f32_f16_sdwa v21, v21 dst_sel:DWORD dst_unused:UNUSED_PAD src0_sel:WORD_1
	v_pk_mul_f32 v[22:23], v[22:23], s[8:9] op_sel_hi:[1,0]
	s_nop 0
	v_pk_fma_f32 v[144:145], v[144:145], v[162:163], v[22:23]
	v_pk_mul_f32 v[20:21], v[20:21], s[8:9] op_sel_hi:[1,0]
	s_nop 0
	v_pk_fma_f32 v[146:147], v[146:147], v[164:165], v[20:21]
	s_nop 0
	ds_read_b64 v[20:21], v185 offset:8192
	s_waitcnt lgkmcnt(0)
	v_cvt_f32_f16_e32 v22, v20
	v_cvt_f32_f16_sdwa v23, v20 dst_sel:DWORD dst_unused:UNUSED_PAD src0_sel:WORD_1
	v_cvt_f32_f16_e32 v20, v21
	v_cvt_f32_f16_sdwa v21, v21 dst_sel:DWORD dst_unused:UNUSED_PAD src0_sel:WORD_1
	v_pk_mul_f32 v[28:29], v[22:23], s[8:9] op_sel_hi:[1,0]
	v_pk_mul_f32 v[20:21], v[20:21], s[8:9] op_sel_hi:[1,0]
	s_nop 0
	v_pk_fma_f32 v[22:23], v[142:143], v[176:177], v[20:21]
	v_pk_fma_f32 v[20:21], v[140:141], v[174:175], v[28:29]
	ds_read_b64 v[28:29], v157 offset:8192
	v_pk_add_f32 v[142:143], v[0:1], v[24:25]
	v_lshlrev_b32_e32 v24, 2, v178
	s_waitcnt lgkmcnt(0)
	v_cvt_f32_f16_e32 v30, v28
	v_cvt_f32_f16_sdwa v31, v28 dst_sel:DWORD dst_unused:UNUSED_PAD src0_sel:WORD_1
	v_cvt_f32_f16_e32 v28, v29
	v_cvt_f32_f16_sdwa v29, v29 dst_sel:DWORD dst_unused:UNUSED_PAD src0_sel:WORD_1
	v_pk_mul_f32 v[140:141], v[30:31], s[8:9] op_sel_hi:[1,0]
	v_pk_mul_f32 v[28:29], v[28:29], s[8:9] op_sel_hi:[1,0]
	s_nop 0
	v_pk_fma_f32 v[30:31], v[138:139], v[172:173], v[28:29]
	v_pk_fma_f32 v[28:29], v[136:137], v[170:171], v[140:141]
	ds_read_b64 v[136:137], v153 offset:8192
	v_add_u32_e32 v140, 0x10000, v181
	s_waitcnt lgkmcnt(0)
	v_cvt_f32_f16_e32 v138, v136
	v_cvt_f32_f16_sdwa v139, v136 dst_sel:DWORD dst_unused:UNUSED_PAD src0_sel:WORD_1
	v_cvt_f32_f16_e32 v136, v137
	v_cvt_f32_f16_sdwa v137, v137 dst_sel:DWORD dst_unused:UNUSED_PAD src0_sel:WORD_1
	v_pk_mul_f32 v[138:139], v[138:139], s[8:9] op_sel_hi:[1,0]
	s_nop 0
	v_pk_fma_f32 v[132:133], v[132:133], v[166:167], v[138:139]
	v_pk_mul_f32 v[136:137], v[136:137], s[8:9] op_sel_hi:[1,0]
	s_nop 0
	v_pk_fma_f32 v[134:135], v[134:135], v[168:169], v[136:137]
	ds_read_b64 v[136:137], v154 offset:8192
	s_waitcnt lgkmcnt(0)
	v_cvt_f32_f16_e32 v138, v136
	v_cvt_f32_f16_sdwa v139, v136 dst_sel:DWORD dst_unused:UNUSED_PAD src0_sel:WORD_1
	v_cvt_f32_f16_e32 v136, v137
	v_cvt_f32_f16_sdwa v137, v137 dst_sel:DWORD dst_unused:UNUSED_PAD src0_sel:WORD_1
	v_pk_mul_f32 v[138:139], v[138:139], s[8:9] op_sel_hi:[1,0]
	s_nop 0
	v_pk_fma_f32 v[128:129], v[128:129], v[162:163], v[138:139]
	v_pk_mul_f32 v[136:137], v[136:137], s[8:9] op_sel_hi:[1,0]
	s_nop 0
	v_pk_fma_f32 v[130:131], v[130:131], v[164:165], v[136:137]
	s_nop 0
	ds_read_b64 v[136:137], v185 offset:16384
	s_waitcnt lgkmcnt(0)
	v_cvt_f32_f16_e32 v138, v136
	v_cvt_f32_f16_sdwa v139, v136 dst_sel:DWORD dst_unused:UNUSED_PAD src0_sel:WORD_1
	v_cvt_f32_f16_e32 v136, v137
	v_cvt_f32_f16_sdwa v137, v137 dst_sel:DWORD dst_unused:UNUSED_PAD src0_sel:WORD_1
	v_pk_mul_f32 v[138:139], v[138:139], s[8:9] op_sel_hi:[1,0]
	s_nop 0
	v_pk_fma_f32 v[124:125], v[124:125], v[174:175], v[138:139]
	v_pk_mul_f32 v[136:137], v[136:137], s[8:9] op_sel_hi:[1,0]
	s_nop 0
	v_pk_fma_f32 v[126:127], v[126:127], v[176:177], v[136:137]
	ds_read_b64 v[136:137], v157 offset:16384
	s_waitcnt lgkmcnt(0)
	v_cvt_f32_f16_e32 v138, v136
	v_cvt_f32_f16_sdwa v139, v136 dst_sel:DWORD dst_unused:UNUSED_PAD src0_sel:WORD_1
	v_cvt_f32_f16_e32 v136, v137
	v_cvt_f32_f16_sdwa v137, v137 dst_sel:DWORD dst_unused:UNUSED_PAD src0_sel:WORD_1
	v_pk_mul_f32 v[138:139], v[138:139], s[8:9] op_sel_hi:[1,0]
	s_nop 0
	v_pk_fma_f32 v[120:121], v[120:121], v[170:171], v[138:139]
	v_pk_mul_f32 v[136:137], v[136:137], s[8:9] op_sel_hi:[1,0]
	s_nop 0
	v_pk_fma_f32 v[122:123], v[122:123], v[172:173], v[136:137]
	ds_read_b64 v[136:137], v153 offset:16384
	s_waitcnt lgkmcnt(0)
	v_cvt_f32_f16_e32 v138, v136
	v_cvt_f32_f16_sdwa v139, v136 dst_sel:DWORD dst_unused:UNUSED_PAD src0_sel:WORD_1
	v_cvt_f32_f16_e32 v136, v137
	v_cvt_f32_f16_sdwa v137, v137 dst_sel:DWORD dst_unused:UNUSED_PAD src0_sel:WORD_1
	v_pk_mul_f32 v[138:139], v[138:139], s[8:9] op_sel_hi:[1,0]
	s_nop 0
	v_pk_fma_f32 v[116:117], v[116:117], v[166:167], v[138:139]
	v_pk_mul_f32 v[136:137], v[136:137], s[8:9] op_sel_hi:[1,0]
	s_nop 0
	v_pk_fma_f32 v[118:119], v[118:119], v[168:169], v[136:137]
	ds_read_b64 v[136:137], v154 offset:16384
	s_waitcnt lgkmcnt(0)
	v_cvt_f32_f16_e32 v138, v136
	v_cvt_f32_f16_sdwa v139, v136 dst_sel:DWORD dst_unused:UNUSED_PAD src0_sel:WORD_1
	v_cvt_f32_f16_e32 v136, v137
	v_cvt_f32_f16_sdwa v137, v137 dst_sel:DWORD dst_unused:UNUSED_PAD src0_sel:WORD_1
	v_pk_mul_f32 v[138:139], v[138:139], s[8:9] op_sel_hi:[1,0]
	s_nop 0
	v_pk_fma_f32 v[112:113], v[112:113], v[162:163], v[138:139]
	v_pk_mul_f32 v[136:137], v[136:137], s[8:9] op_sel_hi:[1,0]
	s_nop 0
	v_pk_fma_f32 v[114:115], v[114:115], v[164:165], v[136:137]
	s_nop 0
	ds_read_b64 v[136:137], v185 offset:24576
	s_waitcnt lgkmcnt(0)
	v_cvt_f32_f16_e32 v138, v136
	v_cvt_f32_f16_sdwa v139, v136 dst_sel:DWORD dst_unused:UNUSED_PAD src0_sel:WORD_1
	v_cvt_f32_f16_e32 v136, v137
	v_cvt_f32_f16_sdwa v137, v137 dst_sel:DWORD dst_unused:UNUSED_PAD src0_sel:WORD_1
	v_pk_mul_f32 v[138:139], v[138:139], s[8:9] op_sel_hi:[1,0]
	s_nop 0
	v_pk_fma_f32 v[108:109], v[108:109], v[174:175], v[138:139]
	v_pk_mul_f32 v[136:137], v[136:137], s[8:9] op_sel_hi:[1,0]
	s_nop 0
	v_pk_fma_f32 v[110:111], v[110:111], v[176:177], v[136:137]
	ds_read_b64 v[136:137], v157 offset:24576
	v_xor_b32_e32 v157, 64, v24
	s_waitcnt lgkmcnt(0)
	v_cvt_f32_f16_e32 v138, v136
	v_cvt_f32_f16_sdwa v139, v136 dst_sel:DWORD dst_unused:UNUSED_PAD src0_sel:WORD_1
	v_cvt_f32_f16_e32 v136, v137
	v_cvt_f32_f16_sdwa v137, v137 dst_sel:DWORD dst_unused:UNUSED_PAD src0_sel:WORD_1
	v_pk_mul_f32 v[138:139], v[138:139], s[8:9] op_sel_hi:[1,0]
	s_nop 0
	v_pk_fma_f32 v[104:105], v[104:105], v[170:171], v[138:139]
	v_pk_mul_f32 v[136:137], v[136:137], s[8:9] op_sel_hi:[1,0]
	s_nop 0
	v_pk_fma_f32 v[106:107], v[106:107], v[172:173], v[136:137]
	ds_read_b64 v[136:137], v153 offset:24576
	s_waitcnt lgkmcnt(0)
	v_cvt_f32_f16_e32 v138, v136
	v_cvt_f32_f16_sdwa v139, v136 dst_sel:DWORD dst_unused:UNUSED_PAD src0_sel:WORD_1
	v_cvt_f32_f16_e32 v136, v137
	v_cvt_f32_f16_sdwa v137, v137 dst_sel:DWORD dst_unused:UNUSED_PAD src0_sel:WORD_1
	v_pk_mul_f32 v[138:139], v[138:139], s[8:9] op_sel_hi:[1,0]
	s_nop 0
	v_pk_fma_f32 v[100:101], v[100:101], v[166:167], v[138:139]
	v_pk_mul_f32 v[136:137], v[136:137], s[8:9] op_sel_hi:[1,0]
	s_nop 0
	v_pk_fma_f32 v[102:103], v[102:103], v[168:169], v[136:137]
	ds_read_b64 v[136:137], v154 offset:24576
	v_pk_add_f32 v[154:155], v[4:5], v[16:17]
	v_pk_add_f32 v[16:17], v[10:11], v[146:147]
	s_waitcnt lgkmcnt(0)
	v_cvt_f32_f16_e32 v138, v136
	v_cvt_f32_f16_sdwa v139, v136 dst_sel:DWORD dst_unused:UNUSED_PAD src0_sel:WORD_1
	v_cvt_f32_f16_e32 v136, v137
	v_cvt_f32_f16_sdwa v137, v137 dst_sel:DWORD dst_unused:UNUSED_PAD src0_sel:WORD_1
	v_pk_mul_f32 v[138:139], v[138:139], s[8:9] op_sel_hi:[1,0]
	s_nop 0
	v_pk_fma_f32 v[96:97], v[96:97], v[162:163], v[138:139]
	v_pk_mul_f32 v[136:137], v[136:137], s[8:9] op_sel_hi:[1,0]
	s_nop 0
	v_pk_fma_f32 v[98:99], v[98:99], v[164:165], v[136:137]
	v_add_u32_e32 v136, v140, v182
	ds_read_b64 v[136:137], v136
	s_waitcnt lgkmcnt(0)
	v_cvt_f32_f16_e32 v138, v136
	v_cvt_f32_f16_sdwa v139, v136 dst_sel:DWORD dst_unused:UNUSED_PAD src0_sel:WORD_1
	v_cvt_f32_f16_e32 v136, v137
	v_cvt_f32_f16_sdwa v137, v137 dst_sel:DWORD dst_unused:UNUSED_PAD src0_sel:WORD_1
	v_pk_mul_f32 v[138:139], v[138:139], s[8:9] op_sel_hi:[1,0]
	s_nop 0
	v_pk_fma_f32 v[92:93], v[92:93], v[174:175], v[138:139]
	v_pk_mul_f32 v[136:137], v[136:137], s[8:9] op_sel_hi:[1,0]
	s_nop 0
	v_pk_fma_f32 v[94:95], v[94:95], v[176:177], v[136:137]
	v_add_u32_e32 v136, v140, v156
	ds_read_b64 v[136:137], v136
	s_waitcnt lgkmcnt(0)
	v_cvt_f32_f16_e32 v138, v136
	v_cvt_f32_f16_sdwa v139, v136 dst_sel:DWORD dst_unused:UNUSED_PAD src0_sel:WORD_1
	v_cvt_f32_f16_e32 v136, v137
	v_cvt_f32_f16_sdwa v137, v137 dst_sel:DWORD dst_unused:UNUSED_PAD src0_sel:WORD_1
	v_pk_mul_f32 v[138:139], v[138:139], s[8:9] op_sel_hi:[1,0]
	s_nop 0
	v_pk_fma_f32 v[88:89], v[88:89], v[170:171], v[138:139]
	v_pk_mul_f32 v[136:137], v[136:137], s[8:9] op_sel_hi:[1,0]
	s_nop 0
	v_pk_fma_f32 v[90:91], v[90:91], v[172:173], v[136:137]
	v_add_u32_e32 v136, v140, v180
	ds_read_b64 v[136:137], v136
	s_waitcnt lgkmcnt(0)
	v_cvt_f32_f16_e32 v138, v136
	v_cvt_f32_f16_sdwa v139, v136 dst_sel:DWORD dst_unused:UNUSED_PAD src0_sel:WORD_1
	v_cvt_f32_f16_e32 v136, v137
	v_cvt_f32_f16_sdwa v137, v137 dst_sel:DWORD dst_unused:UNUSED_PAD src0_sel:WORD_1
	v_pk_mul_f32 v[138:139], v[138:139], s[8:9] op_sel_hi:[1,0]
	s_nop 0
	v_pk_fma_f32 v[84:85], v[84:85], v[166:167], v[138:139]
	v_pk_mul_f32 v[136:137], v[136:137], s[8:9] op_sel_hi:[1,0]
	s_nop 0
	v_pk_fma_f32 v[86:87], v[86:87], v[168:169], v[136:137]
	v_add_u32_e32 v136, v140, v152
	ds_read_b64 v[136:137], v136
	s_waitcnt lgkmcnt(0)
	v_cvt_f32_f16_e32 v138, v136
	v_cvt_f32_f16_sdwa v139, v136 dst_sel:DWORD dst_unused:UNUSED_PAD src0_sel:WORD_1
	v_cvt_f32_f16_e32 v136, v137
	v_cvt_f32_f16_sdwa v137, v137 dst_sel:DWORD dst_unused:UNUSED_PAD src0_sel:WORD_1
	v_pk_mul_f32 v[138:139], v[138:139], s[8:9] op_sel_hi:[1,0]
	s_nop 0
	v_pk_fma_f32 v[80:81], v[80:81], v[162:163], v[138:139]
	v_pk_mul_f32 v[136:137], v[136:137], s[8:9] op_sel_hi:[1,0]
	s_nop 0
	v_pk_fma_f32 v[82:83], v[82:83], v[164:165], v[136:137]
	v_add_u32_e32 v136, 0x12000, v184
	v_and_b32_e32 v136, 0xffffbc00, v136
	v_add_u32_e32 v140, v183, v136
	v_add_u32_e32 v136, v140, v182
	ds_read_b64 v[136:137], v136
	s_waitcnt lgkmcnt(0)
	v_cvt_f32_f16_e32 v138, v136
	v_cvt_f32_f16_sdwa v139, v136 dst_sel:DWORD dst_unused:UNUSED_PAD src0_sel:WORD_1
	v_cvt_f32_f16_e32 v136, v137
	v_cvt_f32_f16_sdwa v137, v137 dst_sel:DWORD dst_unused:UNUSED_PAD src0_sel:WORD_1
	v_pk_mul_f32 v[138:139], v[138:139], s[8:9] op_sel_hi:[1,0]
	s_nop 0
	v_pk_fma_f32 v[76:77], v[76:77], v[174:175], v[138:139]
	v_pk_mul_f32 v[136:137], v[136:137], s[8:9] op_sel_hi:[1,0]
	s_nop 0
	v_pk_fma_f32 v[78:79], v[78:79], v[176:177], v[136:137]
	v_add_u32_e32 v136, v140, v156
	ds_read_b64 v[136:137], v136
	s_waitcnt lgkmcnt(0)
	v_cvt_f32_f16_e32 v138, v136
	v_cvt_f32_f16_sdwa v139, v136 dst_sel:DWORD dst_unused:UNUSED_PAD src0_sel:WORD_1
	v_cvt_f32_f16_e32 v136, v137
	v_cvt_f32_f16_sdwa v137, v137 dst_sel:DWORD dst_unused:UNUSED_PAD src0_sel:WORD_1
	v_pk_mul_f32 v[138:139], v[138:139], s[8:9] op_sel_hi:[1,0]
	s_nop 0
	v_pk_fma_f32 v[72:73], v[72:73], v[170:171], v[138:139]
	v_pk_mul_f32 v[136:137], v[136:137], s[8:9] op_sel_hi:[1,0]
	s_nop 0
	v_pk_fma_f32 v[74:75], v[74:75], v[172:173], v[136:137]
	v_add_u32_e32 v136, v140, v180
	ds_read_b64 v[136:137], v136
	s_waitcnt lgkmcnt(0)
	v_cvt_f32_f16_e32 v138, v136
	v_cvt_f32_f16_sdwa v139, v136 dst_sel:DWORD dst_unused:UNUSED_PAD src0_sel:WORD_1
	v_cvt_f32_f16_e32 v136, v137
	v_cvt_f32_f16_sdwa v137, v137 dst_sel:DWORD dst_unused:UNUSED_PAD src0_sel:WORD_1
	v_pk_mul_f32 v[138:139], v[138:139], s[8:9] op_sel_hi:[1,0]
	s_nop 0
	v_pk_fma_f32 v[68:69], v[68:69], v[166:167], v[138:139]
	v_pk_mul_f32 v[136:137], v[136:137], s[8:9] op_sel_hi:[1,0]
	s_nop 0
	v_pk_fma_f32 v[70:71], v[70:71], v[168:169], v[136:137]
	v_add_u32_e32 v136, v140, v152
	ds_read_b64 v[136:137], v136
	v_add_u32_e32 v140, 0x14000, v181
	s_waitcnt lgkmcnt(0)
	v_cvt_f32_f16_e32 v138, v136
	v_cvt_f32_f16_sdwa v139, v136 dst_sel:DWORD dst_unused:UNUSED_PAD src0_sel:WORD_1
	v_cvt_f32_f16_e32 v136, v137
	v_cvt_f32_f16_sdwa v137, v137 dst_sel:DWORD dst_unused:UNUSED_PAD src0_sel:WORD_1
	v_pk_mul_f32 v[138:139], v[138:139], s[8:9] op_sel_hi:[1,0]
	s_nop 0
	v_pk_fma_f32 v[64:65], v[64:65], v[162:163], v[138:139]
	v_pk_mul_f32 v[136:137], v[136:137], s[8:9] op_sel_hi:[1,0]
	s_nop 0
	v_pk_fma_f32 v[66:67], v[66:67], v[164:165], v[136:137]
	v_add_u32_e32 v136, v140, v182
	ds_read_b64 v[136:137], v136
	s_waitcnt lgkmcnt(0)
	v_cvt_f32_f16_e32 v138, v136
	v_cvt_f32_f16_sdwa v139, v136 dst_sel:DWORD dst_unused:UNUSED_PAD src0_sel:WORD_1
	v_cvt_f32_f16_e32 v136, v137
	v_cvt_f32_f16_sdwa v137, v137 dst_sel:DWORD dst_unused:UNUSED_PAD src0_sel:WORD_1
	v_pk_mul_f32 v[138:139], v[138:139], s[8:9] op_sel_hi:[1,0]
	s_nop 0
	v_pk_fma_f32 v[60:61], v[60:61], v[174:175], v[138:139]
	v_pk_mul_f32 v[136:137], v[136:137], s[8:9] op_sel_hi:[1,0]
	s_nop 0
	v_pk_fma_f32 v[62:63], v[62:63], v[176:177], v[136:137]
	v_add_u32_e32 v136, v140, v156
	ds_read_b64 v[136:137], v136
	s_waitcnt lgkmcnt(0)
	v_cvt_f32_f16_e32 v138, v136
	v_cvt_f32_f16_sdwa v139, v136 dst_sel:DWORD dst_unused:UNUSED_PAD src0_sel:WORD_1
	v_cvt_f32_f16_e32 v136, v137
	v_cvt_f32_f16_sdwa v137, v137 dst_sel:DWORD dst_unused:UNUSED_PAD src0_sel:WORD_1
	v_pk_mul_f32 v[138:139], v[138:139], s[8:9] op_sel_hi:[1,0]
	s_nop 0
	v_pk_fma_f32 v[56:57], v[56:57], v[170:171], v[138:139]
	v_pk_mul_f32 v[136:137], v[136:137], s[8:9] op_sel_hi:[1,0]
	s_nop 0
	v_pk_fma_f32 v[58:59], v[58:59], v[172:173], v[136:137]
	v_add_u32_e32 v136, v140, v180
	ds_read_b64 v[136:137], v136
	s_waitcnt lgkmcnt(0)
	v_cvt_f32_f16_e32 v138, v136
	v_cvt_f32_f16_sdwa v139, v136 dst_sel:DWORD dst_unused:UNUSED_PAD src0_sel:WORD_1
	v_cvt_f32_f16_e32 v136, v137
	v_cvt_f32_f16_sdwa v137, v137 dst_sel:DWORD dst_unused:UNUSED_PAD src0_sel:WORD_1
	v_pk_mul_f32 v[138:139], v[138:139], s[8:9] op_sel_hi:[1,0]
	s_nop 0
	v_pk_fma_f32 v[52:53], v[52:53], v[166:167], v[138:139]
	v_pk_mul_f32 v[136:137], v[136:137], s[8:9] op_sel_hi:[1,0]
	s_nop 0
	v_pk_fma_f32 v[54:55], v[54:55], v[168:169], v[136:137]
	v_add_u32_e32 v136, v140, v152
	ds_read_b64 v[136:137], v136
	v_add_u32_e32 v140, 0x16000, v181
	s_waitcnt lgkmcnt(0)
	v_cvt_f32_f16_e32 v138, v136
	v_cvt_f32_f16_sdwa v139, v136 dst_sel:DWORD dst_unused:UNUSED_PAD src0_sel:WORD_1
	v_cvt_f32_f16_e32 v136, v137
	v_cvt_f32_f16_sdwa v137, v137 dst_sel:DWORD dst_unused:UNUSED_PAD src0_sel:WORD_1
	v_pk_mul_f32 v[138:139], v[138:139], s[8:9] op_sel_hi:[1,0]
	s_nop 0
	v_pk_fma_f32 v[48:49], v[48:49], v[162:163], v[138:139]
	v_pk_mul_f32 v[136:137], v[136:137], s[8:9] op_sel_hi:[1,0]
	s_nop 0
	v_pk_fma_f32 v[50:51], v[50:51], v[164:165], v[136:137]
	v_add_u32_e32 v136, v140, v182
	ds_read_b64 v[136:137], v136
	s_waitcnt lgkmcnt(0)
	v_cvt_f32_f16_e32 v138, v136
	v_cvt_f32_f16_sdwa v139, v136 dst_sel:DWORD dst_unused:UNUSED_PAD src0_sel:WORD_1
	v_cvt_f32_f16_e32 v136, v137
	v_cvt_f32_f16_sdwa v137, v137 dst_sel:DWORD dst_unused:UNUSED_PAD src0_sel:WORD_1
	v_pk_mul_f32 v[138:139], v[138:139], s[8:9] op_sel_hi:[1,0]
	s_nop 0
	v_pk_fma_f32 v[44:45], v[44:45], v[174:175], v[138:139]
	v_pk_mul_f32 v[136:137], v[136:137], s[8:9] op_sel_hi:[1,0]
	s_nop 0
	v_pk_fma_f32 v[46:47], v[46:47], v[176:177], v[136:137]
	v_add_u32_e32 v136, v140, v156
	ds_read_b64 v[136:137], v136
	v_xor_b32_e32 v156, 0x80, v24
	s_waitcnt lgkmcnt(0)
	v_cvt_f32_f16_e32 v138, v136
	v_cvt_f32_f16_sdwa v139, v136 dst_sel:DWORD dst_unused:UNUSED_PAD src0_sel:WORD_1
	v_cvt_f32_f16_e32 v136, v137
	v_cvt_f32_f16_sdwa v137, v137 dst_sel:DWORD dst_unused:UNUSED_PAD src0_sel:WORD_1
	v_pk_mul_f32 v[138:139], v[138:139], s[8:9] op_sel_hi:[1,0]
	s_nop 0
	v_pk_fma_f32 v[40:41], v[40:41], v[170:171], v[138:139]
	v_pk_mul_f32 v[136:137], v[136:137], s[8:9] op_sel_hi:[1,0]
	s_nop 0
	v_pk_fma_f32 v[42:43], v[42:43], v[172:173], v[136:137]
	v_add_u32_e32 v136, v140, v180
	ds_read_b64 v[136:137], v136
	s_waitcnt lgkmcnt(0)
	v_cvt_f32_f16_e32 v138, v136
	v_cvt_f32_f16_sdwa v139, v136 dst_sel:DWORD dst_unused:UNUSED_PAD src0_sel:WORD_1
	v_cvt_f32_f16_e32 v136, v137
	v_cvt_f32_f16_sdwa v137, v137 dst_sel:DWORD dst_unused:UNUSED_PAD src0_sel:WORD_1
	v_pk_mul_f32 v[138:139], v[138:139], s[8:9] op_sel_hi:[1,0]
	s_nop 0
	v_pk_fma_f32 v[36:37], v[36:37], v[166:167], v[138:139]
	v_pk_mul_f32 v[136:137], v[136:137], s[8:9] op_sel_hi:[1,0]
	s_nop 0
	v_pk_fma_f32 v[38:39], v[38:39], v[168:169], v[136:137]
	v_add_u32_e32 v136, v140, v152
	ds_read_b64 v[136:137], v136
	v_pk_add_f32 v[152:153], v[6:7], v[18:19]
	v_pk_add_f32 v[140:141], v[2:3], v[26:27]
	v_pk_mov_b32 v[24:25], v[154:155], v[152:153] op_sel:[1,0]
	v_mov_b32_e32 v26, v154
	s_waitcnt lgkmcnt(0)
	v_cvt_f32_f16_e32 v138, v136
	v_cvt_f32_f16_sdwa v139, v136 dst_sel:DWORD dst_unused:UNUSED_PAD src0_sel:WORD_1
	v_cvt_f32_f16_e32 v136, v137
	v_cvt_f32_f16_sdwa v137, v137 dst_sel:DWORD dst_unused:UNUSED_PAD src0_sel:WORD_1
	v_mov_b32_e32 v27, v153
	v_pk_add_f32 v[18:19], v[8:9], v[144:145]
	v_pk_add_f32 v[24:25], v[24:25], v[26:27]
	v_pk_mov_b32 v[26:27], v[142:143], v[140:141] op_sel:[1,0]
	v_mov_b32_e32 v144, v142
	v_mov_b32_e32 v145, v141
	v_pk_mul_f32 v[138:139], v[138:139], s[8:9] op_sel_hi:[1,0]
	v_pk_mul_f32 v[136:137], v[136:137], s[8:9] op_sel_hi:[1,0]
	v_pk_add_f32 v[26:27], v[26:27], v[144:145]
	v_pk_fma_f32 v[34:35], v[34:35], v[164:165], v[136:137]
	v_pk_fma_f32 v[32:33], v[32:33], v[162:163], v[138:139]
	v_pk_add_f32 v[136:137], v[14:15], v[150:151]
	v_pk_add_f32 v[138:139], v[12:13], v[148:149]
	v_add_f32_e32 v24, v24, v25
	v_pk_add_f32 v[26:27], v[26:27], v[26:27] op_sel_hi:[0,1]
	v_add_f32_e32 v25, 0, v24
	v_add_f32_e32 v145, v138, v139
	v_add_f32_e32 v147, v136, v137
	v_mov_b32_e32 v144, v18
	v_mov_b32_e32 v146, v19
	v_mov_b32_e32 v26, v16
	v_mov_b32_e32 v24, v17
	v_pk_add_f32 v[144:145], v[144:145], v[146:147]
	v_pk_add_f32 v[24:25], v[26:27], v[24:25]
	s_waitcnt lgkmcnt(0)
	s_barrier
	v_pk_add_f32 v[24:25], v[144:145], v[24:25]
	s_nop 0
	v_add_f32_e32 v24, v24, v25
	ds_bpermute_b32 v25, v157, v24
	s_waitcnt lgkmcnt(0)
	v_add_f32_e32 v24, v24, v25
	ds_bpermute_b32 v25, v156, v24
	s_waitcnt lgkmcnt(0)
	v_add_f32_e32 v24, v24, v25
	v_fmamk_f32 v26, v24, 0xbc800000, v153
	v_fmamk_f32 v144, v24, 0xbc800000, v155
	v_fmamk_f32 v25, v24, 0xbc800000, v152
	v_fmamk_f32 v27, v24, 0xbc800000, v154
	v_mul_f32_e32 v144, v144, v144
	v_mul_f32_e32 v26, v26, v26
	v_fmac_f32_e32 v144, v27, v27
	v_fmac_f32_e32 v26, v25, v25
	v_fmamk_f32 v27, v24, 0xbc800000, v141
	v_fmamk_f32 v145, v24, 0xbc800000, v143
	v_add_f32_e32 v25, v144, v26
	v_fmamk_f32 v26, v24, 0xbc800000, v140
	v_fmamk_f32 v144, v24, 0xbc800000, v142
	v_mul_f32_e32 v145, v145, v145
	v_mul_f32_e32 v27, v27, v27
	v_fmac_f32_e32 v145, v144, v144
	v_fmac_f32_e32 v27, v26, v26
	v_add_f32_e32 v26, v145, v27
	v_fmamk_f32 v27, v24, 0xbc800000, v137
	v_fmamk_f32 v145, v24, 0xbc800000, v139
	v_add_f32_e32 v25, v25, v26
	v_fmamk_f32 v26, v24, 0xbc800000, v136
	v_fmamk_f32 v144, v24, 0xbc800000, v138
	v_mul_f32_e32 v145, v145, v145
	v_mul_f32_e32 v27, v27, v27
	v_fmac_f32_e32 v145, v144, v144
	v_fmac_f32_e32 v27, v26, v26
	v_add_f32_e32 v26, v145, v27
	v_fmamk_f32 v27, v24, 0xbc800000, v17
	v_fmamk_f32 v145, v24, 0xbc800000, v19
	v_add_f32_e32 v25, v26, v25
	v_fmamk_f32 v26, v24, 0xbc800000, v16
	v_fmamk_f32 v144, v24, 0xbc800000, v18
	v_mul_f32_e32 v145, v145, v145
	v_mul_f32_e32 v27, v27, v27
	v_fmac_f32_e32 v145, v144, v144
	v_fmac_f32_e32 v27, v26, v26
	v_add_f32_e32 v26, v145, v27
	v_add_f32_e32 v25, v26, v25
	ds_bpermute_b32 v26, v157, v25
	s_waitcnt lgkmcnt(0)
	v_add_f32_e32 v25, v25, v26
	ds_bpermute_b32 v26, v156, v25
	s_and_saveexec_b64 s[8:9], vcc
	s_cbranch_execz .LBB0_417
	s_lshl_b32 s3, s22, 11
	s_add_i32 s3, s12, s3
	v_mul_f32_e32 v24, 0x3c800000, v24
	s_waitcnt lgkmcnt(0)
	v_add_f32_e32 v25, v25, v26
	v_lshl_add_u32 v26, v178, 5, s3
	ds_write_b64 v26, v[24:25]

.LBB0_471:
	s_or_b64 exec, exec, s[10:11]
	v_lshlrev_b64 v[4:5], 2, v[160:161]
	s_waitcnt lgkmcnt(0)
	s_barrier
	v_lshl_add_u64 v[34:35], s[14:15], 0, v[4:5]
	v_lshl_add_u64 v[36:37], s[16:17], 0, v[4:5]
	global_load_dwordx4 v[0:3], v[34:35], off
	global_load_dwordx4 v[4:7], v[36:37], off
	global_load_dwordx4 v[180:183], v[34:35], off offset:64
	global_load_dwordx4 v[184:187], v[36:37], off offset:64
	global_load_dwordx4 v[188:191], v[34:35], off offset:512
	global_load_dwordx4 v[192:195], v[36:37], off offset:512
	global_load_dwordx4 v[196:199], v[34:35], off offset:576
	global_load_dwordx4 v[200:203], v[36:37], off offset:576
	v_and_b32_e32 v96, 15, v178
	v_or_b32_e32 v45, s33, v96
	v_lshl_add_u32 v33, v45, 3, 0
	v_lshlrev_b32_e32 v115, 2, v45
	s_waitcnt lgkmcnt(0)
	v_cmp_ne_u32_e32 vcc, 0, v32
	v_sub_u32_e32 v32, v33, v115
	ds_read_b64 v[38:39], v33 offset:8192
	ds_read_b32 v33, v32 offset:12288
	v_readlane_b32 s3, v254, 55
	s_or_b64 s[8:9], vcc, s[6:7]
	s_or_b32 s3, s34, s3
	s_cmp_eq_u32 s3, 0
	s_cselect_b64 s[10:11], -1, 0
	v_cmp_gt_u32_e32 vcc, 16, v178
	s_waitcnt lgkmcnt(0)
	v_max_f32_e32 v33, v33, v33
	v_max_f32_e32 v47, 0xda24260, v33
	s_and_b64 s[10:11], s[10:11], vcc
	s_and_saveexec_b64 s[12:13], s[10:11]
	s_cbranch_execz .LBB0_473
	v_readlane_b32 s3, v254, 17
	v_mul_f32_e32 v33, 0x3c010204, v47
	v_cndmask_b32_e64 v33, v33, v232, s[8:9]
	v_add_u32_e32 v98, s3, v45
	v_ashrrev_i32_e32 v99, 31, v98
	v_lshl_add_u64 v[98:99], v[98:99], 2, s[54:55]
	global_store_dword v[98:99], v33, off

.LBB0_487:
	s_or_b64 exec, exec, s[12:13]
	s_waitcnt lgkmcnt(0)
	v_sub_f32_e32 v129, v129, v94
	v_sub_f32_e32 v128, v128, v94
	v_pk_mul_f32 v[128:129], v[94:95], v[128:129] op_sel:[1,0]
	v_div_scale_f32 v45, s[10:11], v115, v115, s57
	v_pk_fma_f32 v[128:129], v[2:3], v[128:129], v[6:7]
	v_sub_f32_e32 v131, v131, v94
	v_cndmask_b32_e64 v153, v129, v232, s[8:9]
	v_rcp_f32_e32 v129, v45
	v_cndmask_b32_e64 v152, v128, v232, s[8:9]
	v_sub_f32_e32 v130, v130, v94
	v_pk_mul_f32 v[130:131], v[94:95], v[130:131] op_sel:[1,0]
	v_fma_f32 v128, -v45, v129, 1.0
	v_fmac_f32_e32 v129, v128, v129
	v_div_scale_f32 v128, vcc, s57, v115, s57
	v_mul_f32_e32 v151, v128, v129
	v_fma_f32 v154, -v45, v151, v128
	v_fmac_f32_e32 v151, v154, v129
	v_fma_f32 v45, -v45, v151, v128
	v_pk_fma_f32 v[130:131], v[0:1], v[130:131], v[4:5]
	v_div_fmas_f32 v45, v45, v129, v151
	v_sub_f32_e32 v63, v63, v78
	v_sub_f32_e32 v62, v62, v78
	v_cndmask_b32_e64 v131, v131, v232, s[8:9]
	v_cndmask_b32_e64 v130, v130, v232, s[8:9]
	v_div_fixup_f32 v128, v45, v115, s57
	v_pk_mul_f32 v[62:63], v[78:79], v[62:63] op_sel:[1,0]
	v_pk_mul_f32 v[154:155], v[128:129], v[130:131] op_sel_hi:[0,1]
	v_pk_fma_f32 v[2:3], v[2:3], v[62:63], v[6:7]
	v_div_scale_f32 v6, s[10:11], v149, v149, s57
	v_pk_mul_f32 v[156:157], v[128:129], v[152:153] op_sel_hi:[0,1]
	v_rndne_f32_e32 v129, v155
	v_rcp_f32_e32 v7, v6
	v_rndne_f32_e32 v45, v157
	v_rndne_f32_e32 v115, v156
	v_cvt_i32_f32_e32 v129, v129
	v_rndne_f32_e32 v151, v154
	v_sub_f32_e32 v61, v61, v78
	v_sub_f32_e32 v60, v60, v78
	v_cvt_i32_f32_e32 v45, v45
	v_cvt_i32_f32_sdwa v115, v115 dst_sel:WORD_1 dst_unused:UNUSED_PAD src0_sel:DWORD
	v_cvt_i32_f32_e32 v151, v151
	v_pk_mul_f32 v[60:61], v[78:79], v[60:61] op_sel:[1,0]
	v_lshlrev_b32_e32 v129, 8, v129
	v_pk_fma_f32 v[0:1], v[0:1], v[60:61], v[4:5]
	v_and_b32_e32 v115, 0xff0000, v115
	v_cndmask_b32_e64 v4, v0, v232, s[8:9]
	v_fma_f32 v0, -v6, v7, 1.0
	v_fmac_f32_e32 v7, v0, v7
	v_div_scale_f32 v0, vcc, s57, v149, s57
	v_and_b32_e32 v129, 0xff00, v129
	v_perm_b32 v45, v45, v151, s56
	v_cndmask_b32_e64 v5, v1, v232, s[8:9]
	v_mul_f32_e32 v1, v0, v7
	v_or3_b32 v155, v45, v129, v115
	v_fma_f32 v45, -v6, v1, v0
	v_fmac_f32_e32 v1, v45, v7
	v_fma_f32 v0, -v6, v1, v0
	v_div_fmas_f32 v0, v0, v7, v1
	v_div_fixup_f32 v60, v0, v149, s57
	v_cndmask_b32_e64 v3, v3, v232, s[8:9]
	v_cndmask_b32_e64 v2, v2, v232, s[8:9]
	v_pk_mul_f32 v[0:1], v[60:61], v[4:5] op_sel_hi:[0,1]
	v_pk_mul_f32 v[6:7], v[60:61], v[2:3] op_sel_hi:[0,1]
	v_rndne_f32_e32 v1, v1
	v_rndne_f32_e32 v7, v7
	v_rndne_f32_e32 v6, v6
	v_cvt_i32_f32_e32 v1, v1
	v_rndne_f32_e32 v0, v0
	v_cvt_i32_f32_e32 v7, v7
	v_cvt_i32_f32_sdwa v6, v6 dst_sel:WORD_1 dst_unused:UNUSED_PAD src0_sel:DWORD
	v_cvt_i32_f32_e32 v0, v0
	v_lshlrev_b32_e32 v1, 8, v1
	v_and_b32_e32 v1, 0xff00, v1
	v_and_b32_e32 v6, 0xff0000, v6
	v_perm_b32 v0, v7, v0, s56
	v_or3_b32 v154, v0, v1, v6
	v_or_b32_e32 v0, v77, v109
	v_ashrrev_i32_e32 v1, 31, v0
	v_lshlrev_b64 v[62:63], 10, v[0:1]
	v_lshl_add_u64 v[6:7], v[62:63], 0, v[112:113]
	v_cvt_pk_f16_f32 v1, v2, v3
	v_cvt_pk_f16_f32 v0, v4, v5
	v_cvt_pk_f16_f32 v3, v152, v153
	v_cvt_pk_f16_f32 v2, v130, v131
	s_nop 1
	v_permlane16_swap_b32_e32 v0, v2
	v_permlane16_swap_b32_e32 v1, v3
	v_lshl_add_u64 v[4:5], v[6:7], 1, s[60:61]
	global_store_dwordx4 v[4:5], v[0:3], off
	v_permlane16_swap_b32_e32 v154, v155
	s_nop 0
	v_lshl_add_u64 v[0:1], s[72:73], 0, v[6:7]
	global_store_dwordx2 v[0:1], v[154:155], off
	v_mov_b32_e32 v0, v180
	v_mov_b32_e32 v1, v181
	v_mov_b32_e32 v2, v182
	v_mov_b32_e32 v3, v183
	v_mov_b32_e32 v4, v184
	v_mov_b32_e32 v5, v185
	v_mov_b32_e32 v6, v186
	v_mov_b32_e32 v7, v187
	v_mov_b32_e32 v160, v39
	v_mov_b32_e32 v161, v39
	v_sub_f32_e32 v165, v141, v38
	v_sub_f32_e32 v164, v140, v38
	v_sub_f32_e32 v141, v143, v38
	v_sub_f32_e32 v140, v142, v38
	v_pk_mul_f32 v[142:143], v[160:161], v[140:141]
	v_mov_b32_e32 v140, v39
	v_mov_b32_e32 v141, v39
	v_pk_mul_f32 v[164:165], v[140:141], v[164:165]
	v_mov_b32_e32 v115, v114
	v_mov_b32_e32 v158, v33
	v_mov_b32_e32 v159, v33
	v_sub_f32_e32 v147, v147, v32
	v_sub_f32_e32 v146, v146, v32
	v_pk_mul_f32 v[146:147], v[158:159], v[146:147]
	v_mov_b32_e32 v45, v44
	v_lshl_add_u64 v[162:163], v[112:113], 0, 16
	v_mov_b32_e32 v156, v99
	v_mov_b32_e32 v157, v99
	v_sub_f32_e32 v121, v121, v98
	v_sub_f32_e32 v120, v120, v98
	v_sub_f32_e32 v123, v123, v98
	v_sub_f32_e32 v122, v122, v98
	v_mov_b32_e32 v149, v148
	v_mov_b32_e32 v154, v47
	v_mov_b32_e32 v155, v47
	v_sub_f32_e32 v107, v107, v46
	v_sub_f32_e32 v106, v106, v46
	v_mov_b32_e32 v109, v108
	v_mov_b32_e32 v152, v127
	v_mov_b32_e32 v153, v127
	v_sub_f32_e32 v89, v89, v126
	v_sub_f32_e32 v88, v88, v126
	v_sub_f32_e32 v91, v91, v126
	v_sub_f32_e32 v90, v90, v126
	v_mov_b32_e32 v151, v150
	v_mov_b32_e32 v130, v111
	v_mov_b32_e32 v131, v111
	v_sub_f32_e32 v75, v75, v110
	v_sub_f32_e32 v74, v74, v110
	v_mov_b32_e32 v77, v76
	v_sub_f32_e32 v57, v57, v78
	v_sub_f32_e32 v56, v56, v78
	v_sub_f32_e32 v41, v41, v94
	v_sub_f32_e32 v40, v40, v94
	v_sub_f32_e32 v59, v59, v78
	v_sub_f32_e32 v58, v58, v78
	v_pk_mul_f32 v[56:57], v[78:79], v[56:57] op_sel:[1,0]
	v_sub_f32_e32 v43, v43, v94
	v_sub_f32_e32 v42, v42, v94
	v_pk_mul_f32 v[40:41], v[94:95], v[40:41] op_sel:[1,0]
	v_pk_mul_f32 v[58:59], v[78:79], v[58:59] op_sel:[1,0]
	v_pk_mul_f32 v[42:43], v[94:95], v[42:43] op_sel:[1,0]
	v_sub_f32_e32 v53, v53, v78
	v_sub_f32_e32 v52, v52, v78
	v_sub_f32_e32 v13, v13, v94
	v_sub_f32_e32 v12, v12, v94
	v_pk_mul_f32 v[52:53], v[78:79], v[52:53] op_sel:[1,0]
	v_sub_f32_e32 v15, v15, v94
	v_sub_f32_e32 v14, v14, v94
	v_pk_mul_f32 v[12:13], v[94:95], v[12:13] op_sel:[1,0]
	v_pk_mul_f32 v[14:15], v[94:95], v[14:15] op_sel:[1,0]
	v_sub_f32_e32 v23, v23, v32
	v_sub_f32_e32 v22, v22, v32
	v_sub_f32_e32 v21, v21, v32
	v_sub_f32_e32 v20, v20, v32
	v_pk_mul_f32 v[22:23], v[158:159], v[22:23]
	s_mov_b64 s[10:11], 0x90
	v_sub_f32_e32 v9, v9, v94
	v_sub_f32_e32 v8, v8, v94
	v_sub_f32_e32 v11, v11, v94
	v_sub_f32_e32 v10, v10, v94
	v_pk_mul_f32 v[8:9], v[94:95], v[8:9] op_sel:[1,0]
	v_pk_mul_f32 v[10:11], v[94:95], v[10:11] op_sel:[1,0]
	v_pk_fma_f32 v[142:143], v[142:143], v[0:1], v[4:5]
	v_pk_fma_f32 v[164:165], v[164:165], v[2:3], v[6:7]
	v_cndmask_b32_e64 v167, v143, v232, s[8:9]
	v_cndmask_b32_e64 v166, v142, v232, s[8:9]
	v_cndmask_b32_e64 v165, v165, v232, s[8:9]
	v_cndmask_b32_e64 v164, v164, v232, s[8:9]
	v_mov_b32_e32 v142, v114
	v_mov_b32_e32 v143, v114
	v_pk_mul_f32 v[170:171], v[114:115], v[166:167]
	v_pk_mul_f32 v[168:169], v[142:143], v[164:165]
	v_rndne_f32_e32 v61, v171
	v_rndne_f32_e32 v39, v170
	v_cvt_i32_f32_e32 v61, v61
	v_rndne_f32_e32 v129, v168
	v_rndne_f32_e32 v168, v169
	v_cvt_i32_f32_e32 v39, v39
	v_cvt_i32_f32_sdwa v129, v129 dst_sel:WORD_1 dst_unused:UNUSED_PAD src0_sel:DWORD
	v_cvt_i32_f32_e32 v168, v168
	v_sub_f32_e32 v171, v145, v32
	v_sub_f32_e32 v170, v144, v32
	v_mov_b32_e32 v144, v33
	v_mov_b32_e32 v145, v33
	v_pk_mul_f32 v[170:171], v[144:145], v[170:171]
	v_pk_fma_f32 v[146:147], v[146:147], v[0:1], v[4:5]
	v_lshlrev_b32_e32 v61, 8, v61
	v_pk_fma_f32 v[170:171], v[170:171], v[2:3], v[6:7]
	v_cndmask_b32_e64 v173, v147, v232, s[8:9]
	v_cndmask_b32_e64 v172, v146, v232, s[8:9]
	v_and_b32_e32 v61, 0xff00, v61
	v_and_b32_e32 v129, 0xff0000, v129
	v_perm_b32 v39, v168, v39, s56
	v_cndmask_b32_e64 v171, v171, v232, s[8:9]
	v_cndmask_b32_e64 v170, v170, v232, s[8:9]
	v_pk_mul_f32 v[174:175], v[44:45], v[172:173]
	v_mov_b32_e32 v146, v44
	v_mov_b32_e32 v147, v44
	v_or3_b32 v168, v39, v61, v129
	v_pk_mul_f32 v[176:177], v[146:147], v[170:171]
	v_rndne_f32_e32 v61, v175
	v_rndne_f32_e32 v33, v177
	v_rndne_f32_e32 v39, v176
	v_cvt_i32_f32_e32 v61, v61
	v_rndne_f32_e32 v129, v174
	v_cvt_i32_f32_e32 v33, v33
	v_cvt_i32_f32_sdwa v39, v39 dst_sel:WORD_1 dst_unused:UNUSED_PAD src0_sel:DWORD
	v_cvt_i32_f32_e32 v129, v129
	v_lshlrev_b32_e32 v61, 8, v61
	v_and_b32_e32 v61, 0xff00, v61
	v_and_b32_e32 v39, 0xff0000, v39
	v_perm_b32 v33, v33, v129, s56
	v_lshl_add_u64 v[174:175], v[96:97], 0, v[162:163]
	v_cvt_pk_f16_f32 v165, v164, v165
	v_cvt_pk_f16_f32 v164, v166, v167
	v_cvt_pk_f16_f32 v167, v170, v171
	v_cvt_pk_f16_f32 v166, v172, v173
	v_or3_b32 v169, v33, v61, v39
	s_nop 0
	v_permlane16_swap_b32_e32 v164, v166
	v_permlane16_swap_b32_e32 v165, v167
	v_lshl_add_u64 v[170:171], v[174:175], 1, s[60:61]
	global_store_dwordx4 v[170:171], v[164:167], off
	v_permlane16_swap_b32_e32 v168, v169
	s_nop 0
	v_lshl_add_u64 v[164:165], s[72:73], 0, v[174:175]
	global_store_dwordx2 v[164:165], v[168:169], off
	v_pk_mul_f32 v[164:165], v[156:157], v[120:121]
	v_mov_b32_e32 v120, v99
	v_mov_b32_e32 v121, v99
	v_pk_mul_f32 v[122:123], v[120:121], v[122:123]
	v_pk_fma_f32 v[164:165], v[164:165], v[0:1], v[4:5]
	v_pk_fma_f32 v[122:123], v[122:123], v[2:3], v[6:7]
	v_cndmask_b32_e64 v167, v165, v232, s[8:9]
	v_cndmask_b32_e64 v166, v164, v232, s[8:9]
	v_cndmask_b32_e64 v165, v123, v232, s[8:9]
	v_cndmask_b32_e64 v164, v122, v232, s[8:9]
	v_mov_b32_e32 v122, v148
	v_mov_b32_e32 v123, v148
	v_pk_mul_f32 v[170:171], v[148:149], v[166:167]
	v_pk_mul_f32 v[168:169], v[122:123], v[164:165]
	v_rndne_f32_e32 v39, v171
	v_rndne_f32_e32 v33, v170
	v_cvt_i32_f32_e32 v39, v39
	v_rndne_f32_e32 v61, v168
	v_rndne_f32_e32 v99, v169
	v_sub_f32_e32 v171, v105, v46
	v_sub_f32_e32 v170, v104, v46
	v_cvt_i32_f32_e32 v33, v33
	v_cvt_i32_f32_sdwa v61, v61 dst_sel:WORD_1 dst_unused:UNUSED_PAD src0_sel:DWORD
	v_cvt_i32_f32_e32 v99, v99
	v_mov_b32_e32 v104, v47
	v_mov_b32_e32 v105, v47
	v_pk_mul_f32 v[170:171], v[154:155], v[170:171]
	v_pk_mul_f32 v[106:107], v[104:105], v[106:107]
	v_pk_fma_f32 v[170:171], v[170:171], v[0:1], v[4:5]
	v_pk_fma_f32 v[106:107], v[106:107], v[2:3], v[6:7]
	v_cndmask_b32_e64 v171, v171, v232, s[8:9]
	v_cndmask_b32_e64 v170, v170, v232, s[8:9]
	v_lshlrev_b32_e32 v39, 8, v39
	v_cndmask_b32_e64 v173, v107, v232, s[8:9]
	v_cndmask_b32_e64 v172, v106, v232, s[8:9]
	v_pk_mul_f32 v[174:175], v[108:109], v[170:171]
	v_mov_b32_e32 v106, v108
	v_mov_b32_e32 v107, v108
	v_and_b32_e32 v39, 0xff00, v39
	v_and_b32_e32 v61, 0xff0000, v61
	v_perm_b32 v33, v99, v33, s56
	v_pk_mul_f32 v[176:177], v[106:107], v[172:173]
	v_rndne_f32_e32 v47, v175
	v_or3_b32 v168, v33, v39, v61
	v_rndne_f32_e32 v33, v177
	v_rndne_f32_e32 v39, v176
	v_cvt_i32_f32_e32 v47, v47
	v_rndne_f32_e32 v61, v174
	v_cvt_i32_f32_e32 v33, v33
	v_cvt_i32_f32_sdwa v39, v39 dst_sel:WORD_1 dst_unused:UNUSED_PAD src0_sel:DWORD
	v_cvt_i32_f32_e32 v61, v61
	v_lshlrev_b32_e32 v47, 8, v47
	v_and_b32_e32 v47, 0xff00, v47
	v_and_b32_e32 v39, 0xff0000, v39
	v_perm_b32 v33, v33, v61, s56
	v_lshl_add_u64 v[174:175], v[124:125], 0, v[162:163]
	v_cvt_pk_f16_f32 v165, v164, v165
	v_cvt_pk_f16_f32 v164, v166, v167
	v_cvt_pk_f16_f32 v167, v172, v173
	v_cvt_pk_f16_f32 v166, v170, v171
	v_or3_b32 v169, v33, v47, v39
	s_nop 0
	v_permlane16_swap_b32_e32 v164, v166
	v_permlane16_swap_b32_e32 v165, v167
	v_lshl_add_u64 v[170:171], v[174:175], 1, s[60:61]
	global_store_dwordx4 v[170:171], v[164:167], off
	v_permlane16_swap_b32_e32 v168, v169
	s_nop 0
	v_lshl_add_u64 v[164:165], s[72:73], 0, v[174:175]
	global_store_dwordx2 v[164:165], v[168:169], off
	v_pk_mul_f32 v[164:165], v[152:153], v[88:89]
	v_mov_b32_e32 v88, v127
	v_mov_b32_e32 v89, v127
	v_pk_mul_f32 v[90:91], v[88:89], v[90:91]
	v_pk_fma_f32 v[164:165], v[164:165], v[0:1], v[4:5]
	v_pk_fma_f32 v[90:91], v[90:91], v[2:3], v[6:7]
	v_cndmask_b32_e64 v167, v165, v232, s[8:9]
	v_cndmask_b32_e64 v166, v164, v232, s[8:9]
	v_cndmask_b32_e64 v165, v91, v232, s[8:9]
	v_cndmask_b32_e64 v164, v90, v232, s[8:9]
	v_mov_b32_e32 v90, v150
	v_mov_b32_e32 v91, v150
	v_pk_mul_f32 v[170:171], v[150:151], v[166:167]
	v_pk_mul_f32 v[168:169], v[90:91], v[164:165]
	v_rndne_f32_e32 v39, v171
	v_rndne_f32_e32 v33, v170
	v_cvt_i32_f32_e32 v39, v39
	v_rndne_f32_e32 v47, v168
	v_rndne_f32_e32 v61, v169
	v_cvt_i32_f32_e32 v33, v33
	v_cvt_i32_f32_sdwa v47, v47 dst_sel:WORD_1 dst_unused:UNUSED_PAD src0_sel:DWORD
	v_cvt_i32_f32_e32 v61, v61
	v_sub_f32_e32 v171, v73, v110
	v_sub_f32_e32 v170, v72, v110
	v_mov_b32_e32 v72, v111
	v_mov_b32_e32 v73, v111
	v_pk_mul_f32 v[170:171], v[130:131], v[170:171]
	v_pk_mul_f32 v[74:75], v[72:73], v[74:75]
	v_pk_fma_f32 v[170:171], v[170:171], v[0:1], v[4:5]
	v_lshlrev_b32_e32 v39, 8, v39
	v_pk_fma_f32 v[74:75], v[74:75], v[2:3], v[6:7]
	v_cndmask_b32_e64 v171, v171, v232, s[8:9]
	v_cndmask_b32_e64 v170, v170, v232, s[8:9]
	v_and_b32_e32 v39, 0xff00, v39
	v_and_b32_e32 v47, 0xff0000, v47
	v_perm_b32 v33, v61, v33, s56
	v_cndmask_b32_e64 v173, v75, v232, s[8:9]
	v_cndmask_b32_e64 v172, v74, v232, s[8:9]
	v_pk_mul_f32 v[174:175], v[76:77], v[170:171]
	v_mov_b32_e32 v74, v76
	v_mov_b32_e32 v75, v76
	v_or3_b32 v168, v33, v39, v47
	v_pk_mul_f32 v[176:177], v[74:75], v[172:173]
	v_rndne_f32_e32 v47, v175
	v_rndne_f32_e32 v33, v177
	v_rndne_f32_e32 v39, v176
	v_cvt_i32_f32_e32 v47, v47
	v_rndne_f32_e32 v61, v174
	v_cvt_i32_f32_e32 v33, v33
	v_cvt_i32_f32_sdwa v39, v39 dst_sel:WORD_1 dst_unused:UNUSED_PAD src0_sel:DWORD
	v_cvt_i32_f32_e32 v61, v61
	v_lshlrev_b32_e32 v47, 8, v47
	v_pk_fma_f32 v[56:57], v[56:57], v[0:1], v[4:5]
	v_pk_fma_f32 v[0:1], v[40:41], v[0:1], v[4:5]
	v_and_b32_e32 v39, 0xff0000, v39
	v_and_b32_e32 v47, 0xff00, v47
	v_perm_b32 v33, v33, v61, s56
	v_lshl_add_u64 v[174:175], v[92:93], 0, v[162:163]
	v_cvt_pk_f16_f32 v165, v164, v165
	v_cvt_pk_f16_f32 v164, v166, v167
	v_cvt_pk_f16_f32 v167, v172, v173
	v_cvt_pk_f16_f32 v166, v170, v171
	v_pk_fma_f32 v[58:59], v[58:59], v[2:3], v[6:7]
	v_pk_fma_f32 v[2:3], v[42:43], v[2:3], v[6:7]
	v_cndmask_b32_e64 v5, v1, v232, s[8:9]
	v_cndmask_b32_e64 v4, v0, v232, s[8:9]
	v_or3_b32 v169, v33, v47, v39
	v_permlane16_swap_b32_e32 v164, v166
	v_permlane16_swap_b32_e32 v165, v167
	v_lshl_add_u64 v[170:171], v[174:175], 1, s[60:61]
	v_cndmask_b32_e64 v57, v57, v232, s[8:9]
	v_cndmask_b32_e64 v56, v56, v232, s[8:9]
	v_cndmask_b32_e64 v3, v3, v232, s[8:9]
	v_cndmask_b32_e64 v2, v2, v232, s[8:9]
	v_pk_mul_f32 v[0:1], v[128:129], v[4:5] op_sel_hi:[0,1]
	global_store_dwordx4 v[170:171], v[164:167], off
	v_permlane16_swap_b32_e32 v168, v169
	s_nop 0
	v_lshl_add_u64 v[164:165], s[72:73], 0, v[174:175]
	v_cndmask_b32_e64 v59, v59, v232, s[8:9]
	v_cndmask_b32_e64 v58, v58, v232, s[8:9]
	v_pk_mul_f32 v[166:167], v[60:61], v[56:57] op_sel_hi:[0,1]
	v_pk_mul_f32 v[6:7], v[128:129], v[2:3] op_sel_hi:[0,1]
	v_rndne_f32_e32 v1, v1
	global_store_dwordx2 v[164:165], v[168:169], off
	v_pk_mul_f32 v[164:165], v[60:61], v[58:59] op_sel_hi:[0,1]
	v_rndne_f32_e32 v39, v167
	v_rndne_f32_e32 v7, v7
	v_rndne_f32_e32 v6, v6
	v_cvt_i32_f32_e32 v1, v1
	v_rndne_f32_e32 v0, v0
	v_rndne_f32_e32 v33, v166
	v_cvt_i32_f32_e32 v39, v39
	v_rndne_f32_e32 v47, v164
	v_rndne_f32_e32 v61, v165
	v_cvt_i32_f32_e32 v7, v7
	v_cvt_i32_f32_sdwa v6, v6 dst_sel:WORD_1 dst_unused:UNUSED_PAD src0_sel:DWORD
	v_cvt_i32_f32_e32 v0, v0
	v_cvt_i32_f32_e32 v33, v33
	v_cvt_i32_f32_sdwa v47, v47 dst_sel:WORD_1 dst_unused:UNUSED_PAD src0_sel:DWORD
	v_cvt_i32_f32_e32 v61, v61
	v_lshlrev_b32_e32 v1, 8, v1
	v_lshlrev_b32_e32 v39, 8, v39
	v_and_b32_e32 v6, 0xff0000, v6
	v_and_b32_e32 v1, 0xff00, v1
	v_perm_b32 v0, v7, v0, s56
	v_and_b32_e32 v39, 0xff00, v39
	v_and_b32_e32 v47, 0xff0000, v47
	v_perm_b32 v33, v61, v33, s56
	v_or3_b32 v165, v0, v1, v6
	v_lshl_add_u64 v[6:7], v[62:63], 0, v[162:163]
	v_cvt_pk_f16_f32 v1, v58, v59
	v_cvt_pk_f16_f32 v0, v56, v57
	v_cvt_pk_f16_f32 v3, v2, v3
	v_cvt_pk_f16_f32 v2, v4, v5
	v_or3_b32 v164, v33, v39, v47
	s_nop 0
	v_permlane16_swap_b32_e32 v0, v2
	v_permlane16_swap_b32_e32 v1, v3
	v_lshl_add_u64 v[4:5], v[6:7], 1, s[60:61]
	global_store_dwordx4 v[4:5], v[0:3], off
	v_permlane16_swap_b32_e32 v164, v165
	s_nop 0
	v_lshl_add_u64 v[0:1], s[72:73], 0, v[6:7]
	global_store_dwordx2 v[0:1], v[164:165], off
	v_mov_b32_e32 v0, v188
	v_mov_b32_e32 v1, v189
	v_mov_b32_e32 v2, v190
	v_mov_b32_e32 v3, v191
	v_mov_b32_e32 v4, v192
	v_mov_b32_e32 v5, v193
	v_mov_b32_e32 v6, v194
	v_mov_b32_e32 v7, v195
	v_sub_f32_e32 v43, v137, v38
	v_sub_f32_e32 v42, v136, v38
	v_sub_f32_e32 v57, v139, v38
	v_sub_f32_e32 v56, v138, v38
	v_pk_mul_f32 v[56:57], v[160:161], v[56:57]
	v_pk_mul_f32 v[42:43], v[140:141], v[42:43]
	v_lshl_add_u64 v[40:41], v[112:113], 0, s[96:97]
	v_pk_mul_f32 v[20:21], v[144:145], v[20:21]
	v_pk_fma_f32 v[42:43], v[42:43], v[2:3], v[6:7]
	v_pk_fma_f32 v[56:57], v[56:57], v[0:1], v[4:5]
	v_cndmask_b32_e64 v43, v43, v232, s[8:9]
	v_cndmask_b32_e64 v59, v57, v232, s[8:9]
	v_cndmask_b32_e64 v58, v56, v232, s[8:9]
	v_cndmask_b32_e64 v42, v42, v232, s[8:9]
	v_pk_mul_f32 v[56:57], v[142:143], v[42:43]
	v_pk_mul_f32 v[136:137], v[114:115], v[58:59]
	v_rndne_f32_e32 v47, v56
	v_rndne_f32_e32 v33, v136
	v_rndne_f32_e32 v56, v57
	v_cvt_i32_f32_e32 v33, v33
	v_cvt_i32_f32_e32 v56, v56
	v_rndne_f32_e32 v39, v137
	v_cvt_i32_f32_e32 v39, v39
	v_cvt_i32_f32_sdwa v47, v47 dst_sel:WORD_1 dst_unused:UNUSED_PAD src0_sel:DWORD
	v_perm_b32 v33, v56, v33, s56
	v_sub_f32_e32 v57, v133, v32
	v_sub_f32_e32 v56, v132, v32
	v_sub_f32_e32 v133, v135, v32
	v_sub_f32_e32 v132, v134, v32
	v_pk_mul_f32 v[56:57], v[158:159], v[56:57]
	v_pk_mul_f32 v[132:133], v[144:145], v[132:133]
	v_pk_fma_f32 v[56:57], v[56:57], v[0:1], v[4:5]
	v_lshlrev_b32_e32 v39, 8, v39
	v_pk_fma_f32 v[132:133], v[132:133], v[2:3], v[6:7]
	v_cndmask_b32_e64 v135, v57, v232, s[8:9]
	v_cndmask_b32_e64 v134, v56, v232, s[8:9]
	v_and_b32_e32 v39, 0xff00, v39
	v_and_b32_e32 v47, 0xff0000, v47
	v_cndmask_b32_e64 v133, v133, v232, s[8:9]
	v_cndmask_b32_e64 v132, v132, v232, s[8:9]
	v_pk_mul_f32 v[56:57], v[44:45], v[134:135]
	v_or3_b32 v136, v33, v39, v47
	v_pk_mul_f32 v[138:139], v[146:147], v[132:133]
	v_rndne_f32_e32 v47, v57
	v_rndne_f32_e32 v33, v139
	v_rndne_f32_e32 v39, v138
	v_cvt_i32_f32_e32 v47, v47
	v_rndne_f32_e32 v56, v56
	v_cvt_i32_f32_e32 v33, v33
	v_cvt_i32_f32_sdwa v39, v39 dst_sel:WORD_1 dst_unused:UNUSED_PAD src0_sel:DWORD
	v_cvt_i32_f32_e32 v56, v56
	v_lshlrev_b32_e32 v47, 8, v47
	v_and_b32_e32 v47, 0xff00, v47
	v_and_b32_e32 v39, 0xff0000, v39
	v_perm_b32 v33, v33, v56, s56
	v_lshl_add_u64 v[138:139], v[96:97], 0, v[40:41]
	v_cvt_pk_f16_f32 v57, v42, v43
	v_cvt_pk_f16_f32 v56, v58, v59
	v_cvt_pk_f16_f32 v59, v132, v133
	v_cvt_pk_f16_f32 v58, v134, v135
	v_or3_b32 v137, v33, v47, v39
	s_nop 0
	v_permlane16_swap_b32_e32 v56, v58
	v_permlane16_swap_b32_e32 v57, v59
	v_lshl_add_u64 v[42:43], v[138:139], 1, s[60:61]
	global_store_dwordx4 v[42:43], v[56:59], off
	v_permlane16_swap_b32_e32 v136, v137
	v_lshl_add_u64 v[42:43], s[72:73], 0, v[138:139]
	global_store_dwordx2 v[42:43], v[136:137], off
	v_sub_f32_e32 v43, v119, v98
	v_sub_f32_e32 v42, v118, v98
	v_sub_f32_e32 v57, v117, v98
	v_sub_f32_e32 v56, v116, v98
	v_pk_mul_f32 v[56:57], v[156:157], v[56:57]
	v_pk_mul_f32 v[42:43], v[120:121], v[42:43]
	v_pk_fma_f32 v[56:57], v[56:57], v[0:1], v[4:5]
	v_pk_fma_f32 v[42:43], v[42:43], v[2:3], v[6:7]
	v_cndmask_b32_e64 v59, v57, v232, s[8:9]
	v_cndmask_b32_e64 v58, v56, v232, s[8:9]
	v_cndmask_b32_e64 v43, v43, v232, s[8:9]
	v_cndmask_b32_e64 v42, v42, v232, s[8:9]
	v_pk_mul_f32 v[56:57], v[122:123], v[42:43]
	v_pk_mul_f32 v[116:117], v[148:149], v[58:59]
	v_rndne_f32_e32 v47, v56
	v_rndne_f32_e32 v33, v116
	v_rndne_f32_e32 v56, v57
	v_cvt_i32_f32_e32 v33, v33
	v_cvt_i32_f32_e32 v56, v56
	v_rndne_f32_e32 v39, v117
	v_cvt_i32_f32_e32 v39, v39
	v_cvt_i32_f32_sdwa v47, v47 dst_sel:WORD_1 dst_unused:UNUSED_PAD src0_sel:DWORD
	v_perm_b32 v33, v56, v33, s56
	v_sub_f32_e32 v57, v101, v46
	v_sub_f32_e32 v56, v100, v46
	v_sub_f32_e32 v101, v103, v46
	v_sub_f32_e32 v100, v102, v46
	v_pk_mul_f32 v[56:57], v[154:155], v[56:57]
	v_pk_mul_f32 v[100:101], v[104:105], v[100:101]
	v_pk_fma_f32 v[56:57], v[56:57], v[0:1], v[4:5]
	v_lshlrev_b32_e32 v39, 8, v39
	v_pk_fma_f32 v[100:101], v[100:101], v[2:3], v[6:7]
	v_cndmask_b32_e64 v103, v57, v232, s[8:9]
	v_cndmask_b32_e64 v102, v56, v232, s[8:9]
	v_and_b32_e32 v39, 0xff00, v39
	v_and_b32_e32 v47, 0xff0000, v47
	v_cndmask_b32_e64 v101, v101, v232, s[8:9]
	v_cndmask_b32_e64 v100, v100, v232, s[8:9]
	v_pk_mul_f32 v[56:57], v[108:109], v[102:103]
	v_or3_b32 v116, v33, v39, v47
	v_pk_mul_f32 v[118:119], v[106:107], v[100:101]
	v_rndne_f32_e32 v47, v57
	v_rndne_f32_e32 v33, v119
	v_rndne_f32_e32 v39, v118
	v_cvt_i32_f32_e32 v47, v47
	v_rndne_f32_e32 v56, v56
	v_cvt_i32_f32_e32 v33, v33
	v_cvt_i32_f32_sdwa v39, v39 dst_sel:WORD_1 dst_unused:UNUSED_PAD src0_sel:DWORD
	v_cvt_i32_f32_e32 v56, v56
	v_lshlrev_b32_e32 v47, 8, v47
	v_and_b32_e32 v47, 0xff00, v47
	v_and_b32_e32 v39, 0xff0000, v39
	v_perm_b32 v33, v33, v56, s56
	v_lshl_add_u64 v[118:119], v[124:125], 0, v[40:41]
	v_cvt_pk_f16_f32 v57, v42, v43
	v_cvt_pk_f16_f32 v56, v58, v59
	v_cvt_pk_f16_f32 v59, v100, v101
	v_cvt_pk_f16_f32 v58, v102, v103
	v_or3_b32 v117, v33, v47, v39
	s_nop 0
	v_permlane16_swap_b32_e32 v56, v58
	v_permlane16_swap_b32_e32 v57, v59
	v_lshl_add_u64 v[42:43], v[118:119], 1, s[60:61]
	global_store_dwordx4 v[42:43], v[56:59], off
	v_permlane16_swap_b32_e32 v116, v117
	v_lshl_add_u64 v[42:43], s[72:73], 0, v[118:119]
	global_store_dwordx2 v[42:43], v[116:117], off
	v_sub_f32_e32 v43, v87, v126
	v_sub_f32_e32 v42, v86, v126
	v_sub_f32_e32 v57, v85, v126
	v_sub_f32_e32 v56, v84, v126
	v_pk_mul_f32 v[56:57], v[152:153], v[56:57]
	v_pk_mul_f32 v[42:43], v[88:89], v[42:43]
	v_pk_fma_f32 v[56:57], v[56:57], v[0:1], v[4:5]
	v_pk_fma_f32 v[42:43], v[42:43], v[2:3], v[6:7]
	v_cndmask_b32_e64 v59, v57, v232, s[8:9]
	v_cndmask_b32_e64 v58, v56, v232, s[8:9]
	v_cndmask_b32_e64 v43, v43, v232, s[8:9]
	v_cndmask_b32_e64 v42, v42, v232, s[8:9]
	v_pk_mul_f32 v[56:57], v[90:91], v[42:43]
	v_pk_mul_f32 v[84:85], v[150:151], v[58:59]
	v_rndne_f32_e32 v47, v56
	v_rndne_f32_e32 v33, v84
	v_rndne_f32_e32 v56, v57
	v_cvt_i32_f32_e32 v33, v33
	v_cvt_i32_f32_e32 v56, v56
	v_rndne_f32_e32 v39, v85
	v_cvt_i32_f32_e32 v39, v39
	v_cvt_i32_f32_sdwa v47, v47 dst_sel:WORD_1 dst_unused:UNUSED_PAD src0_sel:DWORD
	v_perm_b32 v33, v56, v33, s56
	v_sub_f32_e32 v57, v69, v110
	v_sub_f32_e32 v56, v68, v110
	v_sub_f32_e32 v69, v71, v110
	v_sub_f32_e32 v68, v70, v110
	v_pk_mul_f32 v[56:57], v[130:131], v[56:57]
	v_pk_mul_f32 v[68:69], v[72:73], v[68:69]
	v_pk_fma_f32 v[56:57], v[56:57], v[0:1], v[4:5]
	v_lshlrev_b32_e32 v39, 8, v39
	v_pk_fma_f32 v[68:69], v[68:69], v[2:3], v[6:7]
	v_cndmask_b32_e64 v71, v57, v232, s[8:9]
	v_cndmask_b32_e64 v70, v56, v232, s[8:9]
	v_and_b32_e32 v39, 0xff00, v39
	v_and_b32_e32 v47, 0xff0000, v47
	v_cndmask_b32_e64 v69, v69, v232, s[8:9]
	v_cndmask_b32_e64 v68, v68, v232, s[8:9]
	v_pk_mul_f32 v[56:57], v[76:77], v[70:71]
	v_or3_b32 v84, v33, v39, v47
	v_pk_mul_f32 v[86:87], v[74:75], v[68:69]
	v_rndne_f32_e32 v47, v57
	v_rndne_f32_e32 v33, v87
	v_rndne_f32_e32 v39, v86
	v_cvt_i32_f32_e32 v47, v47
	v_rndne_f32_e32 v56, v56
	v_cvt_i32_f32_e32 v33, v33
	v_cvt_i32_f32_sdwa v39, v39 dst_sel:WORD_1 dst_unused:UNUSED_PAD src0_sel:DWORD
	v_cvt_i32_f32_e32 v56, v56
	v_lshlrev_b32_e32 v47, 8, v47
	v_and_b32_e32 v47, 0xff00, v47
	v_and_b32_e32 v39, 0xff0000, v39
	v_perm_b32 v33, v33, v56, s56
	v_lshl_add_u64 v[86:87], v[92:93], 0, v[40:41]
	v_cvt_pk_f16_f32 v57, v42, v43
	v_cvt_pk_f16_f32 v56, v58, v59
	v_cvt_pk_f16_f32 v59, v68, v69
	v_cvt_pk_f16_f32 v58, v70, v71
	v_or3_b32 v85, v33, v47, v39
	s_nop 0
	v_permlane16_swap_b32_e32 v56, v58
	v_permlane16_swap_b32_e32 v57, v59
	v_lshl_add_u64 v[42:43], v[86:87], 1, s[60:61]
	global_store_dwordx4 v[42:43], v[56:59], off
	v_permlane16_swap_b32_e32 v84, v85
	v_lshl_add_u64 v[42:43], s[72:73], 0, v[86:87]
	global_store_dwordx2 v[42:43], v[84:85], off
	v_sub_f32_e32 v43, v55, v78
	v_sub_f32_e32 v42, v54, v78
	v_pk_mul_f32 v[42:43], v[78:79], v[42:43] op_sel:[1,0]
	v_pk_fma_f32 v[52:53], v[52:53], v[0:1], v[4:5]
	v_pk_fma_f32 v[0:1], v[12:13], v[0:1], v[4:5]
	v_pk_fma_f32 v[42:43], v[42:43], v[2:3], v[6:7]
	v_pk_fma_f32 v[2:3], v[14:15], v[2:3], v[6:7]
	v_cndmask_b32_e64 v5, v1, v232, s[8:9]
	v_cndmask_b32_e64 v4, v0, v232, s[8:9]
	v_cndmask_b32_e64 v53, v53, v232, s[8:9]
	v_cndmask_b32_e64 v52, v52, v232, s[8:9]
	v_cndmask_b32_e64 v3, v3, v232, s[8:9]
	v_cndmask_b32_e64 v2, v2, v232, s[8:9]
	v_pk_mul_f32 v[0:1], v[128:129], v[4:5] op_sel_hi:[0,1]
	v_cndmask_b32_e64 v43, v43, v232, s[8:9]
	v_cndmask_b32_e64 v42, v42, v232, s[8:9]
	v_pk_mul_f32 v[56:57], v[60:61], v[52:53] op_sel_hi:[0,1]
	v_pk_mul_f32 v[6:7], v[128:129], v[2:3] op_sel_hi:[0,1]
	v_rndne_f32_e32 v1, v1
	v_pk_mul_f32 v[54:55], v[60:61], v[42:43] op_sel_hi:[0,1]
	v_rndne_f32_e32 v39, v57
	v_rndne_f32_e32 v7, v7
	v_rndne_f32_e32 v6, v6
	v_cvt_i32_f32_e32 v1, v1
	v_rndne_f32_e32 v0, v0
	v_rndne_f32_e32 v33, v56
	v_cvt_i32_f32_e32 v39, v39
	v_rndne_f32_e32 v47, v54
	v_rndne_f32_e32 v54, v55
	v_cvt_i32_f32_e32 v7, v7
	v_cvt_i32_f32_sdwa v6, v6 dst_sel:WORD_1 dst_unused:UNUSED_PAD src0_sel:DWORD
	v_cvt_i32_f32_e32 v0, v0
	v_cvt_i32_f32_e32 v33, v33
	v_cvt_i32_f32_sdwa v47, v47 dst_sel:WORD_1 dst_unused:UNUSED_PAD src0_sel:DWORD
	v_cvt_i32_f32_e32 v54, v54
	v_lshlrev_b32_e32 v1, 8, v1
	v_lshlrev_b32_e32 v39, 8, v39
	v_and_b32_e32 v6, 0xff0000, v6
	v_and_b32_e32 v1, 0xff00, v1
	v_perm_b32 v0, v7, v0, s56
	v_and_b32_e32 v39, 0xff00, v39
	v_and_b32_e32 v47, 0xff0000, v47
	v_perm_b32 v33, v54, v33, s56
	v_or3_b32 v55, v0, v1, v6
	v_lshl_add_u64 v[6:7], v[62:63], 0, v[40:41]
	v_cvt_pk_f16_f32 v1, v42, v43
	v_cvt_pk_f16_f32 v0, v52, v53
	v_cvt_pk_f16_f32 v3, v2, v3
	v_cvt_pk_f16_f32 v2, v4, v5
	v_or3_b32 v54, v33, v39, v47
	s_nop 0
	v_permlane16_swap_b32_e32 v0, v2
	v_permlane16_swap_b32_e32 v1, v3
	v_lshl_add_u64 v[4:5], v[6:7], 1, s[60:61]
	global_store_dwordx4 v[4:5], v[0:3], off
	v_permlane16_swap_b32_e32 v54, v55
	s_nop 0
	v_lshl_add_u64 v[0:1], s[72:73], 0, v[6:7]
	global_store_dwordx2 v[0:1], v[54:55], off
	v_mov_b32_e32 v0, v196
	v_mov_b32_e32 v1, v197
	v_mov_b32_e32 v2, v198
	v_mov_b32_e32 v3, v199
	v_mov_b32_e32 v4, v200
	v_mov_b32_e32 v5, v201
	v_mov_b32_e32 v6, v202
	v_mov_b32_e32 v7, v203
	v_sub_f32_e32 v15, v17, v38
	v_sub_f32_e32 v14, v16, v38
	v_sub_f32_e32 v17, v19, v38
	v_sub_f32_e32 v16, v18, v38
	v_pk_mul_f32 v[16:17], v[160:161], v[16:17]
	v_pk_mul_f32 v[14:15], v[140:141], v[14:15]
	v_lshl_add_u64 v[12:13], v[112:113], 0, s[10:11]
	v_pk_fma_f32 v[16:17], v[16:17], v[0:1], v[4:5]
	v_pk_fma_f32 v[14:15], v[14:15], v[2:3], v[6:7]
	v_cndmask_b32_e64 v17, v17, v232, s[8:9]
	v_cndmask_b32_e64 v16, v16, v232, s[8:9]
	v_cndmask_b32_e64 v15, v15, v232, s[8:9]
	v_cndmask_b32_e64 v14, v14, v232, s[8:9]
	v_pk_mul_f32 v[34:35], v[114:115], v[16:17]
	v_pk_mul_f32 v[18:19], v[142:143], v[14:15]
	v_rndne_f32_e32 v33, v34
	v_rndne_f32_e32 v34, v35
	v_cvt_i32_f32_e32 v34, v34
	v_rndne_f32_e32 v18, v18
	v_rndne_f32_e32 v19, v19
	v_cvt_i32_f32_e32 v33, v33
	v_cvt_i32_f32_sdwa v18, v18 dst_sel:WORD_1 dst_unused:UNUSED_PAD src0_sel:DWORD
	v_cvt_i32_f32_e32 v19, v19
	v_pk_fma_f32 v[22:23], v[22:23], v[0:1], v[4:5]
	v_lshlrev_b32_e32 v34, 8, v34
	v_pk_fma_f32 v[20:21], v[20:21], v[2:3], v[6:7]
	v_cndmask_b32_e64 v23, v23, v232, s[8:9]
	v_cndmask_b32_e64 v22, v22, v232, s[8:9]
	v_and_b32_e32 v34, 0xff00, v34
	v_and_b32_e32 v18, 0xff0000, v18
	v_perm_b32 v19, v19, v33, s56
	v_cndmask_b32_e64 v21, v21, v232, s[8:9]
	v_cndmask_b32_e64 v20, v20, v232, s[8:9]
	v_pk_mul_f32 v[32:33], v[44:45], v[22:23]
	v_or3_b32 v18, v19, v34, v18
	v_pk_mul_f32 v[34:35], v[146:147], v[20:21]
	v_rndne_f32_e32 v33, v33
	v_rndne_f32_e32 v19, v35
	v_rndne_f32_e32 v34, v34
	v_cvt_i32_f32_e32 v33, v33
	v_rndne_f32_e32 v32, v32
	v_cvt_i32_f32_e32 v19, v19
	v_cvt_i32_f32_sdwa v34, v34 dst_sel:WORD_1 dst_unused:UNUSED_PAD src0_sel:DWORD
	v_cvt_i32_f32_e32 v32, v32
	v_lshlrev_b32_e32 v33, 8, v33
	v_and_b32_e32 v33, 0xff00, v33
	v_and_b32_e32 v34, 0xff0000, v34
	v_perm_b32 v19, v19, v32, s56
	v_or3_b32 v19, v19, v33, v34
	v_lshl_add_u64 v[32:33], v[96:97], 0, v[12:13]
	v_cvt_pk_f16_f32 v15, v14, v15
	v_cvt_pk_f16_f32 v14, v16, v17
	v_cvt_pk_f16_f32 v17, v20, v21
	v_cvt_pk_f16_f32 v16, v22, v23
	s_nop 1
	v_permlane16_swap_b32_e32 v14, v16
	v_permlane16_swap_b32_e32 v15, v17
	v_lshl_add_u64 v[20:21], v[32:33], 1, s[60:61]
	global_store_dwordx4 v[20:21], v[14:17], off
	v_permlane16_swap_b32_e32 v18, v19
	s_nop 0
	v_lshl_add_u64 v[14:15], s[72:73], 0, v[32:33]
	v_sub_f32_e32 v17, v25, v98
	v_sub_f32_e32 v16, v24, v98
	global_store_dwordx2 v[14:15], v[18:19], off
	v_sub_f32_e32 v15, v27, v98
	v_sub_f32_e32 v14, v26, v98
	v_pk_mul_f32 v[16:17], v[156:157], v[16:17]
	v_pk_mul_f32 v[14:15], v[120:121], v[14:15]
	v_pk_fma_f32 v[16:17], v[16:17], v[0:1], v[4:5]
	v_pk_fma_f32 v[14:15], v[14:15], v[2:3], v[6:7]
	v_cndmask_b32_e64 v17, v17, v232, s[8:9]
	v_cndmask_b32_e64 v16, v16, v232, s[8:9]
	v_cndmask_b32_e64 v15, v15, v232, s[8:9]
	v_cndmask_b32_e64 v14, v14, v232, s[8:9]
	v_pk_mul_f32 v[20:21], v[148:149], v[16:17]
	v_pk_mul_f32 v[18:19], v[122:123], v[14:15]
	v_rndne_f32_e32 v21, v21
	v_rndne_f32_e32 v20, v20
	v_cvt_i32_f32_e32 v21, v21
	v_rndne_f32_e32 v18, v18
	v_rndne_f32_e32 v19, v19
	v_cvt_i32_f32_e32 v20, v20
	v_cvt_i32_f32_sdwa v18, v18 dst_sel:WORD_1 dst_unused:UNUSED_PAD src0_sel:DWORD
	v_cvt_i32_f32_e32 v19, v19
	v_lshlrev_b32_e32 v21, 8, v21
	v_and_b32_e32 v21, 0xff00, v21
	v_and_b32_e32 v18, 0xff0000, v18
	v_perm_b32 v19, v19, v20, s56
	v_or3_b32 v18, v19, v21, v18
	v_sub_f32_e32 v21, v31, v46
	v_sub_f32_e32 v20, v30, v46
	v_sub_f32_e32 v23, v29, v46
	v_sub_f32_e32 v22, v28, v46
	v_pk_mul_f32 v[20:21], v[154:155], v[20:21]
	v_pk_mul_f32 v[22:23], v[104:105], v[22:23]
	v_pk_fma_f32 v[20:21], v[20:21], v[0:1], v[4:5]
	v_pk_fma_f32 v[22:23], v[22:23], v[2:3], v[6:7]
	v_cndmask_b32_e64 v21, v21, v232, s[8:9]
	v_cndmask_b32_e64 v20, v20, v232, s[8:9]
	v_cndmask_b32_e64 v23, v23, v232, s[8:9]
	v_cndmask_b32_e64 v22, v22, v232, s[8:9]
	v_pk_mul_f32 v[24:25], v[108:109], v[20:21]
	v_pk_mul_f32 v[26:27], v[106:107], v[22:23]
	v_rndne_f32_e32 v25, v25
	v_rndne_f32_e32 v19, v27
	v_rndne_f32_e32 v26, v26
	v_cvt_i32_f32_e32 v25, v25
	v_rndne_f32_e32 v24, v24
	v_cvt_i32_f32_e32 v19, v19
	v_cvt_i32_f32_sdwa v26, v26 dst_sel:WORD_1 dst_unused:UNUSED_PAD src0_sel:DWORD
	v_cvt_i32_f32_e32 v24, v24
	v_lshlrev_b32_e32 v25, 8, v25
	v_and_b32_e32 v25, 0xff00, v25
	v_and_b32_e32 v26, 0xff0000, v26
	v_perm_b32 v19, v19, v24, s56
	v_or3_b32 v19, v19, v25, v26
	v_lshl_add_u64 v[24:25], v[124:125], 0, v[12:13]
	v_cvt_pk_f16_f32 v15, v14, v15
	v_cvt_pk_f16_f32 v14, v16, v17
	v_cvt_pk_f16_f32 v17, v22, v23
	v_cvt_pk_f16_f32 v16, v20, v21
	s_nop 1
	v_permlane16_swap_b32_e32 v14, v16
	v_permlane16_swap_b32_e32 v15, v17
	v_lshl_add_u64 v[20:21], v[24:25], 1, s[60:61]
	global_store_dwordx4 v[20:21], v[14:17], off
	v_permlane16_swap_b32_e32 v18, v19
	s_nop 0
	v_lshl_add_u64 v[14:15], s[72:73], 0, v[24:25]
	v_sub_f32_e32 v17, v81, v126
	v_sub_f32_e32 v16, v80, v126
	global_store_dwordx2 v[14:15], v[18:19], off
	v_sub_f32_e32 v15, v83, v126
	v_sub_f32_e32 v14, v82, v126
	v_pk_mul_f32 v[16:17], v[152:153], v[16:17]
	v_pk_mul_f32 v[14:15], v[88:89], v[14:15]
	v_pk_fma_f32 v[16:17], v[16:17], v[0:1], v[4:5]
	v_pk_fma_f32 v[14:15], v[14:15], v[2:3], v[6:7]
	v_cndmask_b32_e64 v17, v17, v232, s[8:9]
	v_cndmask_b32_e64 v16, v16, v232, s[8:9]
	v_cndmask_b32_e64 v15, v15, v232, s[8:9]
	v_cndmask_b32_e64 v14, v14, v232, s[8:9]
	v_pk_mul_f32 v[20:21], v[150:151], v[16:17]
	v_pk_mul_f32 v[18:19], v[90:91], v[14:15]
	v_rndne_f32_e32 v21, v21
	v_rndne_f32_e32 v20, v20
	v_cvt_i32_f32_e32 v21, v21
	v_rndne_f32_e32 v18, v18
	v_rndne_f32_e32 v19, v19
	v_cvt_i32_f32_e32 v20, v20
	v_cvt_i32_f32_sdwa v18, v18 dst_sel:WORD_1 dst_unused:UNUSED_PAD src0_sel:DWORD
	v_cvt_i32_f32_e32 v19, v19
	v_lshlrev_b32_e32 v21, 8, v21
	v_and_b32_e32 v21, 0xff00, v21
	v_and_b32_e32 v18, 0xff0000, v18
	v_perm_b32 v19, v19, v20, s56
	v_or3_b32 v18, v19, v21, v18
	v_sub_f32_e32 v21, v65, v110
	v_sub_f32_e32 v20, v64, v110
	v_sub_f32_e32 v23, v67, v110
	v_sub_f32_e32 v22, v66, v110
	v_pk_mul_f32 v[20:21], v[130:131], v[20:21]
	v_pk_mul_f32 v[22:23], v[72:73], v[22:23]
	v_pk_fma_f32 v[20:21], v[20:21], v[0:1], v[4:5]
	v_pk_fma_f32 v[22:23], v[22:23], v[2:3], v[6:7]
	v_cndmask_b32_e64 v21, v21, v232, s[8:9]
	v_cndmask_b32_e64 v20, v20, v232, s[8:9]
	v_cndmask_b32_e64 v23, v23, v232, s[8:9]
	v_cndmask_b32_e64 v22, v22, v232, s[8:9]
	v_pk_mul_f32 v[24:25], v[76:77], v[20:21]
	v_pk_mul_f32 v[26:27], v[74:75], v[22:23]
	v_rndne_f32_e32 v25, v25
	v_rndne_f32_e32 v19, v27
	v_rndne_f32_e32 v26, v26
	v_cvt_i32_f32_e32 v25, v25
	v_rndne_f32_e32 v24, v24
	v_cvt_i32_f32_e32 v19, v19
	v_cvt_i32_f32_sdwa v26, v26 dst_sel:WORD_1 dst_unused:UNUSED_PAD src0_sel:DWORD
	v_cvt_i32_f32_e32 v24, v24
	v_lshlrev_b32_e32 v25, 8, v25
	v_and_b32_e32 v25, 0xff00, v25
	v_and_b32_e32 v26, 0xff0000, v26
	v_perm_b32 v19, v19, v24, s56
	v_or3_b32 v19, v19, v25, v26
	v_lshl_add_u64 v[24:25], v[92:93], 0, v[12:13]
	v_cvt_pk_f16_f32 v15, v14, v15
	v_cvt_pk_f16_f32 v14, v16, v17
	v_cvt_pk_f16_f32 v17, v22, v23
	v_cvt_pk_f16_f32 v16, v20, v21
	s_nop 1
	v_permlane16_swap_b32_e32 v14, v16
	v_permlane16_swap_b32_e32 v15, v17
	v_lshl_add_u64 v[20:21], v[24:25], 1, s[60:61]
	v_pk_fma_f32 v[8:9], v[8:9], v[0:1], v[4:5]
	global_store_dwordx4 v[20:21], v[14:17], off
	v_permlane16_swap_b32_e32 v18, v19
	s_nop 0
	v_lshl_add_u64 v[14:15], s[72:73], 0, v[24:25]
	v_pk_fma_f32 v[10:11], v[10:11], v[2:3], v[6:7]
	v_cndmask_b32_e64 v9, v9, v232, s[8:9]
	v_cndmask_b32_e64 v8, v8, v232, s[8:9]
	global_store_dwordx2 v[14:15], v[18:19], off
	v_cndmask_b32_e64 v11, v11, v232, s[8:9]
	v_cndmask_b32_e64 v10, v10, v232, s[8:9]
	v_pk_mul_f32 v[14:15], v[128:129], v[8:9] op_sel_hi:[0,1]
	v_pk_mul_f32 v[16:17], v[128:129], v[10:11] op_sel_hi:[0,1]
	v_rndne_f32_e32 v15, v15
	v_rndne_f32_e32 v17, v17
	v_rndne_f32_e32 v16, v16
	v_cvt_i32_f32_e32 v15, v15
	v_rndne_f32_e32 v14, v14
	v_cvt_i32_f32_e32 v17, v17
	v_cvt_i32_f32_sdwa v16, v16 dst_sel:WORD_1 dst_unused:UNUSED_PAD src0_sel:DWORD
	v_cvt_i32_f32_e32 v14, v14
	v_lshlrev_b32_e32 v15, 8, v15
	v_and_b32_e32 v15, 0xff00, v15
	v_and_b32_e32 v16, 0xff0000, v16
	v_perm_b32 v14, v17, v14, s56
	v_or3_b32 v15, v14, v15, v16
	v_sub_f32_e32 v17, v49, v78
	v_sub_f32_e32 v16, v48, v78
	v_sub_f32_e32 v19, v51, v78
	v_sub_f32_e32 v18, v50, v78
	v_pk_mul_f32 v[16:17], v[78:79], v[16:17] op_sel:[1,0]
	v_pk_mul_f32 v[18:19], v[78:79], v[18:19] op_sel:[1,0]
	v_pk_fma_f32 v[0:1], v[16:17], v[0:1], v[4:5]
	v_pk_fma_f32 v[2:3], v[18:19], v[2:3], v[6:7]
	v_cndmask_b32_e64 v5, v1, v232, s[8:9]
	v_cndmask_b32_e64 v4, v0, v232, s[8:9]
	v_cndmask_b32_e64 v3, v3, v232, s[8:9]
	v_cndmask_b32_e64 v2, v2, v232, s[8:9]
	v_pk_mul_f32 v[0:1], v[60:61], v[4:5] op_sel_hi:[0,1]
	v_pk_mul_f32 v[6:7], v[60:61], v[2:3] op_sel_hi:[0,1]
	v_rndne_f32_e32 v1, v1
	v_rndne_f32_e32 v7, v7
	v_rndne_f32_e32 v6, v6
	v_cvt_i32_f32_e32 v1, v1
	v_rndne_f32_e32 v0, v0
	v_cvt_i32_f32_e32 v7, v7
	v_cvt_i32_f32_sdwa v6, v6 dst_sel:WORD_1 dst_unused:UNUSED_PAD src0_sel:DWORD
	v_cvt_i32_f32_e32 v0, v0
	v_lshlrev_b32_e32 v1, 8, v1
	v_and_b32_e32 v1, 0xff00, v1
	v_and_b32_e32 v6, 0xff0000, v6
	v_perm_b32 v0, v7, v0, s56
	v_or3_b32 v14, v0, v1, v6
	v_lshl_add_u64 v[6:7], v[62:63], 0, v[12:13]
	v_cvt_pk_f16_f32 v1, v2, v3
	v_cvt_pk_f16_f32 v0, v4, v5
	v_cvt_pk_f16_f32 v3, v10, v11
	v_cvt_pk_f16_f32 v2, v8, v9
	s_nop 1
	v_permlane16_swap_b32_e32 v0, v2
	v_permlane16_swap_b32_e32 v1, v3
	v_lshl_add_u64 v[4:5], v[6:7], 1, s[60:61]
	global_store_dwordx4 v[4:5], v[0:3], off
	v_permlane16_swap_b32_e32 v14, v15
	s_nop 0
	v_lshl_add_u64 v[0:1], s[72:73], 0, v[6:7]
	s_mov_b64 s[8:9], 0
	global_store_dwordx2 v[0:1], v[14:15], off

.LBB0_551:
	s_or_b64 exec, exec, s[10:11]
	s_lshl_b32 s3, s5, 5
	v_readlane_b32 s8, v253, 46
	v_ashrrev_i32_e32 v152, 2, v143
	s_or_b32 s0, s8, s3
	v_and_b32_e32 v0, -4, v152
	v_add_u32_e32 v0, s0, v0
	v_ashrrev_i32_e32 v1, 31, v0
	v_lshlrev_b64 v[4:5], 2, v[0:1]
	s_waitcnt lgkmcnt(0)
	s_barrier
	v_lshl_add_u64 v[102:103], s[14:15], 0, v[4:5]
	v_lshl_add_u64 v[112:113], s[16:17], 0, v[4:5]
	global_load_dwordx4 v[0:3], v[102:103], off
	global_load_dwordx4 v[4:7], v[112:113], off
	global_load_dwordx4 v[180:183], v[102:103], off offset:64
	global_load_dwordx4 v[184:187], v[112:113], off offset:64
	global_load_dwordx4 v[188:191], v[102:103], off offset:512
	global_load_dwordx4 v[192:195], v[112:113], off offset:512
	global_load_dwordx4 v[196:199], v[102:103], off offset:576
	global_load_dwordx4 v[200:203], v[112:113], off offset:576
	v_and_b32_e32 v150, 15, v143
	v_or_b32_e32 v129, s4, v150
	v_lshl_add_u32 v101, v129, 3, 0
	v_lshlrev_b32_e32 v149, 2, v129
	s_waitcnt lgkmcnt(0)
	v_cmp_ne_u32_e32 vcc, 0, v100
	v_sub_u32_e32 v100, v101, v149
	ds_read_b64 v[114:115], v101 offset:8192
	ds_read_b32 v101, v100 offset:12288
	v_readlane_b32 s3, v254, 55
	s_or_b64 s[6:7], vcc, s[6:7]
	s_or_b32 s3, s5, s3
	s_cmp_eq_u32 s3, 0
	s_cselect_b64 s[8:9], -1, 0
	v_cmp_gt_u32_e32 vcc, 16, v143
	s_waitcnt lgkmcnt(0)
	v_max_f32_e32 v101, v101, v101
	v_max_f32_e32 v142, 0xda24260, v101
	s_and_b64 s[8:9], s[8:9], vcc
	s_and_saveexec_b64 s[10:11], s[8:9]
	s_cbranch_execz .LBB0_553
	v_readlane_b32 s3, v254, 17
	v_mul_f32_e32 v101, 0x3c010204, v142
	v_cndmask_b32_e64 v101, v101, v232, s[6:7]
	v_add_u32_e32 v154, s3, v129
	v_ashrrev_i32_e32 v155, 31, v154
	v_lshl_add_u64 v[154:155], v[154:155], 2, s[54:55]
	global_store_dword v[154:155], v101, off

.LBB0_567:
	s_or_b64 exec, exec, s[10:11]
	s_waitcnt lgkmcnt(0)
	v_sub_f32_e32 v145, v145, v140
	v_sub_f32_e32 v144, v144, v140
	v_pk_mul_f32 v[144:145], v[140:141], v[144:145] op_sel:[1,0]
	v_div_scale_f32 v129, s[4:5], v149, v149, s57
	v_pk_fma_f32 v[144:145], v[2:3], v[144:145], v[6:7]
	v_sub_f32_e32 v45, v45, v60
	v_cndmask_b32_e64 v153, v145, v232, s[6:7]
	v_rcp_f32_e32 v145, v129
	v_sub_f32_e32 v44, v44, v60
	v_pk_mul_f32 v[44:45], v[60:61], v[44:45] op_sel:[1,0]
	v_cndmask_b32_e64 v152, v144, v232, s[6:7]
	v_fma_f32 v144, -v129, v145, 1.0
	v_pk_fma_f32 v[2:3], v[2:3], v[44:45], v[6:7]
	v_div_scale_f32 v6, s[4:5], v143, v143, s57
	v_fmac_f32_e32 v145, v144, v145
	v_div_scale_f32 v144, vcc, s57, v149, s57
	v_rcp_f32_e32 v7, v6
	v_sub_f32_e32 v147, v147, v140
	v_sub_f32_e32 v146, v146, v140
	v_mul_f32_e32 v151, v144, v145
	v_sub_f32_e32 v47, v47, v60
	v_sub_f32_e32 v46, v46, v60
	v_pk_mul_f32 v[146:147], v[140:141], v[146:147] op_sel:[1,0]
	v_fma_f32 v154, -v129, v151, v144
	v_pk_mul_f32 v[46:47], v[60:61], v[46:47] op_sel:[1,0]
	v_pk_fma_f32 v[146:147], v[0:1], v[146:147], v[4:5]
	v_fmac_f32_e32 v151, v154, v145
	v_pk_fma_f32 v[0:1], v[0:1], v[46:47], v[4:5]
	v_fma_f32 v129, -v129, v151, v144
	v_cndmask_b32_e64 v4, v0, v232, s[6:7]
	v_fma_f32 v0, -v6, v7, 1.0
	v_div_fmas_f32 v129, v129, v145, v151
	v_fmac_f32_e32 v7, v0, v7
	v_div_scale_f32 v0, vcc, s57, v143, s57
	v_cndmask_b32_e64 v5, v1, v232, s[6:7]
	v_mul_f32_e32 v1, v0, v7
	v_fma_f32 v44, -v6, v1, v0
	v_fmac_f32_e32 v1, v44, v7
	v_fma_f32 v0, -v6, v1, v0
	v_div_fmas_f32 v0, v0, v7, v1
	v_div_fixup_f32 v44, v0, v143, s57
	v_cndmask_b32_e64 v3, v3, v232, s[6:7]
	v_cndmask_b32_e64 v2, v2, v232, s[6:7]
	v_pk_mul_f32 v[0:1], v[44:45], v[4:5] op_sel_hi:[0,1]
	v_pk_mul_f32 v[6:7], v[44:45], v[2:3] op_sel_hi:[0,1]
	v_rndne_f32_e32 v1, v1
	v_rndne_f32_e32 v7, v7
	v_rndne_f32_e32 v6, v6
	v_cvt_i32_f32_e32 v1, v1
	v_rndne_f32_e32 v0, v0
	v_cndmask_b32_e64 v147, v147, v232, s[6:7]
	v_cndmask_b32_e64 v146, v146, v232, s[6:7]
	v_div_fixup_f32 v144, v129, v149, s57
	v_cvt_i32_f32_e32 v7, v7
	v_cvt_i32_f32_sdwa v6, v6 dst_sel:WORD_1 dst_unused:UNUSED_PAD src0_sel:DWORD
	v_cvt_i32_f32_e32 v0, v0
	v_pk_mul_f32 v[154:155], v[144:145], v[146:147] op_sel_hi:[0,1]
	v_pk_mul_f32 v[156:157], v[144:145], v[152:153] op_sel_hi:[0,1]
	v_rndne_f32_e32 v149, v155
	v_rndne_f32_e32 v129, v157
	v_rndne_f32_e32 v145, v156
	v_cvt_i32_f32_e32 v149, v149
	v_rndne_f32_e32 v151, v154
	v_lshlrev_b32_e32 v1, 8, v1
	v_cvt_i32_f32_e32 v129, v129
	v_cvt_i32_f32_sdwa v145, v145 dst_sel:WORD_1 dst_unused:UNUSED_PAD src0_sel:DWORD
	v_cvt_i32_f32_e32 v151, v151
	v_and_b32_e32 v6, 0xff0000, v6
	v_and_b32_e32 v1, 0xff00, v1
	v_perm_b32 v0, v7, v0, s56
	v_or3_b32 v154, v0, v1, v6
	v_or_b32_e32 v0, v131, v109
	v_ashrrev_i32_e32 v1, 31, v0
	v_lshlrev_b32_e32 v149, 8, v149
	v_lshlrev_b64 v[46:47], 10, v[0:1]
	v_and_b32_e32 v145, 0xff0000, v145
	v_and_b32_e32 v149, 0xff00, v149
	v_perm_b32 v129, v129, v151, s56
	v_lshl_add_u64 v[6:7], v[46:47], 0, v[138:139]
	v_cvt_pk_f16_f32 v1, v2, v3
	v_cvt_pk_f16_f32 v0, v4, v5
	v_cvt_pk_f16_f32 v3, v152, v153
	v_cvt_pk_f16_f32 v2, v146, v147
	v_or3_b32 v155, v129, v149, v145
	s_nop 0
	v_permlane16_swap_b32_e32 v0, v2
	v_permlane16_swap_b32_e32 v1, v3
	v_lshl_add_u64 v[4:5], v[6:7], 1, s[60:61]
	global_store_dwordx4 v[4:5], v[0:3], off
	v_permlane16_swap_b32_e32 v154, v155
	s_nop 0
	v_lshl_add_u64 v[0:1], s[72:73], 0, v[6:7]
	global_store_dwordx2 v[0:1], v[154:155], off
	v_mov_b32_e32 v0, v180
	v_mov_b32_e32 v1, v181
	v_mov_b32_e32 v2, v182
	v_mov_b32_e32 v3, v183
	v_mov_b32_e32 v4, v184
	v_mov_b32_e32 v5, v185
	v_mov_b32_e32 v6, v186
	v_mov_b32_e32 v7, v187
	v_mov_b32_e32 v160, v115
	v_mov_b32_e32 v161, v115
	v_sub_f32_e32 v125, v125, v114
	v_sub_f32_e32 v124, v124, v114
	v_sub_f32_e32 v127, v127, v114
	v_sub_f32_e32 v126, v126, v114
	v_pk_mul_f32 v[164:165], v[160:161], v[124:125]
	v_mov_b32_e32 v124, v115
	v_mov_b32_e32 v125, v115
	v_pk_mul_f32 v[126:127], v[124:125], v[126:127]
	v_mov_b32_e32 v143, v142
	v_mov_b32_e32 v158, v101
	v_mov_b32_e32 v159, v101
	v_sub_f32_e32 v123, v123, v100
	v_sub_f32_e32 v122, v122, v100
	v_pk_mul_f32 v[122:123], v[158:159], v[122:123]
	v_mov_b32_e32 v129, v128
	v_lshl_add_u64 v[162:163], v[138:139], 0, 16
	v_mov_b32_e32 v156, v137
	v_mov_b32_e32 v157, v137
	v_sub_f32_e32 v97, v97, v136
	v_sub_f32_e32 v96, v96, v136
	v_sub_f32_e32 v99, v99, v136
	v_sub_f32_e32 v98, v98, v136
	v_mov_b32_e32 v149, v148
	v_mov_b32_e32 v154, v133
	v_mov_b32_e32 v155, v133
	v_sub_f32_e32 v107, v107, v132
	v_sub_f32_e32 v106, v106, v132
	v_pk_mul_f32 v[106:107], v[154:155], v[106:107]
	v_mov_b32_e32 v109, v108
	v_mov_b32_e32 v152, v119
	v_mov_b32_e32 v153, v119
	v_sub_f32_e32 v57, v57, v118
	v_sub_f32_e32 v56, v56, v118
	v_sub_f32_e32 v59, v59, v118
	v_sub_f32_e32 v58, v58, v118
	v_mov_b32_e32 v151, v150
	v_mov_b32_e32 v146, v111
	v_mov_b32_e32 v147, v111
	v_sub_f32_e32 v43, v43, v110
	v_sub_f32_e32 v42, v42, v110
	v_mov_b32_e32 v131, v130
	v_sub_f32_e32 v25, v25, v60
	v_sub_f32_e32 v24, v24, v60
	v_sub_f32_e32 v31, v31, v140
	v_sub_f32_e32 v30, v30, v140
	v_sub_f32_e32 v27, v27, v60
	v_sub_f32_e32 v26, v26, v60
	v_pk_mul_f32 v[24:25], v[60:61], v[24:25] op_sel:[1,0]
	v_sub_f32_e32 v29, v29, v140
	v_sub_f32_e32 v28, v28, v140
	v_pk_mul_f32 v[30:31], v[140:141], v[30:31] op_sel:[1,0]
	v_pk_mul_f32 v[26:27], v[60:61], v[26:27] op_sel:[1,0]
	v_pk_mul_f32 v[28:29], v[140:141], v[28:29] op_sel:[1,0]
	v_sub_f32_e32 v37, v37, v110
	v_sub_f32_e32 v36, v36, v110
	v_sub_f32_e32 v39, v39, v110
	v_sub_f32_e32 v38, v38, v110
	v_pk_mul_f32 v[36:37], v[146:147], v[36:37]
	v_sub_f32_e32 v21, v21, v60
	v_sub_f32_e32 v20, v20, v60
	v_sub_f32_e32 v15, v15, v140
	v_sub_f32_e32 v14, v14, v140
	v_sub_f32_e32 v23, v23, v60
	v_sub_f32_e32 v22, v22, v60
	v_pk_mul_f32 v[20:21], v[60:61], v[20:21] op_sel:[1,0]
	v_sub_f32_e32 v13, v13, v140
	v_sub_f32_e32 v12, v12, v140
	v_pk_mul_f32 v[14:15], v[140:141], v[14:15] op_sel:[1,0]
	v_pk_mul_f32 v[22:23], v[60:61], v[22:23] op_sel:[1,0]
	v_pk_mul_f32 v[12:13], v[140:141], v[12:13] op_sel:[1,0]
	s_mov_b64 s[4:5], 0x90
	v_sub_f32_e32 v11, v11, v140
	v_sub_f32_e32 v10, v10, v140
	v_sub_f32_e32 v17, v17, v60
	v_sub_f32_e32 v16, v16, v60
	v_sub_f32_e32 v9, v9, v140
	v_sub_f32_e32 v8, v8, v140
	v_pk_fma_f32 v[164:165], v[164:165], v[0:1], v[4:5]
	v_pk_fma_f32 v[126:127], v[126:127], v[2:3], v[6:7]
	v_cndmask_b32_e64 v167, v165, v232, s[6:7]
	v_cndmask_b32_e64 v166, v164, v232, s[6:7]
	v_cndmask_b32_e64 v165, v127, v232, s[6:7]
	v_cndmask_b32_e64 v164, v126, v232, s[6:7]
	v_mov_b32_e32 v126, v142
	v_mov_b32_e32 v127, v142
	v_pk_mul_f32 v[170:171], v[142:143], v[166:167]
	v_pk_mul_f32 v[168:169], v[126:127], v[164:165]
	v_rndne_f32_e32 v115, v171
	v_rndne_f32_e32 v45, v170
	v_cvt_i32_f32_e32 v115, v115
	v_rndne_f32_e32 v145, v168
	v_rndne_f32_e32 v168, v169
	v_cvt_i32_f32_e32 v45, v45
	v_cvt_i32_f32_sdwa v145, v145 dst_sel:WORD_1 dst_unused:UNUSED_PAD src0_sel:DWORD
	v_cvt_i32_f32_e32 v168, v168
	v_sub_f32_e32 v171, v121, v100
	v_sub_f32_e32 v170, v120, v100
	v_mov_b32_e32 v120, v101
	v_mov_b32_e32 v121, v101
	v_pk_mul_f32 v[170:171], v[120:121], v[170:171]
	v_pk_fma_f32 v[122:123], v[122:123], v[0:1], v[4:5]
	v_lshlrev_b32_e32 v115, 8, v115
	v_pk_fma_f32 v[170:171], v[170:171], v[2:3], v[6:7]
	v_cndmask_b32_e64 v173, v123, v232, s[6:7]
	v_cndmask_b32_e64 v172, v122, v232, s[6:7]
	v_and_b32_e32 v115, 0xff00, v115
	v_and_b32_e32 v145, 0xff0000, v145
	v_perm_b32 v45, v168, v45, s56
	v_cndmask_b32_e64 v171, v171, v232, s[6:7]
	v_cndmask_b32_e64 v170, v170, v232, s[6:7]
	v_pk_mul_f32 v[174:175], v[128:129], v[172:173]
	v_mov_b32_e32 v122, v128
	v_mov_b32_e32 v123, v128
	v_or3_b32 v168, v45, v115, v145
	v_pk_mul_f32 v[176:177], v[122:123], v[170:171]
	v_rndne_f32_e32 v115, v175
	v_rndne_f32_e32 v45, v177
	v_rndne_f32_e32 v101, v176
	v_cvt_i32_f32_e32 v115, v115
	v_rndne_f32_e32 v145, v174
	v_cvt_i32_f32_e32 v45, v45
	v_cvt_i32_f32_sdwa v101, v101 dst_sel:WORD_1 dst_unused:UNUSED_PAD src0_sel:DWORD
	v_cvt_i32_f32_e32 v145, v145
	v_lshlrev_b32_e32 v115, 8, v115
	v_and_b32_e32 v115, 0xff00, v115
	v_and_b32_e32 v101, 0xff0000, v101
	v_perm_b32 v45, v45, v145, s56
	v_lshl_add_u64 v[174:175], v[134:135], 0, v[162:163]
	v_cvt_pk_f16_f32 v165, v164, v165
	v_cvt_pk_f16_f32 v164, v166, v167
	v_cvt_pk_f16_f32 v167, v170, v171
	v_cvt_pk_f16_f32 v166, v172, v173
	v_or3_b32 v169, v45, v115, v101
	s_nop 0
	v_permlane16_swap_b32_e32 v164, v166
	v_permlane16_swap_b32_e32 v165, v167
	v_lshl_add_u64 v[170:171], v[174:175], 1, s[60:61]
	global_store_dwordx4 v[170:171], v[164:167], off
	v_permlane16_swap_b32_e32 v168, v169
	s_nop 0
	v_lshl_add_u64 v[164:165], s[72:73], 0, v[174:175]
	global_store_dwordx2 v[164:165], v[168:169], off
	v_pk_mul_f32 v[164:165], v[156:157], v[96:97]
	v_mov_b32_e32 v96, v137
	v_mov_b32_e32 v97, v137
	v_pk_mul_f32 v[98:99], v[96:97], v[98:99]
	v_pk_fma_f32 v[164:165], v[164:165], v[0:1], v[4:5]
	v_pk_fma_f32 v[98:99], v[98:99], v[2:3], v[6:7]
	v_cndmask_b32_e64 v167, v165, v232, s[6:7]
	v_cndmask_b32_e64 v166, v164, v232, s[6:7]
	v_cndmask_b32_e64 v165, v99, v232, s[6:7]
	v_cndmask_b32_e64 v164, v98, v232, s[6:7]
	v_mov_b32_e32 v98, v148
	v_mov_b32_e32 v99, v148
	v_pk_mul_f32 v[170:171], v[148:149], v[166:167]
	v_pk_mul_f32 v[168:169], v[98:99], v[164:165]
	v_rndne_f32_e32 v101, v171
	v_rndne_f32_e32 v45, v170
	v_cvt_i32_f32_e32 v101, v101
	v_rndne_f32_e32 v115, v168
	v_rndne_f32_e32 v137, v169
	v_cvt_i32_f32_e32 v45, v45
	v_cvt_i32_f32_sdwa v115, v115 dst_sel:WORD_1 dst_unused:UNUSED_PAD src0_sel:DWORD
	v_cvt_i32_f32_e32 v137, v137
	v_sub_f32_e32 v171, v105, v132
	v_sub_f32_e32 v170, v104, v132
	v_mov_b32_e32 v104, v133
	v_mov_b32_e32 v105, v133
	v_pk_mul_f32 v[170:171], v[104:105], v[170:171]
	v_pk_fma_f32 v[106:107], v[106:107], v[0:1], v[4:5]
	v_lshlrev_b32_e32 v101, 8, v101
	v_pk_fma_f32 v[170:171], v[170:171], v[2:3], v[6:7]
	v_cndmask_b32_e64 v173, v107, v232, s[6:7]
	v_cndmask_b32_e64 v172, v106, v232, s[6:7]
	v_and_b32_e32 v101, 0xff00, v101
	v_and_b32_e32 v115, 0xff0000, v115
	v_perm_b32 v45, v137, v45, s56
	v_cndmask_b32_e64 v171, v171, v232, s[6:7]
	v_cndmask_b32_e64 v170, v170, v232, s[6:7]
	v_pk_mul_f32 v[174:175], v[108:109], v[172:173]
	v_mov_b32_e32 v106, v108
	v_mov_b32_e32 v107, v108
	v_or3_b32 v168, v45, v101, v115
	v_pk_mul_f32 v[176:177], v[106:107], v[170:171]
	v_rndne_f32_e32 v115, v175
	v_rndne_f32_e32 v45, v177
	v_rndne_f32_e32 v101, v176
	v_cvt_i32_f32_e32 v115, v115
	v_rndne_f32_e32 v133, v174
	v_cvt_i32_f32_e32 v45, v45
	v_cvt_i32_f32_sdwa v101, v101 dst_sel:WORD_1 dst_unused:UNUSED_PAD src0_sel:DWORD
	v_cvt_i32_f32_e32 v133, v133
	v_lshlrev_b32_e32 v115, 8, v115
	v_and_b32_e32 v115, 0xff00, v115
	v_and_b32_e32 v101, 0xff0000, v101
	v_perm_b32 v45, v45, v133, s56
	v_lshl_add_u64 v[174:175], v[116:117], 0, v[162:163]
	v_cvt_pk_f16_f32 v165, v164, v165
	v_cvt_pk_f16_f32 v164, v166, v167
	v_cvt_pk_f16_f32 v167, v170, v171
	v_cvt_pk_f16_f32 v166, v172, v173
	v_or3_b32 v169, v45, v115, v101
	s_nop 0
	v_permlane16_swap_b32_e32 v164, v166
	v_permlane16_swap_b32_e32 v165, v167
	v_lshl_add_u64 v[170:171], v[174:175], 1, s[60:61]
	global_store_dwordx4 v[170:171], v[164:167], off
	v_permlane16_swap_b32_e32 v168, v169
	s_nop 0
	v_lshl_add_u64 v[164:165], s[72:73], 0, v[174:175]
	global_store_dwordx2 v[164:165], v[168:169], off
	v_pk_mul_f32 v[164:165], v[152:153], v[56:57]
	v_mov_b32_e32 v56, v119
	v_mov_b32_e32 v57, v119
	v_pk_mul_f32 v[58:59], v[56:57], v[58:59]
	v_pk_fma_f32 v[164:165], v[164:165], v[0:1], v[4:5]
	v_pk_fma_f32 v[58:59], v[58:59], v[2:3], v[6:7]
	v_cndmask_b32_e64 v167, v165, v232, s[6:7]
	v_cndmask_b32_e64 v166, v164, v232, s[6:7]
	v_cndmask_b32_e64 v165, v59, v232, s[6:7]
	v_cndmask_b32_e64 v164, v58, v232, s[6:7]
	v_mov_b32_e32 v58, v150
	v_mov_b32_e32 v59, v150
	v_pk_mul_f32 v[170:171], v[150:151], v[166:167]
	v_pk_mul_f32 v[168:169], v[58:59], v[164:165]
	v_rndne_f32_e32 v101, v171
	v_rndne_f32_e32 v45, v170
	v_cvt_i32_f32_e32 v101, v101
	v_rndne_f32_e32 v115, v168
	v_rndne_f32_e32 v119, v169
	v_sub_f32_e32 v171, v41, v110
	v_sub_f32_e32 v170, v40, v110
	v_cvt_i32_f32_e32 v45, v45
	v_cvt_i32_f32_sdwa v115, v115 dst_sel:WORD_1 dst_unused:UNUSED_PAD src0_sel:DWORD
	v_cvt_i32_f32_e32 v119, v119
	v_mov_b32_e32 v40, v111
	v_mov_b32_e32 v41, v111
	v_pk_mul_f32 v[170:171], v[146:147], v[170:171]
	v_pk_mul_f32 v[42:43], v[40:41], v[42:43]
	v_pk_fma_f32 v[170:171], v[170:171], v[0:1], v[4:5]
	v_pk_fma_f32 v[42:43], v[42:43], v[2:3], v[6:7]
	v_cndmask_b32_e64 v171, v171, v232, s[6:7]
	v_cndmask_b32_e64 v170, v170, v232, s[6:7]
	v_lshlrev_b32_e32 v101, 8, v101
	v_cndmask_b32_e64 v173, v43, v232, s[6:7]
	v_cndmask_b32_e64 v172, v42, v232, s[6:7]
	v_pk_mul_f32 v[174:175], v[130:131], v[170:171]
	v_mov_b32_e32 v42, v130
	v_mov_b32_e32 v43, v130
	v_and_b32_e32 v101, 0xff00, v101
	v_and_b32_e32 v115, 0xff0000, v115
	v_perm_b32 v45, v119, v45, s56
	v_pk_mul_f32 v[176:177], v[42:43], v[172:173]
	v_rndne_f32_e32 v111, v175
	v_or3_b32 v168, v45, v101, v115
	v_rndne_f32_e32 v45, v177
	v_rndne_f32_e32 v101, v176
	v_cvt_i32_f32_e32 v111, v111
	v_rndne_f32_e32 v115, v174
	v_cvt_i32_f32_e32 v45, v45
	v_cvt_i32_f32_sdwa v101, v101 dst_sel:WORD_1 dst_unused:UNUSED_PAD src0_sel:DWORD
	v_cvt_i32_f32_e32 v115, v115
	v_lshlrev_b32_e32 v111, 8, v111
	v_pk_fma_f32 v[24:25], v[24:25], v[0:1], v[4:5]
	v_pk_fma_f32 v[0:1], v[30:31], v[0:1], v[4:5]
	v_and_b32_e32 v101, 0xff0000, v101
	v_and_b32_e32 v111, 0xff00, v111
	v_perm_b32 v45, v45, v115, s56
	v_lshl_add_u64 v[174:175], v[62:63], 0, v[162:163]
	v_cvt_pk_f16_f32 v165, v164, v165
	v_cvt_pk_f16_f32 v164, v166, v167
	v_cvt_pk_f16_f32 v167, v172, v173
	v_cvt_pk_f16_f32 v166, v170, v171
	v_pk_fma_f32 v[26:27], v[26:27], v[2:3], v[6:7]
	v_pk_fma_f32 v[2:3], v[28:29], v[2:3], v[6:7]
	v_cndmask_b32_e64 v5, v1, v232, s[6:7]
	v_cndmask_b32_e64 v4, v0, v232, s[6:7]
	v_or3_b32 v169, v45, v111, v101
	v_permlane16_swap_b32_e32 v164, v166
	v_permlane16_swap_b32_e32 v165, v167
	v_lshl_add_u64 v[170:171], v[174:175], 1, s[60:61]
	v_cndmask_b32_e64 v25, v25, v232, s[6:7]
	v_cndmask_b32_e64 v24, v24, v232, s[6:7]
	v_cndmask_b32_e64 v3, v3, v232, s[6:7]
	v_cndmask_b32_e64 v2, v2, v232, s[6:7]
	v_pk_mul_f32 v[0:1], v[144:145], v[4:5] op_sel_hi:[0,1]
	global_store_dwordx4 v[170:171], v[164:167], off
	v_permlane16_swap_b32_e32 v168, v169
	s_nop 0
	v_lshl_add_u64 v[164:165], s[72:73], 0, v[174:175]
	v_cndmask_b32_e64 v27, v27, v232, s[6:7]
	v_cndmask_b32_e64 v26, v26, v232, s[6:7]
	v_pk_mul_f32 v[166:167], v[44:45], v[24:25] op_sel_hi:[0,1]
	v_pk_mul_f32 v[6:7], v[144:145], v[2:3] op_sel_hi:[0,1]
	v_rndne_f32_e32 v1, v1
	global_store_dwordx2 v[164:165], v[168:169], off
	v_pk_mul_f32 v[164:165], v[44:45], v[26:27] op_sel_hi:[0,1]
	v_rndne_f32_e32 v101, v167
	v_rndne_f32_e32 v7, v7
	v_rndne_f32_e32 v6, v6
	v_cvt_i32_f32_e32 v1, v1
	v_rndne_f32_e32 v0, v0
	v_rndne_f32_e32 v45, v166
	v_cvt_i32_f32_e32 v101, v101
	v_rndne_f32_e32 v111, v164
	v_rndne_f32_e32 v115, v165
	v_cvt_i32_f32_e32 v7, v7
	v_cvt_i32_f32_sdwa v6, v6 dst_sel:WORD_1 dst_unused:UNUSED_PAD src0_sel:DWORD
	v_cvt_i32_f32_e32 v0, v0
	v_cvt_i32_f32_e32 v45, v45
	v_cvt_i32_f32_sdwa v111, v111 dst_sel:WORD_1 dst_unused:UNUSED_PAD src0_sel:DWORD
	v_cvt_i32_f32_e32 v115, v115
	v_lshlrev_b32_e32 v1, 8, v1
	v_lshlrev_b32_e32 v101, 8, v101
	v_and_b32_e32 v6, 0xff0000, v6
	v_and_b32_e32 v1, 0xff00, v1
	v_perm_b32 v0, v7, v0, s56
	v_and_b32_e32 v101, 0xff00, v101
	v_and_b32_e32 v111, 0xff0000, v111
	v_perm_b32 v45, v115, v45, s56
	v_or3_b32 v165, v0, v1, v6
	v_lshl_add_u64 v[6:7], v[46:47], 0, v[162:163]
	v_cvt_pk_f16_f32 v1, v26, v27
	v_cvt_pk_f16_f32 v0, v24, v25
	v_cvt_pk_f16_f32 v3, v2, v3
	v_cvt_pk_f16_f32 v2, v4, v5
	v_or3_b32 v164, v45, v101, v111
	s_nop 0
	v_permlane16_swap_b32_e32 v0, v2
	v_permlane16_swap_b32_e32 v1, v3
	v_lshl_add_u64 v[4:5], v[6:7], 1, s[60:61]
	global_store_dwordx4 v[4:5], v[0:3], off
	v_permlane16_swap_b32_e32 v164, v165
	s_nop 0
	v_lshl_add_u64 v[0:1], s[72:73], 0, v[6:7]
	global_store_dwordx2 v[0:1], v[164:165], off
	v_mov_b32_e32 v0, v188
	v_mov_b32_e32 v1, v189
	v_mov_b32_e32 v2, v190
	v_mov_b32_e32 v3, v191
	v_mov_b32_e32 v4, v192
	v_mov_b32_e32 v5, v193
	v_mov_b32_e32 v6, v194
	v_mov_b32_e32 v7, v195
	v_sub_f32_e32 v29, v81, v114
	v_sub_f32_e32 v28, v80, v114
	v_sub_f32_e32 v27, v83, v114
	v_sub_f32_e32 v26, v82, v114
	v_pk_mul_f32 v[28:29], v[160:161], v[28:29]
	v_pk_mul_f32 v[26:27], v[124:125], v[26:27]
	v_sub_f32_e32 v83, v87, v100
	v_sub_f32_e32 v82, v86, v100
	v_pk_mul_f32 v[82:83], v[120:121], v[82:83]
	v_lshl_add_u64 v[24:25], v[138:139], 0, s[96:97]
	v_pk_mul_f32 v[38:39], v[40:41], v[38:39]
	v_pk_mul_f32 v[10:11], v[140:141], v[10:11] op_sel:[1,0]
	v_sub_f32_e32 v19, v19, v60
	v_sub_f32_e32 v18, v18, v60
	v_pk_mul_f32 v[16:17], v[60:61], v[16:17] op_sel:[1,0]
	v_pk_mul_f32 v[8:9], v[140:141], v[8:9] op_sel:[1,0]
	v_pk_mul_f32 v[18:19], v[60:61], v[18:19] op_sel:[1,0]
	v_pk_fma_f32 v[28:29], v[28:29], v[0:1], v[4:5]
	v_pk_fma_f32 v[26:27], v[26:27], v[2:3], v[6:7]
	v_cndmask_b32_e64 v29, v29, v232, s[6:7]
	v_cndmask_b32_e64 v28, v28, v232, s[6:7]
	v_cndmask_b32_e64 v27, v27, v232, s[6:7]
	v_cndmask_b32_e64 v26, v26, v232, s[6:7]
	v_pk_mul_f32 v[80:81], v[142:143], v[28:29]
	v_pk_mul_f32 v[30:31], v[126:127], v[26:27]
	v_rndne_f32_e32 v45, v80
	v_rndne_f32_e32 v80, v81
	v_cvt_i32_f32_e32 v80, v80
	v_rndne_f32_e32 v30, v30
	v_rndne_f32_e32 v31, v31
	v_cvt_i32_f32_e32 v45, v45
	v_cvt_i32_f32_sdwa v30, v30 dst_sel:WORD_1 dst_unused:UNUSED_PAD src0_sel:DWORD
	v_cvt_i32_f32_e32 v31, v31
	v_lshlrev_b32_e32 v80, 8, v80
	v_and_b32_e32 v80, 0xff00, v80
	v_and_b32_e32 v30, 0xff0000, v30
	v_perm_b32 v31, v31, v45, s56
	v_or3_b32 v30, v31, v80, v30
	v_sub_f32_e32 v81, v85, v100
	v_sub_f32_e32 v80, v84, v100
	v_pk_mul_f32 v[80:81], v[158:159], v[80:81]
	v_pk_fma_f32 v[82:83], v[82:83], v[2:3], v[6:7]
	v_pk_fma_f32 v[80:81], v[80:81], v[0:1], v[4:5]
	v_cndmask_b32_e64 v83, v83, v232, s[6:7]
	v_cndmask_b32_e64 v81, v81, v232, s[6:7]
	v_cndmask_b32_e64 v80, v80, v232, s[6:7]
	v_cndmask_b32_e64 v82, v82, v232, s[6:7]
	v_pk_mul_f32 v[84:85], v[128:129], v[80:81]
	v_pk_mul_f32 v[86:87], v[122:123], v[82:83]
	v_rndne_f32_e32 v85, v85
	v_rndne_f32_e32 v31, v87
	v_rndne_f32_e32 v45, v86
	v_cvt_i32_f32_e32 v85, v85
	v_rndne_f32_e32 v84, v84
	v_cvt_i32_f32_e32 v31, v31
	v_cvt_i32_f32_sdwa v45, v45 dst_sel:WORD_1 dst_unused:UNUSED_PAD src0_sel:DWORD
	v_cvt_i32_f32_e32 v84, v84
	v_lshlrev_b32_e32 v85, 8, v85
	v_and_b32_e32 v85, 0xff00, v85
	v_and_b32_e32 v45, 0xff0000, v45
	v_perm_b32 v31, v31, v84, s56
	v_or3_b32 v31, v31, v85, v45
	v_lshl_add_u64 v[84:85], v[134:135], 0, v[24:25]
	v_cvt_pk_f16_f32 v27, v26, v27
	v_cvt_pk_f16_f32 v26, v28, v29
	v_cvt_pk_f16_f32 v29, v82, v83
	v_cvt_pk_f16_f32 v28, v80, v81
	s_nop 1
	v_permlane16_swap_b32_e32 v26, v28
	v_permlane16_swap_b32_e32 v27, v29
	v_lshl_add_u64 v[80:81], v[84:85], 1, s[60:61]
	global_store_dwordx4 v[80:81], v[26:29], off
	v_permlane16_swap_b32_e32 v30, v31
	s_nop 0
	v_lshl_add_u64 v[26:27], s[72:73], 0, v[84:85]
	v_sub_f32_e32 v29, v89, v136
	v_sub_f32_e32 v28, v88, v136
	global_store_dwordx2 v[26:27], v[30:31], off
	v_sub_f32_e32 v27, v91, v136
	v_sub_f32_e32 v26, v90, v136
	v_pk_mul_f32 v[28:29], v[156:157], v[28:29]
	v_pk_mul_f32 v[26:27], v[96:97], v[26:27]
	v_pk_fma_f32 v[28:29], v[28:29], v[0:1], v[4:5]
	v_pk_fma_f32 v[26:27], v[26:27], v[2:3], v[6:7]
	v_cndmask_b32_e64 v29, v29, v232, s[6:7]
	v_cndmask_b32_e64 v28, v28, v232, s[6:7]
	v_cndmask_b32_e64 v27, v27, v232, s[6:7]
	v_cndmask_b32_e64 v26, v26, v232, s[6:7]
	v_pk_mul_f32 v[80:81], v[148:149], v[28:29]
	v_pk_mul_f32 v[30:31], v[98:99], v[26:27]
	v_rndne_f32_e32 v45, v80
	v_rndne_f32_e32 v80, v81
	v_cvt_i32_f32_e32 v80, v80
	v_rndne_f32_e32 v30, v30
	v_rndne_f32_e32 v31, v31
	v_cvt_i32_f32_e32 v45, v45
	v_cvt_i32_f32_sdwa v30, v30 dst_sel:WORD_1 dst_unused:UNUSED_PAD src0_sel:DWORD
	v_cvt_i32_f32_e32 v31, v31
	v_lshlrev_b32_e32 v80, 8, v80
	v_and_b32_e32 v80, 0xff00, v80
	v_and_b32_e32 v30, 0xff0000, v30
	v_perm_b32 v31, v31, v45, s56
	v_or3_b32 v30, v31, v80, v30
	v_sub_f32_e32 v81, v95, v132
	v_sub_f32_e32 v80, v94, v132
	v_sub_f32_e32 v83, v93, v132
	v_sub_f32_e32 v82, v92, v132
	v_pk_mul_f32 v[80:81], v[154:155], v[80:81]
	v_pk_mul_f32 v[82:83], v[104:105], v[82:83]
	v_pk_fma_f32 v[80:81], v[80:81], v[0:1], v[4:5]
	v_pk_fma_f32 v[82:83], v[82:83], v[2:3], v[6:7]
	v_cndmask_b32_e64 v81, v81, v232, s[6:7]
	v_cndmask_b32_e64 v80, v80, v232, s[6:7]
	v_cndmask_b32_e64 v83, v83, v232, s[6:7]
	v_cndmask_b32_e64 v82, v82, v232, s[6:7]
	v_pk_mul_f32 v[84:85], v[108:109], v[80:81]
	v_pk_mul_f32 v[86:87], v[106:107], v[82:83]
	v_rndne_f32_e32 v85, v85
	v_rndne_f32_e32 v31, v87
	v_rndne_f32_e32 v45, v86
	v_cvt_i32_f32_e32 v85, v85
	v_rndne_f32_e32 v84, v84
	v_cvt_i32_f32_e32 v31, v31
	v_cvt_i32_f32_sdwa v45, v45 dst_sel:WORD_1 dst_unused:UNUSED_PAD src0_sel:DWORD
	v_cvt_i32_f32_e32 v84, v84
	v_lshlrev_b32_e32 v85, 8, v85
	v_and_b32_e32 v85, 0xff00, v85
	v_and_b32_e32 v45, 0xff0000, v45
	v_perm_b32 v31, v31, v84, s56
	v_or3_b32 v31, v31, v85, v45
	v_lshl_add_u64 v[84:85], v[116:117], 0, v[24:25]
	v_cvt_pk_f16_f32 v27, v26, v27
	v_cvt_pk_f16_f32 v26, v28, v29
	v_cvt_pk_f16_f32 v29, v82, v83
	v_cvt_pk_f16_f32 v28, v80, v81
	s_nop 1
	v_permlane16_swap_b32_e32 v26, v28
	v_permlane16_swap_b32_e32 v27, v29
	v_lshl_add_u64 v[80:81], v[84:85], 1, s[60:61]
	global_store_dwordx4 v[80:81], v[26:29], off
	v_permlane16_swap_b32_e32 v30, v31
	s_nop 0
	v_lshl_add_u64 v[26:27], s[72:73], 0, v[84:85]
	v_sub_f32_e32 v29, v53, v118
	v_sub_f32_e32 v28, v52, v118
	global_store_dwordx2 v[26:27], v[30:31], off
	v_sub_f32_e32 v27, v55, v118
	v_sub_f32_e32 v26, v54, v118
	v_pk_mul_f32 v[28:29], v[152:153], v[28:29]
	v_pk_mul_f32 v[26:27], v[56:57], v[26:27]
	v_pk_fma_f32 v[28:29], v[28:29], v[0:1], v[4:5]
	v_pk_fma_f32 v[26:27], v[26:27], v[2:3], v[6:7]
	v_cndmask_b32_e64 v29, v29, v232, s[6:7]
	v_cndmask_b32_e64 v28, v28, v232, s[6:7]
	v_cndmask_b32_e64 v27, v27, v232, s[6:7]
	v_cndmask_b32_e64 v26, v26, v232, s[6:7]
	v_pk_mul_f32 v[52:53], v[150:151], v[28:29]
	v_pk_mul_f32 v[30:31], v[58:59], v[26:27]
	v_rndne_f32_e32 v45, v52
	v_rndne_f32_e32 v52, v53
	v_cvt_i32_f32_e32 v52, v52
	v_rndne_f32_e32 v30, v30
	v_rndne_f32_e32 v31, v31
	v_cvt_i32_f32_e32 v45, v45
	v_cvt_i32_f32_sdwa v30, v30 dst_sel:WORD_1 dst_unused:UNUSED_PAD src0_sel:DWORD
	v_cvt_i32_f32_e32 v31, v31
	v_lshlrev_b32_e32 v52, 8, v52
	v_pk_fma_f32 v[36:37], v[36:37], v[0:1], v[4:5]
	v_and_b32_e32 v52, 0xff00, v52
	v_and_b32_e32 v30, 0xff0000, v30
	v_perm_b32 v31, v31, v45, s56
	v_pk_fma_f32 v[38:39], v[38:39], v[2:3], v[6:7]
	v_cndmask_b32_e64 v37, v37, v232, s[6:7]
	v_cndmask_b32_e64 v36, v36, v232, s[6:7]
	v_or3_b32 v30, v31, v52, v30
	v_cndmask_b32_e64 v39, v39, v232, s[6:7]
	v_cndmask_b32_e64 v38, v38, v232, s[6:7]
	v_pk_mul_f32 v[52:53], v[130:131], v[36:37]
	v_pk_mul_f32 v[54:55], v[42:43], v[38:39]
	v_rndne_f32_e32 v53, v53
	v_rndne_f32_e32 v31, v55
	v_rndne_f32_e32 v45, v54
	v_cvt_i32_f32_e32 v53, v53
	v_rndne_f32_e32 v52, v52
	v_cvt_i32_f32_e32 v31, v31
	v_cvt_i32_f32_sdwa v45, v45 dst_sel:WORD_1 dst_unused:UNUSED_PAD src0_sel:DWORD
	v_cvt_i32_f32_e32 v52, v52
	v_lshlrev_b32_e32 v53, 8, v53
	v_and_b32_e32 v53, 0xff00, v53
	v_and_b32_e32 v45, 0xff0000, v45
	v_perm_b32 v31, v31, v52, s56
	v_or3_b32 v31, v31, v53, v45
	v_lshl_add_u64 v[52:53], v[62:63], 0, v[24:25]
	v_cvt_pk_f16_f32 v27, v26, v27
	v_cvt_pk_f16_f32 v26, v28, v29
	v_cvt_pk_f16_f32 v29, v38, v39
	v_cvt_pk_f16_f32 v28, v36, v37
	v_pk_fma_f32 v[20:21], v[20:21], v[0:1], v[4:5]
	v_pk_fma_f32 v[0:1], v[14:15], v[0:1], v[4:5]
	v_permlane16_swap_b32_e32 v26, v28
	v_permlane16_swap_b32_e32 v27, v29
	v_lshl_add_u64 v[36:37], v[52:53], 1, s[60:61]
	v_pk_fma_f32 v[22:23], v[22:23], v[2:3], v[6:7]
	v_cndmask_b32_e64 v21, v21, v232, s[6:7]
	v_cndmask_b32_e64 v20, v20, v232, s[6:7]
	v_pk_fma_f32 v[2:3], v[12:13], v[2:3], v[6:7]
	v_cndmask_b32_e64 v5, v1, v232, s[6:7]
	v_cndmask_b32_e64 v4, v0, v232, s[6:7]
	global_store_dwordx4 v[36:37], v[26:29], off
	v_permlane16_swap_b32_e32 v30, v31
	s_nop 0
	v_lshl_add_u64 v[26:27], s[72:73], 0, v[52:53]
	v_cndmask_b32_e64 v23, v23, v232, s[6:7]
	v_cndmask_b32_e64 v22, v22, v232, s[6:7]
	v_pk_mul_f32 v[28:29], v[44:45], v[20:21] op_sel_hi:[0,1]
	v_cndmask_b32_e64 v3, v3, v232, s[6:7]
	v_cndmask_b32_e64 v2, v2, v232, s[6:7]
	v_pk_mul_f32 v[0:1], v[144:145], v[4:5] op_sel_hi:[0,1]
	global_store_dwordx2 v[26:27], v[30:31], off
	v_pk_mul_f32 v[26:27], v[44:45], v[22:23] op_sel_hi:[0,1]
	v_rndne_f32_e32 v29, v29
	v_pk_mul_f32 v[6:7], v[144:145], v[2:3] op_sel_hi:[0,1]
	v_rndne_f32_e32 v1, v1
	v_rndne_f32_e32 v28, v28
	v_cvt_i32_f32_e32 v29, v29
	v_rndne_f32_e32 v26, v26
	v_rndne_f32_e32 v27, v27
	v_rndne_f32_e32 v7, v7
	v_rndne_f32_e32 v6, v6
	v_cvt_i32_f32_e32 v1, v1
	v_rndne_f32_e32 v0, v0
	v_cvt_i32_f32_e32 v28, v28
	v_cvt_i32_f32_sdwa v26, v26 dst_sel:WORD_1 dst_unused:UNUSED_PAD src0_sel:DWORD
	v_cvt_i32_f32_e32 v27, v27
	v_cvt_i32_f32_e32 v7, v7
	v_cvt_i32_f32_sdwa v6, v6 dst_sel:WORD_1 dst_unused:UNUSED_PAD src0_sel:DWORD
	v_cvt_i32_f32_e32 v0, v0
	v_lshlrev_b32_e32 v29, 8, v29
	v_lshlrev_b32_e32 v1, 8, v1
	v_and_b32_e32 v29, 0xff00, v29
	v_and_b32_e32 v26, 0xff0000, v26
	v_perm_b32 v27, v27, v28, s56
	v_and_b32_e32 v6, 0xff0000, v6
	v_and_b32_e32 v1, 0xff00, v1
	v_perm_b32 v0, v7, v0, s56
	v_or3_b32 v26, v27, v29, v26
	v_or3_b32 v27, v0, v1, v6
	v_lshl_add_u64 v[6:7], v[46:47], 0, v[24:25]
	v_cvt_pk_f16_f32 v1, v22, v23
	v_cvt_pk_f16_f32 v0, v20, v21
	v_cvt_pk_f16_f32 v3, v2, v3
	v_cvt_pk_f16_f32 v2, v4, v5
	s_nop 1
	v_permlane16_swap_b32_e32 v0, v2
	v_permlane16_swap_b32_e32 v1, v3
	v_lshl_add_u64 v[4:5], v[6:7], 1, s[60:61]
	global_store_dwordx4 v[4:5], v[0:3], off
	v_permlane16_swap_b32_e32 v26, v27
	s_nop 0
	v_lshl_add_u64 v[0:1], s[72:73], 0, v[6:7]
	global_store_dwordx2 v[0:1], v[26:27], off
	v_mov_b32_e32 v0, v196
	v_mov_b32_e32 v1, v197
	v_mov_b32_e32 v2, v198
	v_mov_b32_e32 v3, v199
	v_mov_b32_e32 v4, v200
	v_mov_b32_e32 v5, v201
	v_mov_b32_e32 v6, v202
	v_mov_b32_e32 v7, v203
	v_sub_f32_e32 v21, v69, v114
	v_sub_f32_e32 v20, v68, v114
	v_sub_f32_e32 v15, v71, v114
	v_sub_f32_e32 v14, v70, v114
	v_pk_mul_f32 v[20:21], v[160:161], v[20:21]
	v_pk_mul_f32 v[14:15], v[124:125], v[14:15]
	v_sub_f32_e32 v27, v73, v100
	v_sub_f32_e32 v26, v72, v100
	v_pk_mul_f32 v[26:27], v[120:121], v[26:27]
	v_lshl_add_u64 v[12:13], v[138:139], 0, s[4:5]
	v_pk_fma_f32 v[20:21], v[20:21], v[0:1], v[4:5]
	v_pk_fma_f32 v[14:15], v[14:15], v[2:3], v[6:7]
	v_cndmask_b32_e64 v23, v21, v232, s[6:7]
	v_cndmask_b32_e64 v22, v20, v232, s[6:7]
	v_cndmask_b32_e64 v15, v15, v232, s[6:7]
	v_cndmask_b32_e64 v14, v14, v232, s[6:7]
	v_pk_mul_f32 v[24:25], v[142:143], v[22:23]
	v_pk_mul_f32 v[20:21], v[126:127], v[14:15]
	v_rndne_f32_e32 v25, v25
	v_rndne_f32_e32 v24, v24
	v_cvt_i32_f32_e32 v25, v25
	v_rndne_f32_e32 v20, v20
	v_rndne_f32_e32 v21, v21
	v_cvt_i32_f32_e32 v24, v24
	v_cvt_i32_f32_sdwa v20, v20 dst_sel:WORD_1 dst_unused:UNUSED_PAD src0_sel:DWORD
	v_cvt_i32_f32_e32 v21, v21
	v_lshlrev_b32_e32 v25, 8, v25
	v_and_b32_e32 v25, 0xff00, v25
	v_and_b32_e32 v20, 0xff0000, v20
	v_perm_b32 v21, v21, v24, s56
	v_or3_b32 v24, v21, v25, v20
	v_sub_f32_e32 v21, v75, v100
	v_sub_f32_e32 v20, v74, v100
	v_pk_mul_f32 v[20:21], v[158:159], v[20:21]
	v_pk_fma_f32 v[26:27], v[26:27], v[2:3], v[6:7]
	v_pk_fma_f32 v[20:21], v[20:21], v[0:1], v[4:5]
	v_cndmask_b32_e64 v27, v27, v232, s[6:7]
	v_cndmask_b32_e64 v29, v21, v232, s[6:7]
	v_cndmask_b32_e64 v28, v20, v232, s[6:7]
	v_cndmask_b32_e64 v26, v26, v232, s[6:7]
	v_pk_mul_f32 v[20:21], v[128:129], v[28:29]
	v_pk_mul_f32 v[30:31], v[122:123], v[26:27]
	v_rndne_f32_e32 v21, v21
	v_rndne_f32_e32 v25, v31
	v_rndne_f32_e32 v30, v30
	v_cvt_i32_f32_e32 v21, v21
	v_rndne_f32_e32 v20, v20
	v_cvt_i32_f32_e32 v25, v25
	v_cvt_i32_f32_sdwa v30, v30 dst_sel:WORD_1 dst_unused:UNUSED_PAD src0_sel:DWORD
	v_cvt_i32_f32_e32 v20, v20
	v_lshlrev_b32_e32 v21, 8, v21
	v_and_b32_e32 v21, 0xff00, v21
	v_and_b32_e32 v30, 0xff0000, v30
	v_perm_b32 v20, v25, v20, s56
	v_or3_b32 v25, v20, v21, v30
	v_lshl_add_u64 v[30:31], v[134:135], 0, v[12:13]
	v_cvt_pk_f16_f32 v21, v14, v15
	v_cvt_pk_f16_f32 v20, v22, v23
	v_cvt_pk_f16_f32 v23, v26, v27
	v_cvt_pk_f16_f32 v22, v28, v29
	s_nop 1
	v_permlane16_swap_b32_e32 v20, v22
	v_permlane16_swap_b32_e32 v21, v23
	v_lshl_add_u64 v[14:15], v[30:31], 1, s[60:61]
	global_store_dwordx4 v[14:15], v[20:23], off
	v_permlane16_swap_b32_e32 v24, v25
	v_lshl_add_u64 v[14:15], s[72:73], 0, v[30:31]
	v_sub_f32_e32 v21, v77, v136
	v_sub_f32_e32 v20, v76, v136
	global_store_dwordx2 v[14:15], v[24:25], off
	v_sub_f32_e32 v15, v79, v136
	v_sub_f32_e32 v14, v78, v136
	v_pk_mul_f32 v[20:21], v[156:157], v[20:21]
	v_pk_mul_f32 v[14:15], v[96:97], v[14:15]
	v_pk_fma_f32 v[20:21], v[20:21], v[0:1], v[4:5]
	v_pk_fma_f32 v[14:15], v[14:15], v[2:3], v[6:7]
	v_cndmask_b32_e64 v23, v21, v232, s[6:7]
	v_cndmask_b32_e64 v22, v20, v232, s[6:7]
	v_cndmask_b32_e64 v15, v15, v232, s[6:7]
	v_cndmask_b32_e64 v14, v14, v232, s[6:7]
	v_pk_mul_f32 v[24:25], v[148:149], v[22:23]
	v_pk_mul_f32 v[20:21], v[98:99], v[14:15]
	v_rndne_f32_e32 v25, v25
	v_rndne_f32_e32 v24, v24
	v_cvt_i32_f32_e32 v25, v25
	v_rndne_f32_e32 v20, v20
	v_rndne_f32_e32 v21, v21
	v_cvt_i32_f32_e32 v24, v24
	v_cvt_i32_f32_sdwa v20, v20 dst_sel:WORD_1 dst_unused:UNUSED_PAD src0_sel:DWORD
	v_cvt_i32_f32_e32 v21, v21
	v_lshlrev_b32_e32 v25, 8, v25
	v_and_b32_e32 v25, 0xff00, v25
	v_and_b32_e32 v20, 0xff0000, v20
	v_perm_b32 v21, v21, v24, s56
	v_or3_b32 v24, v21, v25, v20
	v_sub_f32_e32 v21, v65, v132
	v_sub_f32_e32 v20, v64, v132
	v_sub_f32_e32 v27, v67, v132
	v_sub_f32_e32 v26, v66, v132
	v_pk_mul_f32 v[20:21], v[154:155], v[20:21]
	v_pk_mul_f32 v[26:27], v[104:105], v[26:27]
	v_pk_fma_f32 v[20:21], v[20:21], v[0:1], v[4:5]
	v_pk_fma_f32 v[26:27], v[26:27], v[2:3], v[6:7]
	v_cndmask_b32_e64 v29, v21, v232, s[6:7]
	v_cndmask_b32_e64 v28, v20, v232, s[6:7]
	v_cndmask_b32_e64 v27, v27, v232, s[6:7]
	v_cndmask_b32_e64 v26, v26, v232, s[6:7]
	v_pk_mul_f32 v[20:21], v[108:109], v[28:29]
	v_pk_mul_f32 v[30:31], v[106:107], v[26:27]
	v_rndne_f32_e32 v21, v21
	v_rndne_f32_e32 v25, v31
	v_rndne_f32_e32 v30, v30
	v_cvt_i32_f32_e32 v21, v21
	v_rndne_f32_e32 v20, v20
	v_cvt_i32_f32_e32 v25, v25
	v_cvt_i32_f32_sdwa v30, v30 dst_sel:WORD_1 dst_unused:UNUSED_PAD src0_sel:DWORD
	v_cvt_i32_f32_e32 v20, v20
	v_lshlrev_b32_e32 v21, 8, v21
	v_and_b32_e32 v21, 0xff00, v21
	v_and_b32_e32 v30, 0xff0000, v30
	v_perm_b32 v20, v25, v20, s56
	v_or3_b32 v25, v20, v21, v30
	v_lshl_add_u64 v[30:31], v[116:117], 0, v[12:13]
	v_cvt_pk_f16_f32 v21, v14, v15
	v_cvt_pk_f16_f32 v20, v22, v23
	v_cvt_pk_f16_f32 v23, v26, v27
	v_cvt_pk_f16_f32 v22, v28, v29
	s_nop 1
	v_permlane16_swap_b32_e32 v20, v22
	v_permlane16_swap_b32_e32 v21, v23
	v_lshl_add_u64 v[14:15], v[30:31], 1, s[60:61]
	global_store_dwordx4 v[14:15], v[20:23], off
	v_permlane16_swap_b32_e32 v24, v25
	v_lshl_add_u64 v[14:15], s[72:73], 0, v[30:31]
	v_sub_f32_e32 v21, v49, v118
	v_sub_f32_e32 v20, v48, v118
	global_store_dwordx2 v[14:15], v[24:25], off
	v_sub_f32_e32 v15, v51, v118
	v_sub_f32_e32 v14, v50, v118
	v_pk_mul_f32 v[20:21], v[152:153], v[20:21]
	v_pk_mul_f32 v[14:15], v[56:57], v[14:15]
	v_pk_fma_f32 v[20:21], v[20:21], v[0:1], v[4:5]
	v_pk_fma_f32 v[14:15], v[14:15], v[2:3], v[6:7]
	v_cndmask_b32_e64 v23, v21, v232, s[6:7]
	v_cndmask_b32_e64 v22, v20, v232, s[6:7]
	v_cndmask_b32_e64 v15, v15, v232, s[6:7]
	v_cndmask_b32_e64 v14, v14, v232, s[6:7]
	v_pk_mul_f32 v[24:25], v[150:151], v[22:23]
	v_pk_mul_f32 v[20:21], v[58:59], v[14:15]
	v_rndne_f32_e32 v25, v25
	v_rndne_f32_e32 v24, v24
	v_cvt_i32_f32_e32 v25, v25
	v_rndne_f32_e32 v20, v20
	v_rndne_f32_e32 v21, v21
	v_cvt_i32_f32_e32 v24, v24
	v_cvt_i32_f32_sdwa v20, v20 dst_sel:WORD_1 dst_unused:UNUSED_PAD src0_sel:DWORD
	v_cvt_i32_f32_e32 v21, v21
	v_lshlrev_b32_e32 v25, 8, v25
	v_and_b32_e32 v25, 0xff00, v25
	v_and_b32_e32 v20, 0xff0000, v20
	v_perm_b32 v21, v21, v24, s56
	v_or3_b32 v24, v21, v25, v20
	v_sub_f32_e32 v21, v33, v110
	v_sub_f32_e32 v20, v32, v110
	v_sub_f32_e32 v27, v35, v110
	v_sub_f32_e32 v26, v34, v110
	v_pk_mul_f32 v[20:21], v[146:147], v[20:21]
	v_pk_mul_f32 v[26:27], v[40:41], v[26:27]
	v_pk_fma_f32 v[20:21], v[20:21], v[0:1], v[4:5]
	v_pk_fma_f32 v[26:27], v[26:27], v[2:3], v[6:7]
	v_cndmask_b32_e64 v29, v21, v232, s[6:7]
	v_cndmask_b32_e64 v28, v20, v232, s[6:7]
	v_cndmask_b32_e64 v27, v27, v232, s[6:7]
	v_cndmask_b32_e64 v26, v26, v232, s[6:7]
	v_pk_mul_f32 v[20:21], v[130:131], v[28:29]
	v_pk_mul_f32 v[30:31], v[42:43], v[26:27]
	v_rndne_f32_e32 v21, v21
	v_rndne_f32_e32 v25, v31
	v_rndne_f32_e32 v30, v30
	v_cvt_i32_f32_e32 v21, v21
	v_rndne_f32_e32 v20, v20
	v_cvt_i32_f32_e32 v25, v25
	v_cvt_i32_f32_sdwa v30, v30 dst_sel:WORD_1 dst_unused:UNUSED_PAD src0_sel:DWORD
	v_cvt_i32_f32_e32 v20, v20
	v_lshlrev_b32_e32 v21, 8, v21
	v_and_b32_e32 v21, 0xff00, v21
	v_and_b32_e32 v30, 0xff0000, v30
	v_perm_b32 v20, v25, v20, s56
	v_or3_b32 v25, v20, v21, v30
	v_lshl_add_u64 v[30:31], v[62:63], 0, v[12:13]
	v_cvt_pk_f16_f32 v21, v14, v15
	v_cvt_pk_f16_f32 v20, v22, v23
	v_cvt_pk_f16_f32 v23, v26, v27
	v_cvt_pk_f16_f32 v22, v28, v29
	s_nop 1
	v_permlane16_swap_b32_e32 v20, v22
	v_permlane16_swap_b32_e32 v21, v23
	v_lshl_add_u64 v[14:15], v[30:31], 1, s[60:61]
	v_pk_fma_f32 v[10:11], v[10:11], v[0:1], v[4:5]
	v_pk_fma_f32 v[0:1], v[16:17], v[0:1], v[4:5]
	global_store_dwordx4 v[14:15], v[20:23], off
	v_permlane16_swap_b32_e32 v24, v25
	v_lshl_add_u64 v[14:15], s[72:73], 0, v[30:31]
	v_pk_fma_f32 v[8:9], v[8:9], v[2:3], v[6:7]
	v_cndmask_b32_e64 v11, v11, v232, s[6:7]
	v_cndmask_b32_e64 v10, v10, v232, s[6:7]
	v_pk_fma_f32 v[2:3], v[18:19], v[2:3], v[6:7]
	v_cndmask_b32_e64 v5, v1, v232, s[6:7]
	v_cndmask_b32_e64 v4, v0, v232, s[6:7]
	global_store_dwordx2 v[14:15], v[24:25], off
	v_cndmask_b32_e64 v9, v9, v232, s[6:7]
	v_cndmask_b32_e64 v8, v8, v232, s[6:7]
	v_pk_mul_f32 v[14:15], v[144:145], v[10:11] op_sel_hi:[0,1]
	v_cndmask_b32_e64 v3, v3, v232, s[6:7]
	v_cndmask_b32_e64 v2, v2, v232, s[6:7]
	v_pk_mul_f32 v[0:1], v[44:45], v[4:5] op_sel_hi:[0,1]
	v_pk_mul_f32 v[20:21], v[144:145], v[8:9] op_sel_hi:[0,1]
	v_rndne_f32_e32 v15, v15
	v_pk_mul_f32 v[6:7], v[44:45], v[2:3] op_sel_hi:[0,1]
	v_rndne_f32_e32 v1, v1
	v_rndne_f32_e32 v21, v21
	v_rndne_f32_e32 v20, v20
	v_cvt_i32_f32_e32 v15, v15
	v_rndne_f32_e32 v14, v14
	v_rndne_f32_e32 v7, v7
	v_rndne_f32_e32 v6, v6
	v_cvt_i32_f32_e32 v1, v1
	v_rndne_f32_e32 v0, v0
	v_cvt_i32_f32_e32 v21, v21
	v_cvt_i32_f32_sdwa v20, v20 dst_sel:WORD_1 dst_unused:UNUSED_PAD src0_sel:DWORD
	v_cvt_i32_f32_e32 v14, v14
	v_cvt_i32_f32_e32 v7, v7
	v_cvt_i32_f32_sdwa v6, v6 dst_sel:WORD_1 dst_unused:UNUSED_PAD src0_sel:DWORD
	v_cvt_i32_f32_e32 v0, v0
	v_lshlrev_b32_e32 v15, 8, v15
	v_lshlrev_b32_e32 v1, 8, v1
	v_and_b32_e32 v20, 0xff0000, v20
	v_and_b32_e32 v15, 0xff00, v15
	v_perm_b32 v14, v21, v14, s56
	v_and_b32_e32 v6, 0xff0000, v6
	v_and_b32_e32 v1, 0xff00, v1
	v_perm_b32 v0, v7, v0, s56
	v_or3_b32 v15, v14, v15, v20
	v_or3_b32 v14, v0, v1, v6
	v_lshl_add_u64 v[6:7], v[46:47], 0, v[12:13]
	v_cvt_pk_f16_f32 v1, v2, v3
	v_cvt_pk_f16_f32 v0, v4, v5
	v_cvt_pk_f16_f32 v3, v8, v9
	v_cvt_pk_f16_f32 v2, v10, v11
	s_nop 1
	v_permlane16_swap_b32_e32 v0, v2
	v_permlane16_swap_b32_e32 v1, v3
	v_lshl_add_u64 v[4:5], v[6:7], 1, s[60:61]
	global_store_dwordx4 v[4:5], v[0:3], off
	v_permlane16_swap_b32_e32 v14, v15
	s_nop 0
	v_lshl_add_u64 v[0:1], s[72:73], 0, v[6:7]
	global_store_dwordx2 v[0:1], v[14:15], off

.LBB0_625:
	v_readlane_b32 s3, v254, 19
	s_nop 1
	v_add_u32_e32 v6, s3, v5
	v_ashrrev_i32_e32 v7, 31, v6
	v_lshlrev_b64 v[6:7], 2, v[6:7]
	v_lshl_add_u64 v[8:9], s[28:29], 0, v[6:7]
	global_load_dword v12, v[8:9], off
	v_readlane_b32 s3, v255, 5
	v_lshl_add_u64 v[8:9], s[26:27], 0, v[6:7]
	global_load_dword v13, v[8:9], off
	v_lshl_add_u64 v[8:9], s[10:11], 0, v[6:7]
	v_add_co_u32_e32 v10, vcc, 0x5000, v8
	global_load_dword v14, v[8:9], off
	s_nop 0
	v_addc_co_u32_e32 v11, vcc, 0, v9, vcc
	global_load_dword v10, v[10:11], off offset:2048
	v_add_co_u32_e32 v8, vcc, 0xb000, v8
	v_lshl_add_u64 v[6:7], s[8:9], 0, v[6:7]
	s_nop 0
	v_addc_co_u32_e32 v9, vcc, 0, v9, vcc
	global_load_dword v8, v[8:9], off
	v_lshlrev_b32_e32 v11, 2, v2
	global_load_dword v6, v[6:7], off
	v_add3_u32 v11, s3, v3, v11
	s_waitcnt vmcnt(5)
	v_max_f32_e32 v12, v12, v12
	v_max_f32_e32 v12, 0xda24260, v12
	v_mul_f32_e32 v12, 0x3c010204, v12
	s_waitcnt vmcnt(3)
	v_mul_f32_e32 v9, v12, v14
	v_mul_f32_e32 v9, v0, v9
	s_waitcnt vmcnt(2)
	v_mul_f32_e32 v15, v12, v10
	v_add_f32_e32 v7, v14, v10
	v_mul_f32_e32 v15, v0, v15
	ds_write2st64_b32 v11, v9, v15 offset1:2
	s_waitcnt vmcnt(1)
	v_add_f32_e32 v7, v7, v8
	v_mul_f32_e32 v9, v12, v8
	s_waitcnt vmcnt(0)
	v_fmac_f32_e32 v6, v13, v7
	v_mul_f32_e32 v9, v0, v9
	v_mul_f32_e32 v6, v0, v6
	ds_write2st64_b32 v11, v9, v6 offset0:4 offset1:6

.LBB0_629:
	s_andn2_saveexec_b64 s[6:7], s[6:7]
	s_cbranch_execz .LBB0_631
	v_readlane_b32 s3, v254, 23
	v_lshlrev_b32_e32 v2, 2, v2
	s_nop 0
	v_add_u32_e32 v4, s3, v5
	v_ashrrev_i32_e32 v5, 31, v4
	v_lshlrev_b64 v[4:5], 2, v[4:5]
	v_lshl_add_u64 v[6:7], s[28:29], 0, v[4:5]
	global_load_dword v1, v[6:7], off
	v_lshl_add_u64 v[6:7], s[26:27], 0, v[4:5]
	global_load_dword v10, v[6:7], off
	v_lshl_add_u64 v[6:7], s[10:11], 0, v[4:5]
	v_add_co_u32_e32 v8, vcc, 0x5000, v6
	global_load_dword v11, v[6:7], off
	s_nop 0
	v_addc_co_u32_e32 v9, vcc, 0, v7, vcc
	global_load_dword v8, v[8:9], off offset:2048
	v_add_co_u32_e32 v6, vcc, 0xb000, v6
	v_readlane_b32 s3, v255, 6
	s_nop 0
	v_addc_co_u32_e32 v7, vcc, 0, v7, vcc
	global_load_dword v6, v[6:7], off
	v_add3_u32 v9, s3, v3, v2
	v_lshl_add_u64 v[12:13], s[8:9], 0, v[4:5]
	global_load_dword v12, v[12:13], off
	s_waitcnt vmcnt(1)
	v_max_f32_e32 v1, v1, v1
	v_max_f32_e32 v1, 0xda24260, v1
	v_mul_f32_e32 v1, 0x3c010204, v1
	v_mul_f32_e32 v7, v1, v11
	v_mul_f32_e32 v7, v0, v7
	v_mul_f32_e32 v2, v1, v8
	v_mul_f32_e32 v2, v0, v2
	ds_write2st64_b32 v9, v7, v2 offset1:2
	v_add_f32_e32 v3, v11, v8
	v_add_f32_e32 v3, v3, v6
	v_mul_f32_e32 v1, v1, v6
	v_mul_f32_e32 v1, v0, v1
	s_waitcnt vmcnt(0)
	v_fmac_f32_e32 v12, v10, v3
	v_mul_f32_e32 v0, v0, v12
	ds_write2st64_b32 v9, v1, v0 offset0:4 offset1:6

.LBB0_734:
	v_readlane_b32 s3, v253, 55
	s_nop 1
	v_add_u32_e32 v6, s3, v5
	v_ashrrev_i32_e32 v7, 31, v6
	v_lshlrev_b64 v[6:7], 2, v[6:7]
	v_lshl_add_u64 v[8:9], s[28:29], 0, v[6:7]
	global_load_dword v12, v[8:9], off
	s_add_i32 s3, 0, 0x20340
	v_lshl_add_u64 v[8:9], s[26:27], 0, v[6:7]
	global_load_dword v13, v[8:9], off
	v_lshl_add_u64 v[8:9], s[10:11], 0, v[6:7]
	v_add_co_u32_e32 v10, vcc, 0x5000, v8
	global_load_dword v14, v[8:9], off
	s_nop 0
	v_addc_co_u32_e32 v11, vcc, 0, v9, vcc
	global_load_dword v10, v[10:11], off offset:2048
	v_add_co_u32_e32 v8, vcc, 0xb000, v8
	v_lshl_add_u64 v[6:7], s[8:9], 0, v[6:7]
	s_nop 0
	v_addc_co_u32_e32 v9, vcc, 0, v9, vcc
	global_load_dword v8, v[8:9], off
	v_lshlrev_b32_e32 v11, 2, v2
	global_load_dword v6, v[6:7], off
	v_add3_u32 v11, s3, v3, v11
	s_waitcnt vmcnt(5)
	v_max_f32_e32 v12, v12, v12
	v_max_f32_e32 v12, 0xda24260, v12
	v_mul_f32_e32 v12, 0x3c010204, v12
	s_waitcnt vmcnt(3)
	v_mul_f32_e32 v9, v12, v14
	v_mul_f32_e32 v9, v0, v9
	s_waitcnt vmcnt(2)
	v_mul_f32_e32 v15, v12, v10
	v_add_f32_e32 v7, v14, v10
	v_mul_f32_e32 v15, v0, v15
	ds_write2st64_b32 v11, v9, v15 offset1:2
	s_waitcnt vmcnt(1)
	v_add_f32_e32 v7, v7, v8
	v_mul_f32_e32 v9, v12, v8
	s_waitcnt vmcnt(0)
	v_fmac_f32_e32 v6, v13, v7
	v_mul_f32_e32 v9, v0, v9
	v_mul_f32_e32 v6, v0, v6
	ds_write2st64_b32 v11, v9, v6 offset0:4 offset1:6
	s_or_b64 exec, exec, s[12:13]
	s_and_saveexec_b64 s[4:5], s[6:7]
	s_xor_b64 s[12:13], exec, s[4:5]
	s_cbranch_execz .LBB0_618

.LBB0_736:
	v_readlane_b32 s3, v253, 56
	s_nop 1
	v_add_u32_e32 v6, s3, v5
	v_ashrrev_i32_e32 v7, 31, v6
	v_lshlrev_b64 v[6:7], 2, v[6:7]
	v_lshl_add_u64 v[8:9], s[28:29], 0, v[6:7]
	global_load_dword v12, v[8:9], off
	v_readlane_b32 s3, v255, 2
	v_lshl_add_u64 v[8:9], s[26:27], 0, v[6:7]
	global_load_dword v13, v[8:9], off
	v_lshl_add_u64 v[8:9], s[10:11], 0, v[6:7]
	v_add_co_u32_e32 v10, vcc, 0x5000, v8
	global_load_dword v14, v[8:9], off
	s_nop 0
	v_addc_co_u32_e32 v11, vcc, 0, v9, vcc
	global_load_dword v10, v[10:11], off offset:2048
	v_add_co_u32_e32 v8, vcc, 0xb000, v8
	v_lshl_add_u64 v[6:7], s[8:9], 0, v[6:7]
	s_nop 0
	v_addc_co_u32_e32 v9, vcc, 0, v9, vcc
	global_load_dword v8, v[8:9], off
	v_lshlrev_b32_e32 v11, 2, v2
	global_load_dword v6, v[6:7], off
	v_add3_u32 v11, s3, v3, v11
	s_waitcnt vmcnt(5)
	v_max_f32_e32 v12, v12, v12
	v_max_f32_e32 v12, 0xda24260, v12
	v_mul_f32_e32 v12, 0x3c010204, v12
	s_waitcnt vmcnt(3)
	v_mul_f32_e32 v9, v12, v14
	v_mul_f32_e32 v9, v0, v9
	s_waitcnt vmcnt(2)
	v_mul_f32_e32 v15, v12, v10
	v_add_f32_e32 v7, v14, v10
	v_mul_f32_e32 v15, v0, v15
	ds_write2st64_b32 v11, v9, v15 offset1:2
	s_waitcnt vmcnt(1)
	v_add_f32_e32 v7, v7, v8
	v_mul_f32_e32 v9, v12, v8
	s_waitcnt vmcnt(0)
	v_fmac_f32_e32 v6, v13, v7
	v_mul_f32_e32 v9, v0, v9
	v_mul_f32_e32 v6, v0, v6
	ds_write2st64_b32 v11, v9, v6 offset0:4 offset1:6
	s_or_b64 exec, exec, s[12:13]
	s_and_saveexec_b64 s[4:5], s[6:7]
	s_xor_b64 s[12:13], exec, s[4:5]
	s_cbranch_execz .LBB0_620

.LBB0_738:
	v_readlane_b32 s3, v253, 57
	s_nop 1
	v_add_u32_e32 v6, s3, v5
	v_ashrrev_i32_e32 v7, 31, v6
	v_lshlrev_b64 v[6:7], 2, v[6:7]
	v_lshl_add_u64 v[8:9], s[28:29], 0, v[6:7]
	global_load_dword v12, v[8:9], off
	v_readlane_b32 s3, v255, 3
	v_lshl_add_u64 v[8:9], s[26:27], 0, v[6:7]
	global_load_dword v13, v[8:9], off
	v_lshl_add_u64 v[8:9], s[10:11], 0, v[6:7]
	v_add_co_u32_e32 v10, vcc, 0x5000, v8
	global_load_dword v14, v[8:9], off
	s_nop 0
	v_addc_co_u32_e32 v11, vcc, 0, v9, vcc
	global_load_dword v10, v[10:11], off offset:2048
	v_add_co_u32_e32 v8, vcc, 0xb000, v8
	v_lshl_add_u64 v[6:7], s[8:9], 0, v[6:7]
	s_nop 0
	v_addc_co_u32_e32 v9, vcc, 0, v9, vcc
	global_load_dword v8, v[8:9], off
	v_lshlrev_b32_e32 v11, 2, v2
	global_load_dword v6, v[6:7], off
	v_add3_u32 v11, s3, v3, v11
	s_waitcnt vmcnt(5)
	v_max_f32_e32 v12, v12, v12
	v_max_f32_e32 v12, 0xda24260, v12
	v_mul_f32_e32 v12, 0x3c010204, v12
	s_waitcnt vmcnt(3)
	v_mul_f32_e32 v9, v12, v14
	v_mul_f32_e32 v9, v0, v9
	s_waitcnt vmcnt(2)
	v_mul_f32_e32 v15, v12, v10
	v_add_f32_e32 v7, v14, v10
	v_mul_f32_e32 v15, v0, v15
	ds_write2st64_b32 v11, v9, v15 offset1:2
	s_waitcnt vmcnt(1)
	v_add_f32_e32 v7, v7, v8
	v_mul_f32_e32 v9, v12, v8
	s_waitcnt vmcnt(0)
	v_fmac_f32_e32 v6, v13, v7
	v_mul_f32_e32 v9, v0, v9
	v_mul_f32_e32 v6, v0, v6
	ds_write2st64_b32 v11, v9, v6 offset0:4 offset1:6
	s_or_b64 exec, exec, s[12:13]
	s_and_saveexec_b64 s[4:5], s[6:7]
	s_xor_b64 s[12:13], exec, s[4:5]
	s_cbranch_execz .LBB0_622

.LBB0_740:
	v_readlane_b32 s3, v253, 58
	s_nop 1
	v_add_u32_e32 v6, s3, v5
	v_ashrrev_i32_e32 v7, 31, v6
	v_lshlrev_b64 v[6:7], 2, v[6:7]
	v_lshl_add_u64 v[8:9], s[28:29], 0, v[6:7]
	global_load_dword v12, v[8:9], off
	v_readlane_b32 s3, v255, 4
	v_lshl_add_u64 v[8:9], s[26:27], 0, v[6:7]
	global_load_dword v13, v[8:9], off
	v_lshl_add_u64 v[8:9], s[10:11], 0, v[6:7]
	v_add_co_u32_e32 v10, vcc, 0x5000, v8
	global_load_dword v14, v[8:9], off
	s_nop 0
	v_addc_co_u32_e32 v11, vcc, 0, v9, vcc
	global_load_dword v10, v[10:11], off offset:2048
	v_add_co_u32_e32 v8, vcc, 0xb000, v8
	v_lshl_add_u64 v[6:7], s[8:9], 0, v[6:7]
	s_nop 0
	v_addc_co_u32_e32 v9, vcc, 0, v9, vcc
	global_load_dword v8, v[8:9], off
	v_lshlrev_b32_e32 v11, 2, v2
	global_load_dword v6, v[6:7], off
	v_add3_u32 v11, s3, v3, v11
	s_waitcnt vmcnt(5)
	v_max_f32_e32 v12, v12, v12
	v_max_f32_e32 v12, 0xda24260, v12
	v_mul_f32_e32 v12, 0x3c010204, v12
	s_waitcnt vmcnt(3)
	v_mul_f32_e32 v9, v12, v14
	v_mul_f32_e32 v9, v0, v9
	s_waitcnt vmcnt(2)
	v_mul_f32_e32 v15, v12, v10
	v_add_f32_e32 v7, v14, v10
	v_mul_f32_e32 v15, v0, v15
	ds_write2st64_b32 v11, v9, v15 offset1:2
	s_waitcnt vmcnt(1)
	v_add_f32_e32 v7, v7, v8
	v_mul_f32_e32 v9, v12, v8
	s_waitcnt vmcnt(0)
	v_fmac_f32_e32 v6, v13, v7
	v_mul_f32_e32 v9, v0, v9
	v_mul_f32_e32 v6, v0, v6
	ds_write2st64_b32 v11, v9, v6 offset0:4 offset1:6
	s_or_b64 exec, exec, s[12:13]
	s_and_saveexec_b64 s[4:5], s[6:7]
	s_xor_b64 s[12:13], exec, s[4:5]
	s_cbranch_execz .LBB0_624

.LBB0_851:
	v_lshl_add_u64 v[20:21], v[160:161], 2, s[18:19]
	global_load_dwordx4 v[196:199], v[20:21], off
	global_load_dwordx4 v[200:203], v[20:21], off offset:64
	global_load_dwordx4 v[204:207], v[20:21], off offset:512
	global_load_dwordx4 v[208:211], v[20:21], off offset:576
	s_mov_b32 s8, 0x3a800000
	s_lshl_b32 s10, s26, 5
	v_readlane_b32 s3, v254, 17
	s_add_i32 s3, s3, s10
	v_cmp_gt_u32_e32 vcc, 16, v178
	s_waitcnt vmcnt(0)
	v_pk_mul_f32 v[174:175], v[198:199], s[8:9] op_sel_hi:[1,0]
	v_pk_mul_f32 v[176:177], v[196:197], s[8:9] op_sel_hi:[1,0]
	v_pk_mul_f32 v[170:171], v[202:203], s[8:9] op_sel_hi:[1,0]
	v_pk_mul_f32 v[172:173], v[200:201], s[8:9] op_sel_hi:[1,0]
	v_pk_mul_f32 v[166:167], v[206:207], s[8:9] op_sel_hi:[1,0]
	v_pk_mul_f32 v[168:169], v[204:205], s[8:9] op_sel_hi:[1,0]
	v_mbcnt_lo_u32_b32 v185, -1, 0
	v_mbcnt_hi_u32_b32 v185, -1, v185
	v_pk_mul_f32 v[164:165], v[208:209], s[8:9] op_sel_hi:[1,0]
	v_pk_mul_f32 v[162:163], v[210:211], s[8:9] op_sel_hi:[1,0]
	v_ashrrev_i32_e32 v30, 5, v185
	v_add_u32_e32 v16, s3, v30
	v_and_b32_e32 v31, 31, v185
	v_ashrrev_i32_e32 v17, 31, v16
	v_readlane_b32 s8, v253, 47
	v_lshlrev_b64 v[16:17], 11, v[16:17]
	v_readlane_b32 s9, v253, 48
	s_lshl_b32 s3, s26, 14
	v_bitop3_b32 v18, v30, v31, 15 bitop3:0x6c
	v_lshl_add_u64 v[16:17], s[8:9], 0, v[16:17]
	s_add_i32 s3, s3, 0
	v_lshlrev_b32_e32 v230, 4, v18
	v_lshl_add_u64 v[18:19], v[16:17], 0, v[230:231]
	s_mov_b32 m0, s3
	s_mov_b64 s[8:9], 0x1000
	global_load_lds_dwordx4 v[18:19], off
	v_lshl_add_u64 v[18:19], v[16:17], 0, s[8:9]
	v_add_u32_e32 v16, 2, v30
	v_bitop3_b32 v16, v16, v31, 15 bitop3:0x6c
	v_lshlrev_b32_e32 v16, 4, v16
	v_mov_b32_e32 v17, v231
	s_add_i32 m0, s3, 0x400
	v_lshl_add_u64 v[20:21], v[18:19], 0, v[16:17]
	global_load_lds_dwordx4 v[20:21], off
	v_lshl_add_u64 v[20:21], v[18:19], 0, s[8:9]
	v_add_u32_e32 v18, 4, v30
	v_bitop3_b32 v18, v18, v31, 15 bitop3:0x6c
	v_lshlrev_b32_e32 v18, 4, v18
	v_mov_b32_e32 v19, v231
	s_add_i32 m0, s3, 0x800
	v_lshl_add_u64 v[22:23], v[20:21], 0, v[18:19]
	global_load_lds_dwordx4 v[22:23], off
	v_lshl_add_u64 v[22:23], v[20:21], 0, s[8:9]
	v_add_u32_e32 v20, 6, v30
	v_bitop3_b32 v20, v20, v31, 15 bitop3:0x6c
	v_lshlrev_b32_e32 v20, 4, v20
	v_mov_b32_e32 v21, v231
	s_add_i32 m0, s3, 0xc00
	v_lshl_add_u64 v[24:25], v[22:23], 0, v[20:21]
	global_load_lds_dwordx4 v[24:25], off
	v_lshl_add_u64 v[24:25], v[22:23], 0, s[8:9]
	v_xor_b32_e32 v22, 0x80, v230
	v_mov_b32_e32 v23, v231
	s_add_i32 m0, s3, 0x1000
	v_lshl_add_u64 v[26:27], v[24:25], 0, v[22:23]
	global_load_lds_dwordx4 v[26:27], off
	v_lshl_add_u64 v[26:27], v[24:25], 0, s[8:9]
	v_add_u32_e32 v24, 10, v30
	v_bitop3_b32 v24, v24, v31, 15 bitop3:0x6c
	v_lshlrev_b32_e32 v24, 4, v24
	v_mov_b32_e32 v25, v231
	s_add_i32 m0, s3, 0x1400
	v_lshl_add_u64 v[28:29], v[26:27], 0, v[24:25]
	global_load_lds_dwordx4 v[28:29], off
	v_add_u32_e32 v28, 12, v30
	v_bitop3_b32 v28, v28, v31, 15 bitop3:0x6c
	v_lshl_add_u64 v[26:27], v[26:27], 0, s[8:9]
	v_lshlrev_b32_e32 v28, 4, v28
	v_mov_b32_e32 v29, v231
	s_add_i32 m0, s3, 0x1800
	v_lshl_add_u64 v[180:181], v[26:27], 0, v[28:29]
	global_load_lds_dwordx4 v[180:181], off
	v_add_u32_e32 v180, 14, v30
	v_lshl_add_u64 v[26:27], v[26:27], 0, s[8:9]
	v_bitop3_b32 v31, v180, v31, 15 bitop3:0x6c
	v_lshlrev_b32_e32 v180, 4, v31
	v_mov_b32_e32 v181, v231
	v_lshl_add_u64 v[182:183], v[26:27], 0, v[180:181]
	s_add_i32 m0, s3, 0x1c00
	v_lshl_add_u64 v[26:27], v[26:27], 0, s[8:9]
	global_load_lds_dwordx4 v[182:183], off
	s_add_i32 m0, s3, 0x2000
	v_lshl_add_u64 v[182:183], v[26:27], 0, v[230:231]
	v_lshl_add_u64 v[26:27], v[26:27], 0, s[8:9]
	global_load_lds_dwordx4 v[182:183], off
	s_add_i32 m0, s3, 0x2400
	v_lshl_add_u64 v[16:17], v[26:27], 0, v[16:17]
	global_load_lds_dwordx4 v[16:17], off
	v_lshl_add_u64 v[16:17], v[26:27], 0, s[8:9]
	s_add_i32 m0, s3, 0x2800
	v_lshl_add_u64 v[18:19], v[16:17], 0, v[18:19]
	v_lshl_add_u64 v[16:17], v[16:17], 0, s[8:9]
	global_load_lds_dwordx4 v[18:19], off
	s_add_i32 m0, s3, 0x2c00
	v_lshl_add_u64 v[18:19], v[16:17], 0, v[20:21]
	v_lshl_add_u64 v[16:17], v[16:17], 0, s[8:9]
	global_load_lds_dwordx4 v[18:19], off
	s_add_i32 m0, s3, 0x3000
	v_lshl_add_u64 v[18:19], v[16:17], 0, v[22:23]
	v_lshl_add_u64 v[16:17], v[16:17], 0, s[8:9]
	global_load_lds_dwordx4 v[18:19], off
	s_add_i32 m0, s3, 0x3400
	v_lshl_add_u64 v[18:19], v[16:17], 0, v[24:25]
	v_lshl_add_u64 v[16:17], v[16:17], 0, s[8:9]
	global_load_lds_dwordx4 v[18:19], off
	s_add_i32 m0, s3, 0x3800
	v_lshl_add_u64 v[18:19], v[16:17], 0, v[28:29]
	v_lshl_add_u64 v[16:17], v[16:17], 0, s[8:9]
	global_load_lds_dwordx4 v[18:19], off
	s_add_i32 m0, s3, 0x3c00
	v_lshl_add_u64 v[18:19], v[16:17], 0, v[180:181]
	v_lshl_add_u64 v[16:17], v[16:17], 0, s[8:9]
	global_load_lds_dwordx4 v[18:19], off
	v_lshrrev_b32_e32 v18, 1, v185
	v_lshlrev_b32_e32 v17, 9, v185
	v_and_b32_e32 v17, 0x200, v17
	v_and_b32_e32 v18, 8, v18
	v_lshl_add_u32 v187, s25, 2, v30
	v_and_b32_e32 v16, 15, v185
	v_add3_u32 v183, 0, v17, v18
	v_add_u32_e32 v17, 16, v187
	v_bitop3_b32 v17, v17, v185, 15 bitop3:0x78
	s_lshl_b32 s3, s24, 15
	v_lshlrev_b32_e32 v16, 9, v16
	v_lshlrev_b32_e32 v180, 4, v17
	v_or_b32_e32 v184, s3, v16
	v_mov_b32_e32 v17, s3
	s_movk_i32 s3, 0x9c00
	v_bitop3_b32 v16, v16, s3, v17 bitop3:0xc8
	v_add_u32_e32 v181, v183, v16
	v_bitop3_b32 v16, v187, v185, 15 bitop3:0x78
	v_lshlrev_b32_e32 v182, 4, v16
	s_waitcnt vmcnt(0)
	s_barrier
	v_add_u32_e32 v186, v181, v182
	ds_read_b64 v[16:17], v186
	s_mov_b32 s8, 0x3fd744fd
	s_lshl_b32 s3, s25, 3
	s_add_i32 s11, s3, 0
	s_waitcnt lgkmcnt(0)
	v_cvt_f32_f16_e32 v18, v16
	v_cvt_f32_f16_sdwa v19, v16 dst_sel:DWORD dst_unused:UNUSED_PAD src0_sel:WORD_1
	v_cvt_f32_f16_e32 v16, v17
	v_cvt_f32_f16_sdwa v17, v17 dst_sel:DWORD dst_unused:UNUSED_PAD src0_sel:WORD_1
	v_pk_mul_f32 v[20:21], v[18:19], s[8:9] op_sel_hi:[1,0]
	v_pk_mul_f32 v[16:17], v[16:17], s[8:9] op_sel_hi:[1,0]
	s_nop 0
	v_pk_fma_f32 v[18:19], v[158:159], v[174:175], v[16:17]
	v_pk_fma_f32 v[16:17], v[156:157], v[176:177], v[20:21]
	v_add_u32_e32 v20, 2, v187
	v_bitop3_b32 v20, v20, v185, 15 bitop3:0x78
	v_lshlrev_b32_e32 v156, 4, v20
	v_add_u32_e32 v157, v181, v156
	ds_read_b64 v[20:21], v157
	s_waitcnt lgkmcnt(0)
	v_cvt_f32_f16_e32 v22, v20
	v_cvt_f32_f16_sdwa v23, v20 dst_sel:DWORD dst_unused:UNUSED_PAD src0_sel:WORD_1
	v_cvt_f32_f16_e32 v20, v21
	v_cvt_f32_f16_sdwa v21, v21 dst_sel:DWORD dst_unused:UNUSED_PAD src0_sel:WORD_1
	v_pk_mul_f32 v[24:25], v[22:23], s[8:9] op_sel_hi:[1,0]
	v_pk_mul_f32 v[20:21], v[20:21], s[8:9] op_sel_hi:[1,0]
	s_nop 0
	v_pk_fma_f32 v[22:23], v[154:155], v[170:171], v[20:21]
	v_pk_fma_f32 v[20:21], v[152:153], v[172:173], v[24:25]
	v_add_u32_e32 v152, v181, v180
	ds_read_b64 v[24:25], v152
	s_waitcnt lgkmcnt(0)
	v_cvt_f32_f16_e32 v26, v24
	v_cvt_f32_f16_sdwa v27, v24 dst_sel:DWORD dst_unused:UNUSED_PAD src0_sel:WORD_1
	v_cvt_f32_f16_e32 v24, v25
	v_cvt_f32_f16_sdwa v25, v25 dst_sel:DWORD dst_unused:UNUSED_PAD src0_sel:WORD_1
	v_pk_mul_f32 v[26:27], v[26:27], s[8:9] op_sel_hi:[1,0]
	s_nop 0
	v_pk_fma_f32 v[28:29], v[148:149], v[168:169], v[26:27]
	v_pk_mul_f32 v[24:25], v[24:25], s[8:9] op_sel_hi:[1,0]
	s_nop 0
	v_pk_fma_f32 v[30:31], v[150:151], v[166:167], v[24:25]
	v_add_u32_e32 v24, 18, v187
	v_bitop3_b32 v24, v24, v185, 15 bitop3:0x78
	v_lshlrev_b32_e32 v148, 4, v24
	v_add_u32_e32 v149, v181, v148
	ds_read_b64 v[24:25], v149
	s_waitcnt lgkmcnt(0)
	v_cvt_f32_f16_e32 v26, v24
	v_cvt_f32_f16_sdwa v27, v24 dst_sel:DWORD dst_unused:UNUSED_PAD src0_sel:WORD_1
	v_cvt_f32_f16_e32 v24, v25
	v_cvt_f32_f16_sdwa v25, v25 dst_sel:DWORD dst_unused:UNUSED_PAD src0_sel:WORD_1
	v_pk_mul_f32 v[26:27], v[26:27], s[8:9] op_sel_hi:[1,0]
	s_nop 0
	v_pk_fma_f32 v[144:145], v[144:145], v[164:165], v[26:27]
	v_pk_mul_f32 v[24:25], v[24:25], s[8:9] op_sel_hi:[1,0]
	s_nop 0
	v_pk_fma_f32 v[146:147], v[146:147], v[162:163], v[24:25]
	s_nop 0
	ds_read_b64 v[24:25], v186 offset:8192
	v_pk_add_f32 v[154:155], v[4:5], v[16:17]
	v_pk_add_f32 v[16:17], v[10:11], v[146:147]
	s_waitcnt lgkmcnt(0)
	v_cvt_f32_f16_e32 v26, v24
	v_cvt_f32_f16_sdwa v27, v24 dst_sel:DWORD dst_unused:UNUSED_PAD src0_sel:WORD_1
	v_cvt_f32_f16_e32 v24, v25
	v_cvt_f32_f16_sdwa v25, v25 dst_sel:DWORD dst_unused:UNUSED_PAD src0_sel:WORD_1
	v_pk_mul_f32 v[150:151], v[26:27], s[8:9] op_sel_hi:[1,0]
	v_pk_mul_f32 v[24:25], v[24:25], s[8:9] op_sel_hi:[1,0]
	s_nop 0
	v_pk_fma_f32 v[26:27], v[142:143], v[174:175], v[24:25]
	v_pk_fma_f32 v[24:25], v[140:141], v[176:177], v[150:151]
	ds_read_b64 v[140:141], v157 offset:8192
	v_pk_add_f32 v[150:151], v[0:1], v[20:21]
	v_lshlrev_b32_e32 v20, 2, v178
	s_waitcnt lgkmcnt(0)
	v_cvt_f32_f16_e32 v142, v140
	v_cvt_f32_f16_sdwa v143, v140 dst_sel:DWORD dst_unused:UNUSED_PAD src0_sel:WORD_1
	v_cvt_f32_f16_e32 v140, v141
	v_cvt_f32_f16_sdwa v141, v141 dst_sel:DWORD dst_unused:UNUSED_PAD src0_sel:WORD_1
	v_pk_mul_f32 v[142:143], v[142:143], s[8:9] op_sel_hi:[1,0]
	s_nop 0
	v_pk_fma_f32 v[136:137], v[136:137], v[172:173], v[142:143]
	v_pk_mul_f32 v[140:141], v[140:141], s[8:9] op_sel_hi:[1,0]
	s_nop 0
	v_pk_fma_f32 v[138:139], v[138:139], v[170:171], v[140:141]
	ds_read_b64 v[140:141], v152 offset:8192
	s_waitcnt lgkmcnt(0)
	v_cvt_f32_f16_e32 v142, v140
	v_cvt_f32_f16_sdwa v143, v140 dst_sel:DWORD dst_unused:UNUSED_PAD src0_sel:WORD_1
	v_cvt_f32_f16_e32 v140, v141
	v_cvt_f32_f16_sdwa v141, v141 dst_sel:DWORD dst_unused:UNUSED_PAD src0_sel:WORD_1
	v_pk_mul_f32 v[142:143], v[142:143], s[8:9] op_sel_hi:[1,0]
	s_nop 0
	v_pk_fma_f32 v[132:133], v[132:133], v[168:169], v[142:143]
	v_pk_mul_f32 v[140:141], v[140:141], s[8:9] op_sel_hi:[1,0]
	s_nop 0
	v_pk_fma_f32 v[134:135], v[134:135], v[166:167], v[140:141]
	ds_read_b64 v[140:141], v149 offset:8192
	s_waitcnt lgkmcnt(0)
	v_cvt_f32_f16_e32 v142, v140
	v_cvt_f32_f16_sdwa v143, v140 dst_sel:DWORD dst_unused:UNUSED_PAD src0_sel:WORD_1
	v_cvt_f32_f16_e32 v140, v141
	v_cvt_f32_f16_sdwa v141, v141 dst_sel:DWORD dst_unused:UNUSED_PAD src0_sel:WORD_1
	v_pk_mul_f32 v[142:143], v[142:143], s[8:9] op_sel_hi:[1,0]
	s_nop 0
	v_pk_fma_f32 v[128:129], v[128:129], v[164:165], v[142:143]
	v_pk_mul_f32 v[140:141], v[140:141], s[8:9] op_sel_hi:[1,0]
	s_nop 0
	v_pk_fma_f32 v[130:131], v[130:131], v[162:163], v[140:141]
	s_nop 0
	ds_read_b64 v[140:141], v186 offset:16384
	s_waitcnt lgkmcnt(0)
	v_cvt_f32_f16_e32 v142, v140
	v_cvt_f32_f16_sdwa v143, v140 dst_sel:DWORD dst_unused:UNUSED_PAD src0_sel:WORD_1
	v_cvt_f32_f16_e32 v140, v141
	v_cvt_f32_f16_sdwa v141, v141 dst_sel:DWORD dst_unused:UNUSED_PAD src0_sel:WORD_1
	v_pk_mul_f32 v[142:143], v[142:143], s[8:9] op_sel_hi:[1,0]
	s_nop 0
	v_pk_fma_f32 v[124:125], v[124:125], v[176:177], v[142:143]
	v_pk_mul_f32 v[140:141], v[140:141], s[8:9] op_sel_hi:[1,0]
	s_nop 0
	v_pk_fma_f32 v[126:127], v[126:127], v[174:175], v[140:141]
	ds_read_b64 v[140:141], v157 offset:16384
	s_waitcnt lgkmcnt(0)
	v_cvt_f32_f16_e32 v142, v140
	v_cvt_f32_f16_sdwa v143, v140 dst_sel:DWORD dst_unused:UNUSED_PAD src0_sel:WORD_1
	v_cvt_f32_f16_e32 v140, v141
	v_cvt_f32_f16_sdwa v141, v141 dst_sel:DWORD dst_unused:UNUSED_PAD src0_sel:WORD_1
	v_pk_mul_f32 v[142:143], v[142:143], s[8:9] op_sel_hi:[1,0]
	s_nop 0
	v_pk_fma_f32 v[120:121], v[120:121], v[172:173], v[142:143]
	v_pk_mul_f32 v[140:141], v[140:141], s[8:9] op_sel_hi:[1,0]
	s_nop 0
	v_pk_fma_f32 v[122:123], v[122:123], v[170:171], v[140:141]
	ds_read_b64 v[140:141], v152 offset:16384
	s_waitcnt lgkmcnt(0)
	v_cvt_f32_f16_e32 v142, v140
	v_cvt_f32_f16_sdwa v143, v140 dst_sel:DWORD dst_unused:UNUSED_PAD src0_sel:WORD_1
	v_cvt_f32_f16_e32 v140, v141
	v_cvt_f32_f16_sdwa v141, v141 dst_sel:DWORD dst_unused:UNUSED_PAD src0_sel:WORD_1
	v_pk_mul_f32 v[142:143], v[142:143], s[8:9] op_sel_hi:[1,0]
	s_nop 0
	v_pk_fma_f32 v[116:117], v[116:117], v[168:169], v[142:143]
	v_pk_mul_f32 v[140:141], v[140:141], s[8:9] op_sel_hi:[1,0]
	s_nop 0
	v_pk_fma_f32 v[118:119], v[118:119], v[166:167], v[140:141]
	ds_read_b64 v[140:141], v149 offset:16384
	s_waitcnt lgkmcnt(0)
	v_cvt_f32_f16_e32 v142, v140
	v_cvt_f32_f16_sdwa v143, v140 dst_sel:DWORD dst_unused:UNUSED_PAD src0_sel:WORD_1
	v_cvt_f32_f16_e32 v140, v141
	v_cvt_f32_f16_sdwa v141, v141 dst_sel:DWORD dst_unused:UNUSED_PAD src0_sel:WORD_1
	v_pk_mul_f32 v[142:143], v[142:143], s[8:9] op_sel_hi:[1,0]
	s_nop 0
	v_pk_fma_f32 v[112:113], v[112:113], v[164:165], v[142:143]
	v_pk_mul_f32 v[140:141], v[140:141], s[8:9] op_sel_hi:[1,0]
	s_nop 0
	v_pk_fma_f32 v[114:115], v[114:115], v[162:163], v[140:141]
	s_nop 0
	ds_read_b64 v[140:141], v186 offset:24576
	s_waitcnt lgkmcnt(0)
	v_cvt_f32_f16_e32 v142, v140
	v_cvt_f32_f16_sdwa v143, v140 dst_sel:DWORD dst_unused:UNUSED_PAD src0_sel:WORD_1
	v_cvt_f32_f16_e32 v140, v141
	v_cvt_f32_f16_sdwa v141, v141 dst_sel:DWORD dst_unused:UNUSED_PAD src0_sel:WORD_1
	v_pk_mul_f32 v[142:143], v[142:143], s[8:9] op_sel_hi:[1,0]
	s_nop 0
	v_pk_fma_f32 v[108:109], v[108:109], v[176:177], v[142:143]
	v_pk_mul_f32 v[140:141], v[140:141], s[8:9] op_sel_hi:[1,0]
	s_nop 0
	v_pk_fma_f32 v[110:111], v[110:111], v[174:175], v[140:141]
	ds_read_b64 v[140:141], v157 offset:24576
	s_waitcnt lgkmcnt(0)
	v_cvt_f32_f16_e32 v142, v140
	v_cvt_f32_f16_sdwa v143, v140 dst_sel:DWORD dst_unused:UNUSED_PAD src0_sel:WORD_1
	v_cvt_f32_f16_e32 v140, v141
	v_cvt_f32_f16_sdwa v141, v141 dst_sel:DWORD dst_unused:UNUSED_PAD src0_sel:WORD_1
	v_pk_mul_f32 v[142:143], v[142:143], s[8:9] op_sel_hi:[1,0]
	s_nop 0
	v_pk_fma_f32 v[104:105], v[104:105], v[172:173], v[142:143]
	v_pk_mul_f32 v[140:141], v[140:141], s[8:9] op_sel_hi:[1,0]
	s_nop 0
	v_pk_fma_f32 v[106:107], v[106:107], v[170:171], v[140:141]
	ds_read_b64 v[140:141], v152 offset:24576
	v_pk_add_f32 v[152:153], v[6:7], v[18:19]
	v_pk_add_f32 v[18:19], v[8:9], v[144:145]
	s_waitcnt lgkmcnt(0)
	v_cvt_f32_f16_e32 v142, v140
	v_cvt_f32_f16_sdwa v143, v140 dst_sel:DWORD dst_unused:UNUSED_PAD src0_sel:WORD_1
	v_cvt_f32_f16_e32 v140, v141
	v_cvt_f32_f16_sdwa v141, v141 dst_sel:DWORD dst_unused:UNUSED_PAD src0_sel:WORD_1
	v_pk_mul_f32 v[142:143], v[142:143], s[8:9] op_sel_hi:[1,0]
	s_nop 0
	v_pk_fma_f32 v[100:101], v[100:101], v[168:169], v[142:143]
	v_pk_mul_f32 v[140:141], v[140:141], s[8:9] op_sel_hi:[1,0]
	s_nop 0
	v_pk_fma_f32 v[102:103], v[102:103], v[166:167], v[140:141]
	ds_read_b64 v[140:141], v149 offset:24576
	v_add_u32_e32 v149, 0x10000, v181
	s_waitcnt lgkmcnt(0)
	v_cvt_f32_f16_e32 v142, v140
	v_cvt_f32_f16_sdwa v143, v140 dst_sel:DWORD dst_unused:UNUSED_PAD src0_sel:WORD_1
	v_cvt_f32_f16_e32 v140, v141
	v_cvt_f32_f16_sdwa v141, v141 dst_sel:DWORD dst_unused:UNUSED_PAD src0_sel:WORD_1
	v_pk_mul_f32 v[142:143], v[142:143], s[8:9] op_sel_hi:[1,0]
	s_nop 0
	v_pk_fma_f32 v[96:97], v[96:97], v[164:165], v[142:143]
	v_pk_mul_f32 v[140:141], v[140:141], s[8:9] op_sel_hi:[1,0]
	s_nop 0
	v_pk_fma_f32 v[98:99], v[98:99], v[162:163], v[140:141]
	v_add_u32_e32 v140, v149, v182
	ds_read_b64 v[140:141], v140
	s_waitcnt lgkmcnt(0)
	v_cvt_f32_f16_e32 v142, v140
	v_cvt_f32_f16_sdwa v143, v140 dst_sel:DWORD dst_unused:UNUSED_PAD src0_sel:WORD_1
	v_cvt_f32_f16_e32 v140, v141
	v_cvt_f32_f16_sdwa v141, v141 dst_sel:DWORD dst_unused:UNUSED_PAD src0_sel:WORD_1
	v_pk_mul_f32 v[142:143], v[142:143], s[8:9] op_sel_hi:[1,0]
	s_nop 0
	v_pk_fma_f32 v[92:93], v[92:93], v[176:177], v[142:143]
	v_pk_mul_f32 v[140:141], v[140:141], s[8:9] op_sel_hi:[1,0]
	s_nop 0
	v_pk_fma_f32 v[94:95], v[94:95], v[174:175], v[140:141]
	v_add_u32_e32 v140, v149, v156
	ds_read_b64 v[140:141], v140
	s_waitcnt lgkmcnt(0)
	v_cvt_f32_f16_e32 v142, v140
	v_cvt_f32_f16_sdwa v143, v140 dst_sel:DWORD dst_unused:UNUSED_PAD src0_sel:WORD_1
	v_cvt_f32_f16_e32 v140, v141
	v_cvt_f32_f16_sdwa v141, v141 dst_sel:DWORD dst_unused:UNUSED_PAD src0_sel:WORD_1
	v_pk_mul_f32 v[142:143], v[142:143], s[8:9] op_sel_hi:[1,0]
	s_nop 0
	v_pk_fma_f32 v[88:89], v[88:89], v[172:173], v[142:143]
	v_pk_mul_f32 v[140:141], v[140:141], s[8:9] op_sel_hi:[1,0]
	s_nop 0
	v_pk_fma_f32 v[90:91], v[90:91], v[170:171], v[140:141]
	v_add_u32_e32 v140, v149, v180
	ds_read_b64 v[140:141], v140
	s_waitcnt lgkmcnt(0)
	v_cvt_f32_f16_e32 v142, v140
	v_cvt_f32_f16_sdwa v143, v140 dst_sel:DWORD dst_unused:UNUSED_PAD src0_sel:WORD_1
	v_cvt_f32_f16_e32 v140, v141
	v_cvt_f32_f16_sdwa v141, v141 dst_sel:DWORD dst_unused:UNUSED_PAD src0_sel:WORD_1
	v_pk_mul_f32 v[142:143], v[142:143], s[8:9] op_sel_hi:[1,0]
	s_nop 0
	v_pk_fma_f32 v[84:85], v[84:85], v[168:169], v[142:143]
	v_pk_mul_f32 v[140:141], v[140:141], s[8:9] op_sel_hi:[1,0]
	s_nop 0
	v_pk_fma_f32 v[86:87], v[86:87], v[166:167], v[140:141]
	v_add_u32_e32 v140, v149, v148
	ds_read_b64 v[140:141], v140
	s_waitcnt lgkmcnt(0)
	v_cvt_f32_f16_e32 v142, v140
	v_cvt_f32_f16_sdwa v143, v140 dst_sel:DWORD dst_unused:UNUSED_PAD src0_sel:WORD_1
	v_cvt_f32_f16_e32 v140, v141
	v_cvt_f32_f16_sdwa v141, v141 dst_sel:DWORD dst_unused:UNUSED_PAD src0_sel:WORD_1
	v_pk_mul_f32 v[142:143], v[142:143], s[8:9] op_sel_hi:[1,0]
	s_nop 0
	v_pk_fma_f32 v[80:81], v[80:81], v[164:165], v[142:143]
	v_pk_mul_f32 v[140:141], v[140:141], s[8:9] op_sel_hi:[1,0]
	s_nop 0
	v_pk_fma_f32 v[82:83], v[82:83], v[162:163], v[140:141]
	v_add_u32_e32 v140, 0x12000, v184
	v_and_b32_e32 v140, 0xffffbc00, v140
	v_add_u32_e32 v149, v183, v140
	v_add_u32_e32 v140, v149, v182
	ds_read_b64 v[140:141], v140
	s_waitcnt lgkmcnt(0)
	v_cvt_f32_f16_e32 v142, v140
	v_cvt_f32_f16_sdwa v143, v140 dst_sel:DWORD dst_unused:UNUSED_PAD src0_sel:WORD_1
	v_cvt_f32_f16_e32 v140, v141
	v_cvt_f32_f16_sdwa v141, v141 dst_sel:DWORD dst_unused:UNUSED_PAD src0_sel:WORD_1
	v_pk_mul_f32 v[142:143], v[142:143], s[8:9] op_sel_hi:[1,0]
	s_nop 0
	v_pk_fma_f32 v[76:77], v[76:77], v[176:177], v[142:143]
	v_pk_mul_f32 v[140:141], v[140:141], s[8:9] op_sel_hi:[1,0]
	s_nop 0
	v_pk_fma_f32 v[78:79], v[78:79], v[174:175], v[140:141]
	v_add_u32_e32 v140, v149, v156
	ds_read_b64 v[140:141], v140
	s_waitcnt lgkmcnt(0)
	v_cvt_f32_f16_e32 v142, v140
	v_cvt_f32_f16_sdwa v143, v140 dst_sel:DWORD dst_unused:UNUSED_PAD src0_sel:WORD_1
	v_cvt_f32_f16_e32 v140, v141
	v_cvt_f32_f16_sdwa v141, v141 dst_sel:DWORD dst_unused:UNUSED_PAD src0_sel:WORD_1
	v_pk_mul_f32 v[142:143], v[142:143], s[8:9] op_sel_hi:[1,0]
	s_nop 0
	v_pk_fma_f32 v[72:73], v[72:73], v[172:173], v[142:143]
	v_pk_mul_f32 v[140:141], v[140:141], s[8:9] op_sel_hi:[1,0]
	s_nop 0
	v_pk_fma_f32 v[74:75], v[74:75], v[170:171], v[140:141]
	v_add_u32_e32 v140, v149, v180
	ds_read_b64 v[140:141], v140
	s_waitcnt lgkmcnt(0)
	v_cvt_f32_f16_e32 v142, v140
	v_cvt_f32_f16_sdwa v143, v140 dst_sel:DWORD dst_unused:UNUSED_PAD src0_sel:WORD_1
	v_cvt_f32_f16_e32 v140, v141
	v_cvt_f32_f16_sdwa v141, v141 dst_sel:DWORD dst_unused:UNUSED_PAD src0_sel:WORD_1
	v_pk_mul_f32 v[142:143], v[142:143], s[8:9] op_sel_hi:[1,0]
	s_nop 0
	v_pk_fma_f32 v[68:69], v[68:69], v[168:169], v[142:143]
	v_pk_mul_f32 v[140:141], v[140:141], s[8:9] op_sel_hi:[1,0]
	s_nop 0
	v_pk_fma_f32 v[70:71], v[70:71], v[166:167], v[140:141]
	v_add_u32_e32 v140, v149, v148
	ds_read_b64 v[140:141], v140
	v_add_u32_e32 v149, 0x14000, v181
	s_waitcnt lgkmcnt(0)
	v_cvt_f32_f16_e32 v142, v140
	v_cvt_f32_f16_sdwa v143, v140 dst_sel:DWORD dst_unused:UNUSED_PAD src0_sel:WORD_1
	v_cvt_f32_f16_e32 v140, v141
	v_cvt_f32_f16_sdwa v141, v141 dst_sel:DWORD dst_unused:UNUSED_PAD src0_sel:WORD_1
	v_pk_mul_f32 v[142:143], v[142:143], s[8:9] op_sel_hi:[1,0]
	s_nop 0
	v_pk_fma_f32 v[64:65], v[64:65], v[164:165], v[142:143]
	v_pk_mul_f32 v[140:141], v[140:141], s[8:9] op_sel_hi:[1,0]
	s_nop 0
	v_pk_fma_f32 v[66:67], v[66:67], v[162:163], v[140:141]
	v_add_u32_e32 v140, v149, v182
	ds_read_b64 v[140:141], v140
	s_waitcnt lgkmcnt(0)
	v_cvt_f32_f16_e32 v142, v140
	v_cvt_f32_f16_sdwa v143, v140 dst_sel:DWORD dst_unused:UNUSED_PAD src0_sel:WORD_1
	v_cvt_f32_f16_e32 v140, v141
	v_cvt_f32_f16_sdwa v141, v141 dst_sel:DWORD dst_unused:UNUSED_PAD src0_sel:WORD_1
	v_pk_mul_f32 v[142:143], v[142:143], s[8:9] op_sel_hi:[1,0]
	s_nop 0
	v_pk_fma_f32 v[60:61], v[60:61], v[176:177], v[142:143]
	v_pk_mul_f32 v[140:141], v[140:141], s[8:9] op_sel_hi:[1,0]
	s_nop 0
	v_pk_fma_f32 v[62:63], v[62:63], v[174:175], v[140:141]
	v_add_u32_e32 v140, v149, v156
	ds_read_b64 v[140:141], v140
	s_waitcnt lgkmcnt(0)
	v_cvt_f32_f16_e32 v142, v140
	v_cvt_f32_f16_sdwa v143, v140 dst_sel:DWORD dst_unused:UNUSED_PAD src0_sel:WORD_1
	v_cvt_f32_f16_e32 v140, v141
	v_cvt_f32_f16_sdwa v141, v141 dst_sel:DWORD dst_unused:UNUSED_PAD src0_sel:WORD_1
	v_pk_mul_f32 v[142:143], v[142:143], s[8:9] op_sel_hi:[1,0]
	s_nop 0
	v_pk_fma_f32 v[56:57], v[56:57], v[172:173], v[142:143]
	v_pk_mul_f32 v[140:141], v[140:141], s[8:9] op_sel_hi:[1,0]
	s_nop 0
	v_pk_fma_f32 v[58:59], v[58:59], v[170:171], v[140:141]
	v_add_u32_e32 v140, v149, v180
	ds_read_b64 v[140:141], v140
	s_waitcnt lgkmcnt(0)
	v_cvt_f32_f16_e32 v142, v140
	v_cvt_f32_f16_sdwa v143, v140 dst_sel:DWORD dst_unused:UNUSED_PAD src0_sel:WORD_1
	v_cvt_f32_f16_e32 v140, v141
	v_cvt_f32_f16_sdwa v141, v141 dst_sel:DWORD dst_unused:UNUSED_PAD src0_sel:WORD_1
	v_pk_mul_f32 v[142:143], v[142:143], s[8:9] op_sel_hi:[1,0]
	s_nop 0
	v_pk_fma_f32 v[52:53], v[52:53], v[168:169], v[142:143]
	v_pk_mul_f32 v[140:141], v[140:141], s[8:9] op_sel_hi:[1,0]
	s_nop 0
	v_pk_fma_f32 v[54:55], v[54:55], v[166:167], v[140:141]
	v_add_u32_e32 v140, v149, v148
	ds_read_b64 v[140:141], v140
	v_add_u32_e32 v149, 0x16000, v181
	s_waitcnt lgkmcnt(0)
	v_cvt_f32_f16_e32 v142, v140
	v_cvt_f32_f16_sdwa v143, v140 dst_sel:DWORD dst_unused:UNUSED_PAD src0_sel:WORD_1
	v_cvt_f32_f16_e32 v140, v141
	v_cvt_f32_f16_sdwa v141, v141 dst_sel:DWORD dst_unused:UNUSED_PAD src0_sel:WORD_1
	v_pk_mul_f32 v[142:143], v[142:143], s[8:9] op_sel_hi:[1,0]
	s_nop 0
	v_pk_fma_f32 v[48:49], v[48:49], v[164:165], v[142:143]
	v_pk_mul_f32 v[140:141], v[140:141], s[8:9] op_sel_hi:[1,0]
	s_nop 0
	v_pk_fma_f32 v[50:51], v[50:51], v[162:163], v[140:141]
	v_add_u32_e32 v140, v149, v182
	ds_read_b64 v[140:141], v140
	s_waitcnt lgkmcnt(0)
	v_cvt_f32_f16_e32 v142, v140
	v_cvt_f32_f16_sdwa v143, v140 dst_sel:DWORD dst_unused:UNUSED_PAD src0_sel:WORD_1
	v_cvt_f32_f16_e32 v140, v141
	v_cvt_f32_f16_sdwa v141, v141 dst_sel:DWORD dst_unused:UNUSED_PAD src0_sel:WORD_1
	v_pk_mul_f32 v[142:143], v[142:143], s[8:9] op_sel_hi:[1,0]
	s_nop 0
	v_pk_fma_f32 v[44:45], v[44:45], v[176:177], v[142:143]
	v_pk_mul_f32 v[140:141], v[140:141], s[8:9] op_sel_hi:[1,0]
	s_nop 0
	v_pk_fma_f32 v[46:47], v[46:47], v[174:175], v[140:141]
	v_add_u32_e32 v140, v149, v156
	ds_read_b64 v[140:141], v140
	s_waitcnt lgkmcnt(0)
	v_cvt_f32_f16_e32 v142, v140
	v_cvt_f32_f16_sdwa v143, v140 dst_sel:DWORD dst_unused:UNUSED_PAD src0_sel:WORD_1
	v_cvt_f32_f16_e32 v140, v141
	v_cvt_f32_f16_sdwa v141, v141 dst_sel:DWORD dst_unused:UNUSED_PAD src0_sel:WORD_1
	v_pk_mul_f32 v[142:143], v[142:143], s[8:9] op_sel_hi:[1,0]
	s_nop 0
	v_pk_fma_f32 v[40:41], v[40:41], v[172:173], v[142:143]
	v_pk_mul_f32 v[140:141], v[140:141], s[8:9] op_sel_hi:[1,0]
	s_nop 0
	v_pk_fma_f32 v[42:43], v[42:43], v[170:171], v[140:141]
	v_add_u32_e32 v140, v149, v180
	ds_read_b64 v[140:141], v140
	s_waitcnt lgkmcnt(0)
	v_cvt_f32_f16_e32 v142, v140
	v_cvt_f32_f16_sdwa v143, v140 dst_sel:DWORD dst_unused:UNUSED_PAD src0_sel:WORD_1
	v_cvt_f32_f16_e32 v140, v141
	v_cvt_f32_f16_sdwa v141, v141 dst_sel:DWORD dst_unused:UNUSED_PAD src0_sel:WORD_1
	v_pk_mul_f32 v[142:143], v[142:143], s[8:9] op_sel_hi:[1,0]
	s_nop 0
	v_pk_fma_f32 v[36:37], v[36:37], v[168:169], v[142:143]
	v_pk_mul_f32 v[140:141], v[140:141], s[8:9] op_sel_hi:[1,0]
	v_xor_b32_e32 v169, 64, v20
	v_pk_fma_f32 v[38:39], v[38:39], v[166:167], v[140:141]
	v_add_u32_e32 v140, v149, v148
	ds_read_b64 v[140:141], v140
	v_pk_add_f32 v[148:149], v[2:3], v[22:23]
	v_xor_b32_e32 v168, 0x80, v20
	v_pk_mov_b32 v[20:21], v[154:155], v[152:153] op_sel:[1,0]
	v_mov_b32_e32 v22, v154
	s_waitcnt lgkmcnt(0)
	v_cvt_f32_f16_e32 v142, v140
	v_cvt_f32_f16_sdwa v143, v140 dst_sel:DWORD dst_unused:UNUSED_PAD src0_sel:WORD_1
	v_cvt_f32_f16_e32 v140, v141
	v_cvt_f32_f16_sdwa v141, v141 dst_sel:DWORD dst_unused:UNUSED_PAD src0_sel:WORD_1
	v_mov_b32_e32 v23, v153
	v_pk_mul_f32 v[142:143], v[142:143], s[8:9] op_sel_hi:[1,0]
	v_pk_add_f32 v[20:21], v[20:21], v[22:23]
	v_pk_fma_f32 v[32:33], v[32:33], v[164:165], v[142:143]
	v_pk_add_f32 v[142:143], v[12:13], v[28:29]
	v_pk_mov_b32 v[22:23], v[150:151], v[148:149] op_sel:[1,0]
	v_mov_b32_e32 v28, v150
	v_mov_b32_e32 v29, v149
	v_pk_mul_f32 v[140:141], v[140:141], s[8:9] op_sel_hi:[1,0]
	v_pk_add_f32 v[22:23], v[22:23], v[28:29]
	v_pk_fma_f32 v[34:35], v[34:35], v[162:163], v[140:141]
	v_pk_add_f32 v[140:141], v[14:15], v[30:31]
	v_add_f32_e32 v20, v20, v21
	v_pk_add_f32 v[22:23], v[22:23], v[22:23] op_sel_hi:[0,1]
	v_add_f32_e32 v21, 0, v20
	v_add_f32_e32 v29, v142, v143
	v_add_f32_e32 v31, v140, v141
	v_mov_b32_e32 v28, v18
	v_mov_b32_e32 v30, v19
	v_mov_b32_e32 v22, v16
	v_mov_b32_e32 v20, v17
	v_pk_add_f32 v[28:29], v[28:29], v[30:31]
	v_pk_add_f32 v[20:21], v[22:23], v[20:21]
	s_waitcnt lgkmcnt(0)
	s_barrier
	v_pk_add_f32 v[20:21], v[28:29], v[20:21]
	s_nop 0
	v_add_f32_e32 v20, v20, v21
	ds_bpermute_b32 v21, v169, v20
	s_waitcnt lgkmcnt(0)
	v_add_f32_e32 v20, v20, v21
	ds_bpermute_b32 v21, v168, v20
	s_waitcnt lgkmcnt(0)
	v_add_f32_e32 v20, v20, v21
	v_fmamk_f32 v22, v20, 0xbc800000, v153
	v_fmamk_f32 v28, v20, 0xbc800000, v155
	v_fmamk_f32 v21, v20, 0xbc800000, v152
	v_fmamk_f32 v23, v20, 0xbc800000, v154
	v_mul_f32_e32 v28, v28, v28
	v_mul_f32_e32 v22, v22, v22
	v_fmac_f32_e32 v28, v23, v23
	v_fmac_f32_e32 v22, v21, v21
	v_fmamk_f32 v23, v20, 0xbc800000, v149
	v_fmamk_f32 v29, v20, 0xbc800000, v151
	v_add_f32_e32 v21, v28, v22
	v_fmamk_f32 v22, v20, 0xbc800000, v148
	v_fmamk_f32 v28, v20, 0xbc800000, v150
	v_mul_f32_e32 v29, v29, v29
	v_mul_f32_e32 v23, v23, v23
	v_fmac_f32_e32 v29, v28, v28
	v_fmac_f32_e32 v23, v22, v22
	v_add_f32_e32 v22, v29, v23
	v_fmamk_f32 v23, v20, 0xbc800000, v141
	v_fmamk_f32 v29, v20, 0xbc800000, v143
	v_add_f32_e32 v21, v21, v22
	v_fmamk_f32 v22, v20, 0xbc800000, v140
	v_fmamk_f32 v28, v20, 0xbc800000, v142
	v_mul_f32_e32 v29, v29, v29
	v_mul_f32_e32 v23, v23, v23
	v_fmac_f32_e32 v29, v28, v28
	v_fmac_f32_e32 v23, v22, v22
	v_add_f32_e32 v22, v29, v23
	v_fmamk_f32 v23, v20, 0xbc800000, v17
	v_fmamk_f32 v29, v20, 0xbc800000, v19
	v_add_f32_e32 v21, v22, v21
	v_fmamk_f32 v22, v20, 0xbc800000, v16
	v_fmamk_f32 v28, v20, 0xbc800000, v18
	v_mul_f32_e32 v29, v29, v29
	v_mul_f32_e32 v23, v23, v23
	v_fmac_f32_e32 v29, v28, v28
	v_fmac_f32_e32 v23, v22, v22
	v_add_f32_e32 v22, v29, v23
	v_add_f32_e32 v21, v22, v21
	ds_bpermute_b32 v22, v169, v21
	s_waitcnt lgkmcnt(0)
	v_add_f32_e32 v21, v21, v22
	ds_bpermute_b32 v22, v168, v21
	s_and_saveexec_b64 s[8:9], vcc
	s_cbranch_execz .LBB0_853
	s_lshl_b32 s3, s24, 11
	s_add_i32 s3, s11, s3
	v_mul_f32_e32 v20, 0x3c800000, v20
	s_waitcnt lgkmcnt(0)
	v_add_f32_e32 v21, v21, v22
	v_lshl_add_u32 v22, v178, 5, s3
	ds_write_b64 v22, v[20:21]

.LBB0_891:
	s_or_b64 exec, exec, s[10:11]
	v_readlane_b32 s8, v255, 28
	v_readlane_b32 s9, v255, 29
	s_cmp_lg_u32 s8, 3
	s_mov_b32 s15, s1
	s_cselect_b64 s[12:13], -1, 0
	s_lshl_b64 s[8:9], s[14:15], 12
	v_readlane_b32 s20, v251, 32
	v_readlane_b32 s21, v251, 33
	s_add_u32 s10, s20, s8
	v_readlane_b32 s22, v251, 34
	s_addc_u32 s11, s21, s9
	v_readlane_b32 s23, v251, 35
	s_add_u32 s20, s22, s8
	s_addc_u32 s21, s23, s9
	v_lshlrev_b64 v[4:5], 2, v[160:161]
	s_waitcnt lgkmcnt(0)
	s_barrier
	v_lshl_add_u64 v[60:61], s[10:11], 0, v[4:5]
	v_lshl_add_u64 v[62:63], s[20:21], 0, v[4:5]
	s_waitcnt lgkmcnt(0)
	v_cmp_ne_u32_e32 vcc, 0, v3
	global_load_dwordx4 v[0:3], v[60:61], off
	global_load_dwordx4 v[4:7], v[62:63], off
	global_load_dwordx4 v[180:183], v[60:61], off offset:64
	global_load_dwordx4 v[184:187], v[62:63], off offset:64
	global_load_dwordx4 v[188:191], v[60:61], off offset:512
	global_load_dwordx4 v[192:195], v[62:63], off offset:512
	global_load_dwordx4 v[196:199], v[60:61], off offset:576
	global_load_dwordx4 v[200:203], v[62:63], off offset:576
	v_and_b32_e32 v40, 15, v178
	v_or_b32_e32 v168, s30, v40
	v_lshl_add_u32 v169, v168, 3, 0
	ds_read_b64 v[46:47], v169 offset:8192
	v_readlane_b32 s10, v253, 44
	v_readlane_b32 s11, v253, 45
	v_readlane_b32 s3, v254, 17
	s_or_b64 s[8:9], vcc, s[6:7]
	s_waitcnt lgkmcnt(0)
	v_sub_f32_e32 v9, v155, v46
	v_sub_f32_e32 v8, v154, v46
	v_sub_f32_e32 v11, v153, v46
	v_sub_f32_e32 v10, v152, v46
	v_pk_mul_f32 v[10:11], v[46:47], v[10:11] op_sel:[1,0]
	v_pk_mul_f32 v[8:9], v[46:47], v[8:9] op_sel:[1,0]
	s_or_b64 s[20:21], s[12:13], s[10:11]
	v_add_u32_e32 v76, s3, v168
	s_mov_b64 s[10:11], 0
	s_and_b64 vcc, exec, s[20:21]
	v_ashrrev_i32_e32 v77, 31, v76
	v_readlane_b32 s24, v251, 36
	v_readlane_b32 s25, v251, 37
	v_readlane_b32 s26, v251, 38
	v_readlane_b32 s27, v251, 39
	s_waitcnt vmcnt(0)
	v_pk_fma_f32 v[8:9], v[0:1], v[8:9], v[4:5]
	v_pk_fma_f32 v[10:11], v[2:3], v[10:11], v[6:7]
	v_cndmask_b32_e64 v9, v9, v232, s[8:9]
	v_cndmask_b32_e64 v11, v11, v232, s[8:9]
	v_cndmask_b32_e64 v10, v10, v232, s[8:9]
	v_cndmask_b32_e64 v8, v8, v232, s[8:9]
	s_cbranch_vccnz .LBB0_893
	v_readlane_b32 s36, v251, 32
	v_lshlrev_b64 v[12:13], 12, v[76:77]
	v_readlane_b32 s40, v251, 36
	v_readlane_b32 s41, v251, 37
	s_mov_b64 s[10:11], s[40:41]
	v_readlane_b32 s37, v251, 33
	v_lshl_add_u64 v[12:13], s[40:41], 0, v[12:13]
	v_lshl_add_u64 v[12:13], v[160:161], 2, v[12:13]
	v_readlane_b32 s38, v251, 34
	v_readlane_b32 s39, v251, 35
	v_readlane_b32 s42, v251, 38
	v_readlane_b32 s43, v251, 39
	global_store_dwordx4 v[12:13], v[8:11], off

.LBB0_915:
	v_mov_b32_e32 v0, v180
	v_mov_b32_e32 v1, v181
	v_mov_b32_e32 v2, v182
	v_mov_b32_e32 v3, v183
	v_mov_b32_e32 v4, v184
	v_mov_b32_e32 v5, v185
	v_mov_b32_e32 v6, v186
	v_mov_b32_e32 v7, v187
	v_mov_b32_e32 v158, v47
	v_mov_b32_e32 v159, v47
	v_sub_f32_e32 v9, v151, v46
	v_sub_f32_e32 v8, v150, v46
	v_sub_f32_e32 v11, v149, v46
	v_sub_f32_e32 v10, v148, v46
	v_mov_b32_e32 v12, v47
	v_mov_b32_e32 v13, v47
	v_pk_mul_f32 v[10:11], v[12:13], v[10:11]
	v_pk_mul_f32 v[8:9], v[158:159], v[8:9]
	s_and_b64 vcc, exec, s[12:13]
	s_mov_b64 s[20:21], 0
	v_pk_fma_f32 v[8:9], v[8:9], v[0:1], v[4:5]
	v_pk_fma_f32 v[10:11], v[10:11], v[2:3], v[6:7]
	v_cndmask_b32_e64 v9, v9, v232, s[8:9]
	v_cndmask_b32_e64 v11, v11, v232, s[8:9]
	v_cndmask_b32_e64 v10, v10, v232, s[8:9]
	v_cndmask_b32_e64 v8, v8, v232, s[8:9]
	s_cbranch_vccnz .LBB0_917
	v_readlane_b32 s20, v251, 32
	v_lshlrev_b64 v[12:13], 12, v[76:77]
	v_readlane_b32 s24, v251, 36
	v_readlane_b32 s25, v251, 37
	v_readlane_b32 s21, v251, 33
	s_mov_b64 s[20:21], s[24:25]
	v_lshl_add_u64 v[12:13], s[24:25], 0, v[12:13]
	v_lshl_add_u64 v[12:13], v[160:161], 2, v[12:13]
	v_readlane_b32 s22, v251, 34
	v_readlane_b32 s23, v251, 35
	v_readlane_b32 s26, v251, 38
	v_readlane_b32 s27, v251, 39
	global_store_dwordx4 v[12:13], v[8:11], off offset:64

.LBB0_939:
	v_mov_b32_e32 v0, v188
	v_mov_b32_e32 v1, v189
	v_mov_b32_e32 v2, v190
	v_mov_b32_e32 v3, v191
	v_mov_b32_e32 v4, v192
	v_mov_b32_e32 v5, v193
	v_mov_b32_e32 v6, v194
	v_mov_b32_e32 v7, v195
	v_sub_f32_e32 v9, v143, v46
	v_sub_f32_e32 v8, v142, v46
	v_sub_f32_e32 v11, v141, v46
	v_sub_f32_e32 v10, v140, v46
	v_mov_b32_e32 v12, v47
	v_mov_b32_e32 v13, v47
	v_pk_mul_f32 v[10:11], v[12:13], v[10:11]
	v_pk_mul_f32 v[8:9], v[158:159], v[8:9]
	s_and_b64 vcc, exec, s[12:13]
	s_mov_b64 s[20:21], 0
	v_pk_fma_f32 v[8:9], v[8:9], v[0:1], v[4:5]
	v_pk_fma_f32 v[10:11], v[10:11], v[2:3], v[6:7]
	v_cndmask_b32_e64 v9, v9, v232, s[8:9]
	v_cndmask_b32_e64 v11, v11, v232, s[8:9]
	v_cndmask_b32_e64 v10, v10, v232, s[8:9]
	v_cndmask_b32_e64 v8, v8, v232, s[8:9]
	s_cbranch_vccnz .LBB0_941
	v_readlane_b32 s20, v251, 32
	v_lshlrev_b64 v[12:13], 12, v[76:77]
	v_readlane_b32 s24, v251, 36
	v_readlane_b32 s25, v251, 37
	v_readlane_b32 s21, v251, 33
	s_mov_b64 s[20:21], s[24:25]
	v_lshl_add_u64 v[12:13], s[24:25], 0, v[12:13]
	v_lshl_add_u64 v[12:13], v[160:161], 2, v[12:13]
	v_readlane_b32 s22, v251, 34
	v_readlane_b32 s23, v251, 35
	v_readlane_b32 s26, v251, 38
	v_readlane_b32 s27, v251, 39
	global_store_dwordx4 v[12:13], v[8:11], off offset:512

.LBB0_963:
	v_mov_b32_e32 v0, v196
	v_mov_b32_e32 v1, v197
	v_mov_b32_e32 v2, v198
	v_mov_b32_e32 v3, v199
	v_mov_b32_e32 v4, v200
	v_mov_b32_e32 v5, v201
	v_mov_b32_e32 v6, v202
	v_mov_b32_e32 v7, v203
	v_sub_f32_e32 v9, v19, v46
	v_sub_f32_e32 v8, v18, v46
	v_sub_f32_e32 v11, v17, v46
	v_sub_f32_e32 v10, v16, v46
	v_mov_b32_e32 v46, v47
	v_pk_mul_f32 v[10:11], v[46:47], v[10:11]
	v_pk_mul_f32 v[8:9], v[158:159], v[8:9]
	s_and_b64 vcc, exec, s[12:13]
	s_mov_b64 s[20:21], 0
	v_pk_fma_f32 v[8:9], v[8:9], v[0:1], v[4:5]
	v_pk_fma_f32 v[10:11], v[10:11], v[2:3], v[6:7]
	v_cndmask_b32_e64 v9, v9, v232, s[8:9]
	v_cndmask_b32_e64 v11, v11, v232, s[8:9]
	v_cndmask_b32_e64 v10, v10, v232, s[8:9]
	v_cndmask_b32_e64 v8, v8, v232, s[8:9]
	s_cbranch_vccnz .LBB0_965
	v_readlane_b32 s20, v251, 32
	v_lshlrev_b64 v[12:13], 12, v[76:77]
	v_readlane_b32 s24, v251, 36
	v_readlane_b32 s25, v251, 37
	v_readlane_b32 s21, v251, 33
	s_mov_b64 s[20:21], s[24:25]
	v_lshl_add_u64 v[12:13], s[24:25], 0, v[12:13]
	v_lshl_add_u64 v[12:13], v[160:161], 2, v[12:13]
	v_readlane_b32 s22, v251, 34
	v_readlane_b32 s23, v251, 35
	v_readlane_b32 s26, v251, 38
	v_readlane_b32 s27, v251, 39
	global_store_dwordx4 v[12:13], v[8:11], off offset:576

.LBB0_1003:
	v_lshl_add_u64 v[20:21], v[160:161], 2, s[18:19]
	global_load_dwordx4 v[196:199], v[20:21], off
	global_load_dwordx4 v[200:203], v[20:21], off offset:64
	global_load_dwordx4 v[204:207], v[20:21], off offset:512
	global_load_dwordx4 v[208:211], v[20:21], off offset:576
	s_mov_b32 s8, 0x3a800000
	s_lshl_b32 s10, s23, 5
	v_readlane_b32 s3, v254, 17
	s_add_i32 s3, s3, s10
	s_lshl_b32 s11, s5, 2
	v_cmp_gt_u32_e32 vcc, 16, v178
	s_waitcnt vmcnt(0)
	v_pk_mul_f32 v[174:175], v[198:199], s[8:9] op_sel_hi:[1,0]
	v_pk_mul_f32 v[176:177], v[196:197], s[8:9] op_sel_hi:[1,0]
	v_pk_mul_f32 v[170:171], v[202:203], s[8:9] op_sel_hi:[1,0]
	v_pk_mul_f32 v[172:173], v[200:201], s[8:9] op_sel_hi:[1,0]
	v_pk_mul_f32 v[166:167], v[206:207], s[8:9] op_sel_hi:[1,0]
	v_pk_mul_f32 v[168:169], v[204:205], s[8:9] op_sel_hi:[1,0]
	v_mbcnt_lo_u32_b32 v30, -1, 0
	v_mbcnt_hi_u32_b32 v30, -1, v30
	v_pk_mul_f32 v[164:165], v[208:209], s[8:9] op_sel_hi:[1,0]
	v_pk_mul_f32 v[162:163], v[210:211], s[8:9] op_sel_hi:[1,0]
	v_ashrrev_i32_e32 v31, 5, v30
	v_add_u32_e32 v16, s3, v31
	v_and_b32_e32 v180, 31, v30
	v_ashrrev_i32_e32 v17, 31, v16
	v_readlane_b32 s8, v253, 47
	v_lshlrev_b64 v[16:17], 11, v[16:17]
	v_readlane_b32 s9, v253, 48
	s_lshl_b32 s3, s23, 14
	v_bitop3_b32 v18, v31, v180, 15 bitop3:0x6c
	v_lshl_add_u64 v[16:17], s[8:9], 0, v[16:17]
	s_add_i32 s3, s3, 0
	v_lshlrev_b32_e32 v230, 4, v18
	v_lshl_add_u64 v[18:19], v[16:17], 0, v[230:231]
	s_mov_b32 m0, s3
	s_mov_b64 s[8:9], 0x1000
	global_load_lds_dwordx4 v[18:19], off
	v_lshl_add_u64 v[18:19], v[16:17], 0, s[8:9]
	v_add_u32_e32 v16, 2, v31
	v_bitop3_b32 v16, v16, v180, 15 bitop3:0x6c
	v_lshlrev_b32_e32 v16, 4, v16
	v_mov_b32_e32 v17, v231
	s_add_i32 m0, s3, 0x400
	v_lshl_add_u64 v[20:21], v[18:19], 0, v[16:17]
	global_load_lds_dwordx4 v[20:21], off
	v_lshl_add_u64 v[20:21], v[18:19], 0, s[8:9]
	v_add_u32_e32 v18, 4, v31
	v_bitop3_b32 v18, v18, v180, 15 bitop3:0x6c
	v_lshlrev_b32_e32 v18, 4, v18
	v_mov_b32_e32 v19, v231
	s_add_i32 m0, s3, 0x800
	v_lshl_add_u64 v[22:23], v[20:21], 0, v[18:19]
	global_load_lds_dwordx4 v[22:23], off
	v_lshl_add_u64 v[22:23], v[20:21], 0, s[8:9]
	v_add_u32_e32 v20, 6, v31
	v_bitop3_b32 v20, v20, v180, 15 bitop3:0x6c
	v_lshlrev_b32_e32 v20, 4, v20
	v_mov_b32_e32 v21, v231
	s_add_i32 m0, s3, 0xc00
	v_lshl_add_u64 v[24:25], v[22:23], 0, v[20:21]
	global_load_lds_dwordx4 v[24:25], off
	v_lshl_add_u64 v[24:25], v[22:23], 0, s[8:9]
	v_xor_b32_e32 v22, 0x80, v230
	v_mov_b32_e32 v23, v231
	s_add_i32 m0, s3, 0x1000
	v_lshl_add_u64 v[26:27], v[24:25], 0, v[22:23]
	global_load_lds_dwordx4 v[26:27], off
	v_lshl_add_u64 v[26:27], v[24:25], 0, s[8:9]
	v_add_u32_e32 v24, 10, v31
	v_bitop3_b32 v24, v24, v180, 15 bitop3:0x6c
	v_lshlrev_b32_e32 v24, 4, v24
	v_mov_b32_e32 v25, v231
	s_add_i32 m0, s3, 0x1400
	v_lshl_add_u64 v[28:29], v[26:27], 0, v[24:25]
	global_load_lds_dwordx4 v[28:29], off
	v_add_u32_e32 v28, 12, v31
	v_lshl_add_u64 v[26:27], v[26:27], 0, s[8:9]
	v_bitop3_b32 v28, v28, v180, 15 bitop3:0x6c
	v_lshlrev_b32_e32 v28, 4, v28
	v_mov_b32_e32 v29, v231
	v_add_u32_e32 v181, 14, v31
	v_lshl_add_u64 v[182:183], v[26:27], 0, v[28:29]
	s_add_i32 m0, s3, 0x1800
	v_lshl_add_u64 v[26:27], v[26:27], 0, s[8:9]
	v_bitop3_b32 v180, v181, v180, 15 bitop3:0x6c
	global_load_lds_dwordx4 v[182:183], off
	v_lshlrev_b32_e32 v180, 4, v180
	v_mov_b32_e32 v181, v231
	v_lshl_add_u64 v[182:183], v[26:27], 0, v[180:181]
	s_add_i32 m0, s3, 0x1c00
	v_lshl_add_u64 v[26:27], v[26:27], 0, s[8:9]
	global_load_lds_dwordx4 v[182:183], off
	s_add_i32 m0, s3, 0x2000
	v_lshl_add_u64 v[182:183], v[26:27], 0, v[230:231]
	v_lshl_add_u64 v[26:27], v[26:27], 0, s[8:9]
	global_load_lds_dwordx4 v[182:183], off
	s_add_i32 m0, s3, 0x2400
	v_lshl_add_u64 v[16:17], v[26:27], 0, v[16:17]
	global_load_lds_dwordx4 v[16:17], off
	v_lshl_add_u64 v[16:17], v[26:27], 0, s[8:9]
	s_add_i32 m0, s3, 0x2800
	v_lshl_add_u64 v[18:19], v[16:17], 0, v[18:19]
	v_lshl_add_u64 v[16:17], v[16:17], 0, s[8:9]
	global_load_lds_dwordx4 v[18:19], off
	s_add_i32 m0, s3, 0x2c00
	v_lshl_add_u64 v[18:19], v[16:17], 0, v[20:21]
	v_lshl_add_u64 v[16:17], v[16:17], 0, s[8:9]
	global_load_lds_dwordx4 v[18:19], off
	s_add_i32 m0, s3, 0x3000
	v_lshl_add_u64 v[18:19], v[16:17], 0, v[22:23]
	v_lshl_add_u64 v[16:17], v[16:17], 0, s[8:9]
	global_load_lds_dwordx4 v[18:19], off
	s_add_i32 m0, s3, 0x3400
	v_lshl_add_u64 v[18:19], v[16:17], 0, v[24:25]
	v_lshl_add_u64 v[16:17], v[16:17], 0, s[8:9]
	global_load_lds_dwordx4 v[18:19], off
	s_add_i32 m0, s3, 0x3800
	v_lshl_add_u64 v[18:19], v[16:17], 0, v[28:29]
	v_lshl_add_u64 v[16:17], v[16:17], 0, s[8:9]
	global_load_lds_dwordx4 v[18:19], off
	s_add_i32 m0, s3, 0x3c00
	v_lshl_add_u64 v[18:19], v[16:17], 0, v[180:181]
	v_lshl_add_u64 v[16:17], v[16:17], 0, s[8:9]
	global_load_lds_dwordx4 v[18:19], off
	v_lshrrev_b32_e32 v18, 1, v30
	v_lshlrev_b32_e32 v17, 9, v30
	v_and_b32_e32 v17, 0x200, v17
	v_and_b32_e32 v18, 8, v18
	v_add_u32_e32 v28, s11, v31
	v_and_b32_e32 v16, 15, v30
	v_add3_u32 v183, 0, v17, v18
	v_add_u32_e32 v17, 16, v28
	v_bitop3_b32 v17, v17, v30, 15 bitop3:0x78
	s_lshl_b32 s3, s22, 15
	v_lshlrev_b32_e32 v16, 9, v16
	v_lshlrev_b32_e32 v180, 4, v17
	v_or_b32_e32 v184, s3, v16
	v_mov_b32_e32 v17, s3
	s_movk_i32 s3, 0x9c00
	v_bitop3_b32 v16, v16, s3, v17 bitop3:0xc8
	v_add_u32_e32 v181, v183, v16
	v_bitop3_b32 v16, v28, v30, 15 bitop3:0x78
	v_lshlrev_b32_e32 v182, 4, v16
	s_waitcnt vmcnt(0)
	s_barrier
	v_add_u32_e32 v185, v181, v182
	ds_read_b64 v[16:17], v185
	s_mov_b32 s8, 0x3fd744fd
	s_lshl_b32 s3, s5, 3
	s_add_i32 s12, s3, 0
	s_waitcnt lgkmcnt(0)
	v_cvt_f32_f16_e32 v18, v16
	v_cvt_f32_f16_sdwa v19, v16 dst_sel:DWORD dst_unused:UNUSED_PAD src0_sel:WORD_1
	v_cvt_f32_f16_e32 v16, v17
	v_cvt_f32_f16_sdwa v17, v17 dst_sel:DWORD dst_unused:UNUSED_PAD src0_sel:WORD_1
	v_pk_mul_f32 v[20:21], v[18:19], s[8:9] op_sel_hi:[1,0]
	v_pk_mul_f32 v[16:17], v[16:17], s[8:9] op_sel_hi:[1,0]
	s_nop 0
	v_pk_fma_f32 v[18:19], v[158:159], v[174:175], v[16:17]
	v_pk_fma_f32 v[16:17], v[156:157], v[176:177], v[20:21]
	v_add_u32_e32 v20, 2, v28
	v_bitop3_b32 v20, v20, v30, 15 bitop3:0x78
	v_lshlrev_b32_e32 v156, 4, v20
	v_add_u32_e32 v157, v181, v156
	ds_read_b64 v[20:21], v157
	s_waitcnt lgkmcnt(0)
	v_cvt_f32_f16_e32 v22, v20
	v_cvt_f32_f16_sdwa v23, v20 dst_sel:DWORD dst_unused:UNUSED_PAD src0_sel:WORD_1
	v_cvt_f32_f16_e32 v20, v21
	v_cvt_f32_f16_sdwa v21, v21 dst_sel:DWORD dst_unused:UNUSED_PAD src0_sel:WORD_1
	v_pk_mul_f32 v[22:23], v[22:23], s[8:9] op_sel_hi:[1,0]
	s_nop 0
	v_pk_fma_f32 v[24:25], v[152:153], v[172:173], v[22:23]
	v_pk_mul_f32 v[20:21], v[20:21], s[8:9] op_sel_hi:[1,0]
	v_add_u32_e32 v153, v181, v180
	v_pk_fma_f32 v[26:27], v[154:155], v[170:171], v[20:21]
	ds_read_b64 v[20:21], v153
	s_waitcnt lgkmcnt(0)
	v_cvt_f32_f16_e32 v22, v20
	v_cvt_f32_f16_sdwa v23, v20 dst_sel:DWORD dst_unused:UNUSED_PAD src0_sel:WORD_1
	v_cvt_f32_f16_e32 v20, v21
	v_cvt_f32_f16_sdwa v21, v21 dst_sel:DWORD dst_unused:UNUSED_PAD src0_sel:WORD_1
	v_pk_mul_f32 v[22:23], v[22:23], s[8:9] op_sel_hi:[1,0]
	s_nop 0
	v_pk_fma_f32 v[148:149], v[148:149], v[168:169], v[22:23]
	v_pk_mul_f32 v[20:21], v[20:21], s[8:9] op_sel_hi:[1,0]
	s_nop 0
	v_pk_fma_f32 v[150:151], v[150:151], v[166:167], v[20:21]
	v_add_u32_e32 v20, 18, v28
	v_bitop3_b32 v20, v20, v30, 15 bitop3:0x78
	v_lshlrev_b32_e32 v152, 4, v20
	v_add_u32_e32 v154, v181, v152
	ds_read_b64 v[20:21], v154
	s_waitcnt lgkmcnt(0)
	v_cvt_f32_f16_e32 v22, v20
	v_cvt_f32_f16_sdwa v23, v20 dst_sel:DWORD dst_unused:UNUSED_PAD src0_sel:WORD_1
	v_cvt_f32_f16_e32 v20, v21
	v_cvt_f32_f16_sdwa v21, v21 dst_sel:DWORD dst_unused:UNUSED_PAD src0_sel:WORD_1
	v_pk_mul_f32 v[22:23], v[22:23], s[8:9] op_sel_hi:[1,0]
	s_nop 0
	v_pk_fma_f32 v[144:145], v[144:145], v[164:165], v[22:23]
	v_pk_mul_f32 v[20:21], v[20:21], s[8:9] op_sel_hi:[1,0]
	s_nop 0
	v_pk_fma_f32 v[146:147], v[146:147], v[162:163], v[20:21]
	s_nop 0
	ds_read_b64 v[20:21], v185 offset:8192
	s_waitcnt lgkmcnt(0)
	v_cvt_f32_f16_e32 v22, v20
	v_cvt_f32_f16_sdwa v23, v20 dst_sel:DWORD dst_unused:UNUSED_PAD src0_sel:WORD_1
	v_cvt_f32_f16_e32 v20, v21
	v_cvt_f32_f16_sdwa v21, v21 dst_sel:DWORD dst_unused:UNUSED_PAD src0_sel:WORD_1
	v_pk_mul_f32 v[28:29], v[22:23], s[8:9] op_sel_hi:[1,0]
	v_pk_mul_f32 v[20:21], v[20:21], s[8:9] op_sel_hi:[1,0]
	s_nop 0
	v_pk_fma_f32 v[22:23], v[142:143], v[174:175], v[20:21]
	v_pk_fma_f32 v[20:21], v[140:141], v[176:177], v[28:29]
	ds_read_b64 v[28:29], v157 offset:8192
	v_pk_add_f32 v[142:143], v[0:1], v[24:25]
	v_lshlrev_b32_e32 v24, 2, v178
	s_waitcnt lgkmcnt(0)
	v_cvt_f32_f16_e32 v30, v28
	v_cvt_f32_f16_sdwa v31, v28 dst_sel:DWORD dst_unused:UNUSED_PAD src0_sel:WORD_1
	v_cvt_f32_f16_e32 v28, v29
	v_cvt_f32_f16_sdwa v29, v29 dst_sel:DWORD dst_unused:UNUSED_PAD src0_sel:WORD_1
	v_pk_mul_f32 v[140:141], v[30:31], s[8:9] op_sel_hi:[1,0]
	v_pk_mul_f32 v[28:29], v[28:29], s[8:9] op_sel_hi:[1,0]
	s_nop 0
	v_pk_fma_f32 v[30:31], v[138:139], v[170:171], v[28:29]
	v_pk_fma_f32 v[28:29], v[136:137], v[172:173], v[140:141]
	ds_read_b64 v[136:137], v153 offset:8192
	v_add_u32_e32 v140, 0x10000, v181
	s_waitcnt lgkmcnt(0)
	v_cvt_f32_f16_e32 v138, v136
	v_cvt_f32_f16_sdwa v139, v136 dst_sel:DWORD dst_unused:UNUSED_PAD src0_sel:WORD_1
	v_cvt_f32_f16_e32 v136, v137
	v_cvt_f32_f16_sdwa v137, v137 dst_sel:DWORD dst_unused:UNUSED_PAD src0_sel:WORD_1
	v_pk_mul_f32 v[138:139], v[138:139], s[8:9] op_sel_hi:[1,0]
	s_nop 0
	v_pk_fma_f32 v[132:133], v[132:133], v[168:169], v[138:139]
	v_pk_mul_f32 v[136:137], v[136:137], s[8:9] op_sel_hi:[1,0]
	s_nop 0
	v_pk_fma_f32 v[134:135], v[134:135], v[166:167], v[136:137]
	ds_read_b64 v[136:137], v154 offset:8192
	s_waitcnt lgkmcnt(0)
	v_cvt_f32_f16_e32 v138, v136
	v_cvt_f32_f16_sdwa v139, v136 dst_sel:DWORD dst_unused:UNUSED_PAD src0_sel:WORD_1
	v_cvt_f32_f16_e32 v136, v137
	v_cvt_f32_f16_sdwa v137, v137 dst_sel:DWORD dst_unused:UNUSED_PAD src0_sel:WORD_1
	v_pk_mul_f32 v[138:139], v[138:139], s[8:9] op_sel_hi:[1,0]
	s_nop 0
	v_pk_fma_f32 v[128:129], v[128:129], v[164:165], v[138:139]
	v_pk_mul_f32 v[136:137], v[136:137], s[8:9] op_sel_hi:[1,0]
	s_nop 0
	v_pk_fma_f32 v[130:131], v[130:131], v[162:163], v[136:137]
	s_nop 0
	ds_read_b64 v[136:137], v185 offset:16384
	s_waitcnt lgkmcnt(0)
	v_cvt_f32_f16_e32 v138, v136
	v_cvt_f32_f16_sdwa v139, v136 dst_sel:DWORD dst_unused:UNUSED_PAD src0_sel:WORD_1
	v_cvt_f32_f16_e32 v136, v137
	v_cvt_f32_f16_sdwa v137, v137 dst_sel:DWORD dst_unused:UNUSED_PAD src0_sel:WORD_1
	v_pk_mul_f32 v[138:139], v[138:139], s[8:9] op_sel_hi:[1,0]
	s_nop 0
	v_pk_fma_f32 v[124:125], v[124:125], v[176:177], v[138:139]
	v_pk_mul_f32 v[136:137], v[136:137], s[8:9] op_sel_hi:[1,0]
	s_nop 0
	v_pk_fma_f32 v[126:127], v[126:127], v[174:175], v[136:137]
	ds_read_b64 v[136:137], v157 offset:16384
	s_waitcnt lgkmcnt(0)
	v_cvt_f32_f16_e32 v138, v136
	v_cvt_f32_f16_sdwa v139, v136 dst_sel:DWORD dst_unused:UNUSED_PAD src0_sel:WORD_1
	v_cvt_f32_f16_e32 v136, v137
	v_cvt_f32_f16_sdwa v137, v137 dst_sel:DWORD dst_unused:UNUSED_PAD src0_sel:WORD_1
	v_pk_mul_f32 v[138:139], v[138:139], s[8:9] op_sel_hi:[1,0]
	s_nop 0
	v_pk_fma_f32 v[120:121], v[120:121], v[172:173], v[138:139]
	v_pk_mul_f32 v[136:137], v[136:137], s[8:9] op_sel_hi:[1,0]
	s_nop 0
	v_pk_fma_f32 v[122:123], v[122:123], v[170:171], v[136:137]
	ds_read_b64 v[136:137], v153 offset:16384
	s_waitcnt lgkmcnt(0)
	v_cvt_f32_f16_e32 v138, v136
	v_cvt_f32_f16_sdwa v139, v136 dst_sel:DWORD dst_unused:UNUSED_PAD src0_sel:WORD_1
	v_cvt_f32_f16_e32 v136, v137
	v_cvt_f32_f16_sdwa v137, v137 dst_sel:DWORD dst_unused:UNUSED_PAD src0_sel:WORD_1
	v_pk_mul_f32 v[138:139], v[138:139], s[8:9] op_sel_hi:[1,0]
	s_nop 0
	v_pk_fma_f32 v[116:117], v[116:117], v[168:169], v[138:139]
	v_pk_mul_f32 v[136:137], v[136:137], s[8:9] op_sel_hi:[1,0]
	s_nop 0
	v_pk_fma_f32 v[118:119], v[118:119], v[166:167], v[136:137]
	ds_read_b64 v[136:137], v154 offset:16384
	s_waitcnt lgkmcnt(0)
	v_cvt_f32_f16_e32 v138, v136
	v_cvt_f32_f16_sdwa v139, v136 dst_sel:DWORD dst_unused:UNUSED_PAD src0_sel:WORD_1
	v_cvt_f32_f16_e32 v136, v137
	v_cvt_f32_f16_sdwa v137, v137 dst_sel:DWORD dst_unused:UNUSED_PAD src0_sel:WORD_1
	v_pk_mul_f32 v[138:139], v[138:139], s[8:9] op_sel_hi:[1,0]
	s_nop 0
	v_pk_fma_f32 v[112:113], v[112:113], v[164:165], v[138:139]
	v_pk_mul_f32 v[136:137], v[136:137], s[8:9] op_sel_hi:[1,0]
	s_nop 0
	v_pk_fma_f32 v[114:115], v[114:115], v[162:163], v[136:137]
	s_nop 0
	ds_read_b64 v[136:137], v185 offset:24576
	s_waitcnt lgkmcnt(0)
	v_cvt_f32_f16_e32 v138, v136
	v_cvt_f32_f16_sdwa v139, v136 dst_sel:DWORD dst_unused:UNUSED_PAD src0_sel:WORD_1
	v_cvt_f32_f16_e32 v136, v137
	v_cvt_f32_f16_sdwa v137, v137 dst_sel:DWORD dst_unused:UNUSED_PAD src0_sel:WORD_1
	v_pk_mul_f32 v[138:139], v[138:139], s[8:9] op_sel_hi:[1,0]
	s_nop 0
	v_pk_fma_f32 v[108:109], v[108:109], v[176:177], v[138:139]
	v_pk_mul_f32 v[136:137], v[136:137], s[8:9] op_sel_hi:[1,0]
	s_nop 0
	v_pk_fma_f32 v[110:111], v[110:111], v[174:175], v[136:137]
	ds_read_b64 v[136:137], v157 offset:24576
	v_xor_b32_e32 v157, 64, v24
	s_waitcnt lgkmcnt(0)
	v_cvt_f32_f16_e32 v138, v136
	v_cvt_f32_f16_sdwa v139, v136 dst_sel:DWORD dst_unused:UNUSED_PAD src0_sel:WORD_1
	v_cvt_f32_f16_e32 v136, v137
	v_cvt_f32_f16_sdwa v137, v137 dst_sel:DWORD dst_unused:UNUSED_PAD src0_sel:WORD_1
	v_pk_mul_f32 v[138:139], v[138:139], s[8:9] op_sel_hi:[1,0]
	s_nop 0
	v_pk_fma_f32 v[104:105], v[104:105], v[172:173], v[138:139]
	v_pk_mul_f32 v[136:137], v[136:137], s[8:9] op_sel_hi:[1,0]
	s_nop 0
	v_pk_fma_f32 v[106:107], v[106:107], v[170:171], v[136:137]
	ds_read_b64 v[136:137], v153 offset:24576
	s_waitcnt lgkmcnt(0)
	v_cvt_f32_f16_e32 v138, v136
	v_cvt_f32_f16_sdwa v139, v136 dst_sel:DWORD dst_unused:UNUSED_PAD src0_sel:WORD_1
	v_cvt_f32_f16_e32 v136, v137
	v_cvt_f32_f16_sdwa v137, v137 dst_sel:DWORD dst_unused:UNUSED_PAD src0_sel:WORD_1
	v_pk_mul_f32 v[138:139], v[138:139], s[8:9] op_sel_hi:[1,0]
	s_nop 0
	v_pk_fma_f32 v[100:101], v[100:101], v[168:169], v[138:139]
	v_pk_mul_f32 v[136:137], v[136:137], s[8:9] op_sel_hi:[1,0]
	s_nop 0
	v_pk_fma_f32 v[102:103], v[102:103], v[166:167], v[136:137]
	ds_read_b64 v[136:137], v154 offset:24576
	v_pk_add_f32 v[154:155], v[4:5], v[16:17]
	v_pk_add_f32 v[16:17], v[10:11], v[146:147]
	s_waitcnt lgkmcnt(0)
	v_cvt_f32_f16_e32 v138, v136
	v_cvt_f32_f16_sdwa v139, v136 dst_sel:DWORD dst_unused:UNUSED_PAD src0_sel:WORD_1
	v_cvt_f32_f16_e32 v136, v137
	v_cvt_f32_f16_sdwa v137, v137 dst_sel:DWORD dst_unused:UNUSED_PAD src0_sel:WORD_1
	v_pk_mul_f32 v[138:139], v[138:139], s[8:9] op_sel_hi:[1,0]
	s_nop 0
	v_pk_fma_f32 v[96:97], v[96:97], v[164:165], v[138:139]
	v_pk_mul_f32 v[136:137], v[136:137], s[8:9] op_sel_hi:[1,0]
	s_nop 0
	v_pk_fma_f32 v[98:99], v[98:99], v[162:163], v[136:137]
	v_add_u32_e32 v136, v140, v182
	ds_read_b64 v[136:137], v136
	s_waitcnt lgkmcnt(0)
	v_cvt_f32_f16_e32 v138, v136
	v_cvt_f32_f16_sdwa v139, v136 dst_sel:DWORD dst_unused:UNUSED_PAD src0_sel:WORD_1
	v_cvt_f32_f16_e32 v136, v137
	v_cvt_f32_f16_sdwa v137, v137 dst_sel:DWORD dst_unused:UNUSED_PAD src0_sel:WORD_1
	v_pk_mul_f32 v[138:139], v[138:139], s[8:9] op_sel_hi:[1,0]
	s_nop 0
	v_pk_fma_f32 v[92:93], v[92:93], v[176:177], v[138:139]
	v_pk_mul_f32 v[136:137], v[136:137], s[8:9] op_sel_hi:[1,0]
	s_nop 0
	v_pk_fma_f32 v[94:95], v[94:95], v[174:175], v[136:137]
	v_add_u32_e32 v136, v140, v156
	ds_read_b64 v[136:137], v136
	s_waitcnt lgkmcnt(0)
	v_cvt_f32_f16_e32 v138, v136
	v_cvt_f32_f16_sdwa v139, v136 dst_sel:DWORD dst_unused:UNUSED_PAD src0_sel:WORD_1
	v_cvt_f32_f16_e32 v136, v137
	v_cvt_f32_f16_sdwa v137, v137 dst_sel:DWORD dst_unused:UNUSED_PAD src0_sel:WORD_1
	v_pk_mul_f32 v[138:139], v[138:139], s[8:9] op_sel_hi:[1,0]
	s_nop 0
	v_pk_fma_f32 v[88:89], v[88:89], v[172:173], v[138:139]
	v_pk_mul_f32 v[136:137], v[136:137], s[8:9] op_sel_hi:[1,0]
	s_nop 0
	v_pk_fma_f32 v[90:91], v[90:91], v[170:171], v[136:137]
	v_add_u32_e32 v136, v140, v180
	ds_read_b64 v[136:137], v136
	s_waitcnt lgkmcnt(0)
	v_cvt_f32_f16_e32 v138, v136
	v_cvt_f32_f16_sdwa v139, v136 dst_sel:DWORD dst_unused:UNUSED_PAD src0_sel:WORD_1
	v_cvt_f32_f16_e32 v136, v137
	v_cvt_f32_f16_sdwa v137, v137 dst_sel:DWORD dst_unused:UNUSED_PAD src0_sel:WORD_1
	v_pk_mul_f32 v[138:139], v[138:139], s[8:9] op_sel_hi:[1,0]
	s_nop 0
	v_pk_fma_f32 v[84:85], v[84:85], v[168:169], v[138:139]
	v_pk_mul_f32 v[136:137], v[136:137], s[8:9] op_sel_hi:[1,0]
	s_nop 0
	v_pk_fma_f32 v[86:87], v[86:87], v[166:167], v[136:137]
	v_add_u32_e32 v136, v140, v152
	ds_read_b64 v[136:137], v136
	s_waitcnt lgkmcnt(0)
	v_cvt_f32_f16_e32 v138, v136
	v_cvt_f32_f16_sdwa v139, v136 dst_sel:DWORD dst_unused:UNUSED_PAD src0_sel:WORD_1
	v_cvt_f32_f16_e32 v136, v137
	v_cvt_f32_f16_sdwa v137, v137 dst_sel:DWORD dst_unused:UNUSED_PAD src0_sel:WORD_1
	v_pk_mul_f32 v[138:139], v[138:139], s[8:9] op_sel_hi:[1,0]
	s_nop 0
	v_pk_fma_f32 v[80:81], v[80:81], v[164:165], v[138:139]
	v_pk_mul_f32 v[136:137], v[136:137], s[8:9] op_sel_hi:[1,0]
	s_nop 0
	v_pk_fma_f32 v[82:83], v[82:83], v[162:163], v[136:137]
	v_add_u32_e32 v136, 0x12000, v184
	v_and_b32_e32 v136, 0xffffbc00, v136
	v_add_u32_e32 v140, v183, v136
	v_add_u32_e32 v136, v140, v182
	ds_read_b64 v[136:137], v136
	s_waitcnt lgkmcnt(0)
	v_cvt_f32_f16_e32 v138, v136
	v_cvt_f32_f16_sdwa v139, v136 dst_sel:DWORD dst_unused:UNUSED_PAD src0_sel:WORD_1
	v_cvt_f32_f16_e32 v136, v137
	v_cvt_f32_f16_sdwa v137, v137 dst_sel:DWORD dst_unused:UNUSED_PAD src0_sel:WORD_1
	v_pk_mul_f32 v[138:139], v[138:139], s[8:9] op_sel_hi:[1,0]
	s_nop 0
	v_pk_fma_f32 v[76:77], v[76:77], v[176:177], v[138:139]
	v_pk_mul_f32 v[136:137], v[136:137], s[8:9] op_sel_hi:[1,0]
	s_nop 0
	v_pk_fma_f32 v[78:79], v[78:79], v[174:175], v[136:137]
	v_add_u32_e32 v136, v140, v156
	ds_read_b64 v[136:137], v136
	s_waitcnt lgkmcnt(0)
	v_cvt_f32_f16_e32 v138, v136
	v_cvt_f32_f16_sdwa v139, v136 dst_sel:DWORD dst_unused:UNUSED_PAD src0_sel:WORD_1
	v_cvt_f32_f16_e32 v136, v137
	v_cvt_f32_f16_sdwa v137, v137 dst_sel:DWORD dst_unused:UNUSED_PAD src0_sel:WORD_1
	v_pk_mul_f32 v[138:139], v[138:139], s[8:9] op_sel_hi:[1,0]
	s_nop 0
	v_pk_fma_f32 v[72:73], v[72:73], v[172:173], v[138:139]
	v_pk_mul_f32 v[136:137], v[136:137], s[8:9] op_sel_hi:[1,0]
	s_nop 0
	v_pk_fma_f32 v[74:75], v[74:75], v[170:171], v[136:137]
	v_add_u32_e32 v136, v140, v180
	ds_read_b64 v[136:137], v136
	s_waitcnt lgkmcnt(0)
	v_cvt_f32_f16_e32 v138, v136
	v_cvt_f32_f16_sdwa v139, v136 dst_sel:DWORD dst_unused:UNUSED_PAD src0_sel:WORD_1
	v_cvt_f32_f16_e32 v136, v137
	v_cvt_f32_f16_sdwa v137, v137 dst_sel:DWORD dst_unused:UNUSED_PAD src0_sel:WORD_1
	v_pk_mul_f32 v[138:139], v[138:139], s[8:9] op_sel_hi:[1,0]
	s_nop 0
	v_pk_fma_f32 v[68:69], v[68:69], v[168:169], v[138:139]
	v_pk_mul_f32 v[136:137], v[136:137], s[8:9] op_sel_hi:[1,0]
	s_nop 0
	v_pk_fma_f32 v[70:71], v[70:71], v[166:167], v[136:137]
	v_add_u32_e32 v136, v140, v152
	ds_read_b64 v[136:137], v136
	v_add_u32_e32 v140, 0x14000, v181
	s_waitcnt lgkmcnt(0)
	v_cvt_f32_f16_e32 v138, v136
	v_cvt_f32_f16_sdwa v139, v136 dst_sel:DWORD dst_unused:UNUSED_PAD src0_sel:WORD_1
	v_cvt_f32_f16_e32 v136, v137
	v_cvt_f32_f16_sdwa v137, v137 dst_sel:DWORD dst_unused:UNUSED_PAD src0_sel:WORD_1
	v_pk_mul_f32 v[138:139], v[138:139], s[8:9] op_sel_hi:[1,0]
	s_nop 0
	v_pk_fma_f32 v[64:65], v[64:65], v[164:165], v[138:139]
	v_pk_mul_f32 v[136:137], v[136:137], s[8:9] op_sel_hi:[1,0]
	s_nop 0
	v_pk_fma_f32 v[66:67], v[66:67], v[162:163], v[136:137]
	v_add_u32_e32 v136, v140, v182
	ds_read_b64 v[136:137], v136
	s_waitcnt lgkmcnt(0)
	v_cvt_f32_f16_e32 v138, v136
	v_cvt_f32_f16_sdwa v139, v136 dst_sel:DWORD dst_unused:UNUSED_PAD src0_sel:WORD_1
	v_cvt_f32_f16_e32 v136, v137
	v_cvt_f32_f16_sdwa v137, v137 dst_sel:DWORD dst_unused:UNUSED_PAD src0_sel:WORD_1
	v_pk_mul_f32 v[138:139], v[138:139], s[8:9] op_sel_hi:[1,0]
	s_nop 0
	v_pk_fma_f32 v[60:61], v[60:61], v[176:177], v[138:139]
	v_pk_mul_f32 v[136:137], v[136:137], s[8:9] op_sel_hi:[1,0]
	s_nop 0
	v_pk_fma_f32 v[62:63], v[62:63], v[174:175], v[136:137]
	v_add_u32_e32 v136, v140, v156
	ds_read_b64 v[136:137], v136
	s_waitcnt lgkmcnt(0)
	v_cvt_f32_f16_e32 v138, v136
	v_cvt_f32_f16_sdwa v139, v136 dst_sel:DWORD dst_unused:UNUSED_PAD src0_sel:WORD_1
	v_cvt_f32_f16_e32 v136, v137
	v_cvt_f32_f16_sdwa v137, v137 dst_sel:DWORD dst_unused:UNUSED_PAD src0_sel:WORD_1
	v_pk_mul_f32 v[138:139], v[138:139], s[8:9] op_sel_hi:[1,0]
	s_nop 0
	v_pk_fma_f32 v[56:57], v[56:57], v[172:173], v[138:139]
	v_pk_mul_f32 v[136:137], v[136:137], s[8:9] op_sel_hi:[1,0]
	s_nop 0
	v_pk_fma_f32 v[58:59], v[58:59], v[170:171], v[136:137]
	v_add_u32_e32 v136, v140, v180
	ds_read_b64 v[136:137], v136
	s_waitcnt lgkmcnt(0)
	v_cvt_f32_f16_e32 v138, v136
	v_cvt_f32_f16_sdwa v139, v136 dst_sel:DWORD dst_unused:UNUSED_PAD src0_sel:WORD_1
	v_cvt_f32_f16_e32 v136, v137
	v_cvt_f32_f16_sdwa v137, v137 dst_sel:DWORD dst_unused:UNUSED_PAD src0_sel:WORD_1
	v_pk_mul_f32 v[138:139], v[138:139], s[8:9] op_sel_hi:[1,0]
	s_nop 0
	v_pk_fma_f32 v[52:53], v[52:53], v[168:169], v[138:139]
	v_pk_mul_f32 v[136:137], v[136:137], s[8:9] op_sel_hi:[1,0]
	s_nop 0
	v_pk_fma_f32 v[54:55], v[54:55], v[166:167], v[136:137]
	v_add_u32_e32 v136, v140, v152
	ds_read_b64 v[136:137], v136
	v_add_u32_e32 v140, 0x16000, v181
	s_waitcnt lgkmcnt(0)
	v_cvt_f32_f16_e32 v138, v136
	v_cvt_f32_f16_sdwa v139, v136 dst_sel:DWORD dst_unused:UNUSED_PAD src0_sel:WORD_1
	v_cvt_f32_f16_e32 v136, v137
	v_cvt_f32_f16_sdwa v137, v137 dst_sel:DWORD dst_unused:UNUSED_PAD src0_sel:WORD_1
	v_pk_mul_f32 v[138:139], v[138:139], s[8:9] op_sel_hi:[1,0]
	s_nop 0
	v_pk_fma_f32 v[48:49], v[48:49], v[164:165], v[138:139]
	v_pk_mul_f32 v[136:137], v[136:137], s[8:9] op_sel_hi:[1,0]
	s_nop 0
	v_pk_fma_f32 v[50:51], v[50:51], v[162:163], v[136:137]
	v_add_u32_e32 v136, v140, v182
	ds_read_b64 v[136:137], v136
	s_waitcnt lgkmcnt(0)
	v_cvt_f32_f16_e32 v138, v136
	v_cvt_f32_f16_sdwa v139, v136 dst_sel:DWORD dst_unused:UNUSED_PAD src0_sel:WORD_1
	v_cvt_f32_f16_e32 v136, v137
	v_cvt_f32_f16_sdwa v137, v137 dst_sel:DWORD dst_unused:UNUSED_PAD src0_sel:WORD_1
	v_pk_mul_f32 v[138:139], v[138:139], s[8:9] op_sel_hi:[1,0]
	s_nop 0
	v_pk_fma_f32 v[44:45], v[44:45], v[176:177], v[138:139]
	v_pk_mul_f32 v[136:137], v[136:137], s[8:9] op_sel_hi:[1,0]
	s_nop 0
	v_pk_fma_f32 v[46:47], v[46:47], v[174:175], v[136:137]
	v_add_u32_e32 v136, v140, v156
	ds_read_b64 v[136:137], v136
	v_xor_b32_e32 v156, 0x80, v24
	s_waitcnt lgkmcnt(0)
	v_cvt_f32_f16_e32 v138, v136
	v_cvt_f32_f16_sdwa v139, v136 dst_sel:DWORD dst_unused:UNUSED_PAD src0_sel:WORD_1
	v_cvt_f32_f16_e32 v136, v137
	v_cvt_f32_f16_sdwa v137, v137 dst_sel:DWORD dst_unused:UNUSED_PAD src0_sel:WORD_1
	v_pk_mul_f32 v[138:139], v[138:139], s[8:9] op_sel_hi:[1,0]
	s_nop 0
	v_pk_fma_f32 v[40:41], v[40:41], v[172:173], v[138:139]
	v_pk_mul_f32 v[136:137], v[136:137], s[8:9] op_sel_hi:[1,0]
	s_nop 0
	v_pk_fma_f32 v[42:43], v[42:43], v[170:171], v[136:137]
	v_add_u32_e32 v136, v140, v180
	ds_read_b64 v[136:137], v136
	s_waitcnt lgkmcnt(0)
	v_cvt_f32_f16_e32 v138, v136
	v_cvt_f32_f16_sdwa v139, v136 dst_sel:DWORD dst_unused:UNUSED_PAD src0_sel:WORD_1
	v_cvt_f32_f16_e32 v136, v137
	v_cvt_f32_f16_sdwa v137, v137 dst_sel:DWORD dst_unused:UNUSED_PAD src0_sel:WORD_1
	v_pk_mul_f32 v[138:139], v[138:139], s[8:9] op_sel_hi:[1,0]
	s_nop 0
	v_pk_fma_f32 v[36:37], v[36:37], v[168:169], v[138:139]
	v_pk_mul_f32 v[136:137], v[136:137], s[8:9] op_sel_hi:[1,0]
	s_nop 0
	v_pk_fma_f32 v[38:39], v[38:39], v[166:167], v[136:137]
	v_add_u32_e32 v136, v140, v152
	ds_read_b64 v[136:137], v136
	v_pk_add_f32 v[152:153], v[6:7], v[18:19]
	v_pk_add_f32 v[140:141], v[2:3], v[26:27]
	v_pk_mov_b32 v[24:25], v[154:155], v[152:153] op_sel:[1,0]
	v_mov_b32_e32 v26, v154
	s_waitcnt lgkmcnt(0)
	v_cvt_f32_f16_e32 v138, v136
	v_cvt_f32_f16_sdwa v139, v136 dst_sel:DWORD dst_unused:UNUSED_PAD src0_sel:WORD_1
	v_cvt_f32_f16_e32 v136, v137
	v_cvt_f32_f16_sdwa v137, v137 dst_sel:DWORD dst_unused:UNUSED_PAD src0_sel:WORD_1
	v_mov_b32_e32 v27, v153
	v_pk_add_f32 v[18:19], v[8:9], v[144:145]
	v_pk_add_f32 v[24:25], v[24:25], v[26:27]
	v_pk_mov_b32 v[26:27], v[142:143], v[140:141] op_sel:[1,0]
	v_mov_b32_e32 v144, v142
	v_mov_b32_e32 v145, v141
	v_pk_mul_f32 v[138:139], v[138:139], s[8:9] op_sel_hi:[1,0]
	v_pk_mul_f32 v[136:137], v[136:137], s[8:9] op_sel_hi:[1,0]
	v_pk_add_f32 v[26:27], v[26:27], v[144:145]
	v_pk_fma_f32 v[34:35], v[34:35], v[162:163], v[136:137]
	v_pk_fma_f32 v[32:33], v[32:33], v[164:165], v[138:139]
	v_pk_add_f32 v[136:137], v[14:15], v[150:151]
	v_pk_add_f32 v[138:139], v[12:13], v[148:149]
	v_add_f32_e32 v24, v24, v25
	v_pk_add_f32 v[26:27], v[26:27], v[26:27] op_sel_hi:[0,1]
	v_add_f32_e32 v25, 0, v24
	v_add_f32_e32 v145, v138, v139
	v_add_f32_e32 v147, v136, v137
	v_mov_b32_e32 v144, v18
	v_mov_b32_e32 v146, v19
	v_mov_b32_e32 v26, v16
	v_mov_b32_e32 v24, v17
	v_pk_add_f32 v[144:145], v[144:145], v[146:147]
	v_pk_add_f32 v[24:25], v[26:27], v[24:25]
	s_waitcnt lgkmcnt(0)
	s_barrier
	v_pk_add_f32 v[24:25], v[144:145], v[24:25]
	s_nop 0
	v_add_f32_e32 v24, v24, v25
	ds_bpermute_b32 v25, v157, v24
	s_waitcnt lgkmcnt(0)
	v_add_f32_e32 v24, v24, v25
	ds_bpermute_b32 v25, v156, v24
	s_waitcnt lgkmcnt(0)
	v_add_f32_e32 v24, v24, v25
	v_fmamk_f32 v26, v24, 0xbc800000, v153
	v_fmamk_f32 v144, v24, 0xbc800000, v155
	v_fmamk_f32 v25, v24, 0xbc800000, v152
	v_fmamk_f32 v27, v24, 0xbc800000, v154
	v_mul_f32_e32 v144, v144, v144
	v_mul_f32_e32 v26, v26, v26
	v_fmac_f32_e32 v144, v27, v27
	v_fmac_f32_e32 v26, v25, v25
	v_fmamk_f32 v27, v24, 0xbc800000, v141
	v_fmamk_f32 v145, v24, 0xbc800000, v143
	v_add_f32_e32 v25, v144, v26
	v_fmamk_f32 v26, v24, 0xbc800000, v140
	v_fmamk_f32 v144, v24, 0xbc800000, v142
	v_mul_f32_e32 v145, v145, v145
	v_mul_f32_e32 v27, v27, v27
	v_fmac_f32_e32 v145, v144, v144
	v_fmac_f32_e32 v27, v26, v26
	v_add_f32_e32 v26, v145, v27
	v_fmamk_f32 v27, v24, 0xbc800000, v137
	v_fmamk_f32 v145, v24, 0xbc800000, v139
	v_add_f32_e32 v25, v25, v26
	v_fmamk_f32 v26, v24, 0xbc800000, v136
	v_fmamk_f32 v144, v24, 0xbc800000, v138
	v_mul_f32_e32 v145, v145, v145
	v_mul_f32_e32 v27, v27, v27
	v_fmac_f32_e32 v145, v144, v144
	v_fmac_f32_e32 v27, v26, v26
	v_add_f32_e32 v26, v145, v27
	v_fmamk_f32 v27, v24, 0xbc800000, v17
	v_fmamk_f32 v145, v24, 0xbc800000, v19
	v_add_f32_e32 v25, v26, v25
	v_fmamk_f32 v26, v24, 0xbc800000, v16
	v_fmamk_f32 v144, v24, 0xbc800000, v18
	v_mul_f32_e32 v145, v145, v145
	v_mul_f32_e32 v27, v27, v27
	v_fmac_f32_e32 v145, v144, v144
	v_fmac_f32_e32 v27, v26, v26
	v_add_f32_e32 v26, v145, v27
	v_add_f32_e32 v25, v26, v25
	ds_bpermute_b32 v26, v157, v25
	s_waitcnt lgkmcnt(0)
	v_add_f32_e32 v25, v25, v26
	ds_bpermute_b32 v26, v156, v25
	s_and_saveexec_b64 s[8:9], vcc
	s_cbranch_execz .LBB0_1005
	s_lshl_b32 s3, s22, 11
	s_add_i32 s3, s12, s3
	v_mul_f32_e32 v24, 0x3c800000, v24
	s_waitcnt lgkmcnt(0)
	v_add_f32_e32 v25, v25, v26
	v_lshl_add_u32 v26, v178, 5, s3
	ds_write_b64 v26, v[24:25]

.LBB0_1059:
	s_or_b64 exec, exec, s[10:11]
	s_mov_b32 s15, s1
	s_lshl_b64 s[8:9], s[14:15], 12
	s_add_u32 s10, s36, s8
	s_addc_u32 s11, s37, s9
	s_add_u32 s8, s38, s8
	s_addc_u32 s9, s39, s9
	v_lshlrev_b64 v[4:5], 2, v[160:161]
	s_waitcnt lgkmcnt(0)
	s_barrier
	v_lshl_add_u64 v[34:35], s[10:11], 0, v[4:5]
	v_lshl_add_u64 v[36:37], s[8:9], 0, v[4:5]
	global_load_dwordx4 v[0:3], v[34:35], off
	global_load_dwordx4 v[4:7], v[36:37], off
	global_load_dwordx4 v[180:183], v[34:35], off offset:64
	global_load_dwordx4 v[184:187], v[36:37], off offset:64
	global_load_dwordx4 v[188:191], v[34:35], off offset:512
	global_load_dwordx4 v[192:195], v[36:37], off offset:512
	global_load_dwordx4 v[196:199], v[34:35], off offset:576
	global_load_dwordx4 v[200:203], v[36:37], off offset:576
	v_and_b32_e32 v96, 15, v178
	v_or_b32_e32 v45, s4, v96
	v_lshl_add_u32 v33, v45, 3, 0
	v_lshlrev_b32_e32 v115, 2, v45
	s_waitcnt lgkmcnt(0)
	v_cmp_ne_u32_e32 vcc, 0, v32
	v_sub_u32_e32 v32, v33, v115
	ds_read_b64 v[38:39], v33 offset:8192
	ds_read_b32 v33, v32 offset:12288
	v_readlane_b32 s3, v254, 55
	s_or_b64 s[6:7], vcc, s[6:7]
	s_or_b32 s3, s5, s3
	s_cmp_eq_u32 s3, 0
	s_cselect_b64 s[8:9], -1, 0
	v_cmp_gt_u32_e32 vcc, 16, v178
	s_waitcnt lgkmcnt(0)
	v_max_f32_e32 v33, v33, v33
	v_max_f32_e32 v47, 0xda24260, v33
	s_and_b64 s[8:9], s[8:9], vcc
	s_and_saveexec_b64 s[10:11], s[8:9]
	s_cbranch_execz .LBB0_1061
	v_readlane_b32 s3, v254, 17
	v_mul_f32_e32 v33, 0x3c010204, v47
	v_cndmask_b32_e64 v33, v33, v232, s[6:7]
	v_add_u32_e32 v98, s3, v45
	v_ashrrev_i32_e32 v99, 31, v98
	v_lshl_add_u64 v[98:99], v[98:99], 2, s[24:25]
	global_store_dword v[98:99], v33, off

.LBB0_1075:
	s_or_b64 exec, exec, s[10:11]
	s_waitcnt lgkmcnt(0)
	v_sub_f32_e32 v129, v129, v94
	v_sub_f32_e32 v128, v128, v94
	v_pk_mul_f32 v[128:129], v[94:95], v[128:129] op_sel:[1,0]
	v_div_scale_f32 v45, s[4:5], v115, v115, s81
	v_pk_fma_f32 v[128:129], v[2:3], v[128:129], v[6:7]
	v_sub_f32_e32 v131, v131, v94
	v_cndmask_b32_e64 v153, v129, v232, s[6:7]
	v_rcp_f32_e32 v129, v45
	v_cndmask_b32_e64 v152, v128, v232, s[6:7]
	v_sub_f32_e32 v130, v130, v94
	v_pk_mul_f32 v[130:131], v[94:95], v[130:131] op_sel:[1,0]
	v_fma_f32 v128, -v45, v129, 1.0
	v_fmac_f32_e32 v129, v128, v129
	v_div_scale_f32 v128, vcc, s81, v115, s81
	v_mul_f32_e32 v151, v128, v129
	v_fma_f32 v154, -v45, v151, v128
	v_fmac_f32_e32 v151, v154, v129
	v_fma_f32 v45, -v45, v151, v128
	v_pk_fma_f32 v[130:131], v[0:1], v[130:131], v[4:5]
	v_div_fmas_f32 v45, v45, v129, v151
	v_sub_f32_e32 v63, v63, v78
	v_sub_f32_e32 v62, v62, v78
	v_cndmask_b32_e64 v131, v131, v232, s[6:7]
	v_cndmask_b32_e64 v130, v130, v232, s[6:7]
	v_div_fixup_f32 v128, v45, v115, s81
	v_pk_mul_f32 v[62:63], v[78:79], v[62:63] op_sel:[1,0]
	v_pk_mul_f32 v[154:155], v[128:129], v[130:131] op_sel_hi:[0,1]
	v_pk_fma_f32 v[2:3], v[2:3], v[62:63], v[6:7]
	v_div_scale_f32 v6, s[4:5], v149, v149, s81
	v_pk_mul_f32 v[156:157], v[128:129], v[152:153] op_sel_hi:[0,1]
	v_rndne_f32_e32 v129, v155
	v_rcp_f32_e32 v7, v6
	v_rndne_f32_e32 v45, v157
	v_rndne_f32_e32 v115, v156
	v_cvt_i32_f32_e32 v129, v129
	v_rndne_f32_e32 v151, v154
	v_sub_f32_e32 v61, v61, v78
	v_sub_f32_e32 v60, v60, v78
	v_cvt_i32_f32_e32 v45, v45
	v_cvt_i32_f32_sdwa v115, v115 dst_sel:WORD_1 dst_unused:UNUSED_PAD src0_sel:DWORD
	v_cvt_i32_f32_e32 v151, v151
	v_pk_mul_f32 v[60:61], v[78:79], v[60:61] op_sel:[1,0]
	v_lshlrev_b32_e32 v129, 8, v129
	v_pk_fma_f32 v[0:1], v[0:1], v[60:61], v[4:5]
	v_and_b32_e32 v115, 0xff0000, v115
	v_cndmask_b32_e64 v4, v0, v232, s[6:7]
	v_fma_f32 v0, -v6, v7, 1.0
	v_fmac_f32_e32 v7, v0, v7
	v_div_scale_f32 v0, vcc, s81, v149, s81
	v_and_b32_e32 v129, 0xff00, v129
	v_perm_b32 v45, v45, v151, s85
	v_cndmask_b32_e64 v5, v1, v232, s[6:7]
	v_mul_f32_e32 v1, v0, v7
	v_or3_b32 v155, v45, v129, v115
	v_fma_f32 v45, -v6, v1, v0
	v_fmac_f32_e32 v1, v45, v7
	v_fma_f32 v0, -v6, v1, v0
	v_div_fmas_f32 v0, v0, v7, v1
	v_div_fixup_f32 v60, v0, v149, s81
	v_cndmask_b32_e64 v3, v3, v232, s[6:7]
	v_cndmask_b32_e64 v2, v2, v232, s[6:7]
	v_pk_mul_f32 v[0:1], v[60:61], v[4:5] op_sel_hi:[0,1]
	v_pk_mul_f32 v[6:7], v[60:61], v[2:3] op_sel_hi:[0,1]
	v_rndne_f32_e32 v1, v1
	v_rndne_f32_e32 v7, v7
	v_rndne_f32_e32 v6, v6
	v_cvt_i32_f32_e32 v1, v1
	v_rndne_f32_e32 v0, v0
	v_cvt_i32_f32_e32 v7, v7
	v_cvt_i32_f32_sdwa v6, v6 dst_sel:WORD_1 dst_unused:UNUSED_PAD src0_sel:DWORD
	v_cvt_i32_f32_e32 v0, v0
	v_lshlrev_b32_e32 v1, 8, v1
	v_and_b32_e32 v1, 0xff00, v1
	v_and_b32_e32 v6, 0xff0000, v6
	v_perm_b32 v0, v7, v0, s85
	v_or3_b32 v154, v0, v1, v6
	v_or_b32_e32 v0, v77, v109
	v_ashrrev_i32_e32 v1, 31, v0
	v_lshlrev_b64 v[62:63], 10, v[0:1]
	v_lshl_add_u64 v[6:7], v[62:63], 0, v[112:113]
	v_cvt_pk_f16_f32 v1, v2, v3
	v_cvt_pk_f16_f32 v0, v4, v5
	v_cvt_pk_f16_f32 v3, v152, v153
	v_cvt_pk_f16_f32 v2, v130, v131
	s_nop 1
	v_permlane16_swap_b32_e32 v0, v2
	v_permlane16_swap_b32_e32 v1, v3
	v_lshl_add_u64 v[4:5], v[6:7], 1, s[60:61]
	global_store_dwordx4 v[4:5], v[0:3], off
	v_permlane16_swap_b32_e32 v154, v155
	s_nop 0
	v_lshl_add_u64 v[0:1], s[72:73], 0, v[6:7]
	global_store_dwordx2 v[0:1], v[154:155], off
	v_mov_b32_e32 v0, v180
	v_mov_b32_e32 v1, v181
	v_mov_b32_e32 v2, v182
	v_mov_b32_e32 v3, v183
	v_mov_b32_e32 v4, v184
	v_mov_b32_e32 v5, v185
	v_mov_b32_e32 v6, v186
	v_mov_b32_e32 v7, v187
	v_mov_b32_e32 v160, v39
	v_mov_b32_e32 v161, v39
	v_sub_f32_e32 v165, v141, v38
	v_sub_f32_e32 v164, v140, v38
	v_sub_f32_e32 v141, v143, v38
	v_sub_f32_e32 v140, v142, v38
	v_pk_mul_f32 v[142:143], v[160:161], v[140:141]
	v_mov_b32_e32 v140, v39
	v_mov_b32_e32 v141, v39
	v_pk_mul_f32 v[164:165], v[140:141], v[164:165]
	v_mov_b32_e32 v115, v114
	v_mov_b32_e32 v158, v33
	v_mov_b32_e32 v159, v33
	v_sub_f32_e32 v147, v147, v32
	v_sub_f32_e32 v146, v146, v32
	v_pk_mul_f32 v[146:147], v[158:159], v[146:147]
	v_mov_b32_e32 v45, v44
	v_lshl_add_u64 v[162:163], v[112:113], 0, 16
	v_mov_b32_e32 v156, v99
	v_mov_b32_e32 v157, v99
	v_sub_f32_e32 v121, v121, v98
	v_sub_f32_e32 v120, v120, v98
	v_sub_f32_e32 v123, v123, v98
	v_sub_f32_e32 v122, v122, v98
	v_mov_b32_e32 v149, v148
	v_mov_b32_e32 v154, v47
	v_mov_b32_e32 v155, v47
	v_sub_f32_e32 v107, v107, v46
	v_sub_f32_e32 v106, v106, v46
	v_mov_b32_e32 v109, v108
	v_mov_b32_e32 v152, v127
	v_mov_b32_e32 v153, v127
	v_sub_f32_e32 v89, v89, v126
	v_sub_f32_e32 v88, v88, v126
	v_sub_f32_e32 v91, v91, v126
	v_sub_f32_e32 v90, v90, v126
	v_mov_b32_e32 v151, v150
	v_mov_b32_e32 v130, v111
	v_mov_b32_e32 v131, v111
	v_sub_f32_e32 v75, v75, v110
	v_sub_f32_e32 v74, v74, v110
	v_mov_b32_e32 v77, v76
	v_sub_f32_e32 v57, v57, v78
	v_sub_f32_e32 v56, v56, v78
	v_sub_f32_e32 v41, v41, v94
	v_sub_f32_e32 v40, v40, v94
	v_sub_f32_e32 v59, v59, v78
	v_sub_f32_e32 v58, v58, v78
	v_pk_mul_f32 v[56:57], v[78:79], v[56:57] op_sel:[1,0]
	v_sub_f32_e32 v43, v43, v94
	v_sub_f32_e32 v42, v42, v94
	v_pk_mul_f32 v[40:41], v[94:95], v[40:41] op_sel:[1,0]
	v_pk_mul_f32 v[58:59], v[78:79], v[58:59] op_sel:[1,0]
	v_pk_mul_f32 v[42:43], v[94:95], v[42:43] op_sel:[1,0]
	v_sub_f32_e32 v53, v53, v78
	v_sub_f32_e32 v52, v52, v78
	v_sub_f32_e32 v13, v13, v94
	v_sub_f32_e32 v12, v12, v94
	v_pk_mul_f32 v[52:53], v[78:79], v[52:53] op_sel:[1,0]
	v_sub_f32_e32 v15, v15, v94
	v_sub_f32_e32 v14, v14, v94
	v_pk_mul_f32 v[12:13], v[94:95], v[12:13] op_sel:[1,0]
	v_pk_mul_f32 v[14:15], v[94:95], v[14:15] op_sel:[1,0]
	v_sub_f32_e32 v23, v23, v32
	v_sub_f32_e32 v22, v22, v32
	v_sub_f32_e32 v21, v21, v32
	v_sub_f32_e32 v20, v20, v32
	v_pk_mul_f32 v[22:23], v[158:159], v[22:23]
	s_mov_b64 s[4:5], 0x90
	v_sub_f32_e32 v9, v9, v94
	v_sub_f32_e32 v8, v8, v94
	v_sub_f32_e32 v11, v11, v94
	v_sub_f32_e32 v10, v10, v94
	v_pk_mul_f32 v[8:9], v[94:95], v[8:9] op_sel:[1,0]
	v_pk_mul_f32 v[10:11], v[94:95], v[10:11] op_sel:[1,0]
	v_pk_fma_f32 v[142:143], v[142:143], v[0:1], v[4:5]
	v_pk_fma_f32 v[164:165], v[164:165], v[2:3], v[6:7]
	v_cndmask_b32_e64 v167, v143, v232, s[6:7]
	v_cndmask_b32_e64 v166, v142, v232, s[6:7]
	v_cndmask_b32_e64 v165, v165, v232, s[6:7]
	v_cndmask_b32_e64 v164, v164, v232, s[6:7]
	v_mov_b32_e32 v142, v114
	v_mov_b32_e32 v143, v114
	v_pk_mul_f32 v[170:171], v[114:115], v[166:167]
	v_pk_mul_f32 v[168:169], v[142:143], v[164:165]
	v_rndne_f32_e32 v61, v171
	v_rndne_f32_e32 v39, v170
	v_cvt_i32_f32_e32 v61, v61
	v_rndne_f32_e32 v129, v168
	v_rndne_f32_e32 v168, v169
	v_cvt_i32_f32_e32 v39, v39
	v_cvt_i32_f32_sdwa v129, v129 dst_sel:WORD_1 dst_unused:UNUSED_PAD src0_sel:DWORD
	v_cvt_i32_f32_e32 v168, v168
	v_sub_f32_e32 v171, v145, v32
	v_sub_f32_e32 v170, v144, v32
	v_mov_b32_e32 v144, v33
	v_mov_b32_e32 v145, v33
	v_pk_mul_f32 v[170:171], v[144:145], v[170:171]
	v_pk_fma_f32 v[146:147], v[146:147], v[0:1], v[4:5]
	v_lshlrev_b32_e32 v61, 8, v61
	v_pk_fma_f32 v[170:171], v[170:171], v[2:3], v[6:7]
	v_cndmask_b32_e64 v173, v147, v232, s[6:7]
	v_cndmask_b32_e64 v172, v146, v232, s[6:7]
	v_and_b32_e32 v61, 0xff00, v61
	v_and_b32_e32 v129, 0xff0000, v129
	v_perm_b32 v39, v168, v39, s85
	v_cndmask_b32_e64 v171, v171, v232, s[6:7]
	v_cndmask_b32_e64 v170, v170, v232, s[6:7]
	v_pk_mul_f32 v[174:175], v[44:45], v[172:173]
	v_mov_b32_e32 v146, v44
	v_mov_b32_e32 v147, v44
	v_or3_b32 v168, v39, v61, v129
	v_pk_mul_f32 v[176:177], v[146:147], v[170:171]
	v_rndne_f32_e32 v61, v175
	v_rndne_f32_e32 v33, v177
	v_rndne_f32_e32 v39, v176
	v_cvt_i32_f32_e32 v61, v61
	v_rndne_f32_e32 v129, v174
	v_cvt_i32_f32_e32 v33, v33
	v_cvt_i32_f32_sdwa v39, v39 dst_sel:WORD_1 dst_unused:UNUSED_PAD src0_sel:DWORD
	v_cvt_i32_f32_e32 v129, v129
	v_lshlrev_b32_e32 v61, 8, v61
	v_and_b32_e32 v61, 0xff00, v61
	v_and_b32_e32 v39, 0xff0000, v39
	v_perm_b32 v33, v33, v129, s85
	v_lshl_add_u64 v[174:175], v[96:97], 0, v[162:163]
	v_cvt_pk_f16_f32 v165, v164, v165
	v_cvt_pk_f16_f32 v164, v166, v167
	v_cvt_pk_f16_f32 v167, v170, v171
	v_cvt_pk_f16_f32 v166, v172, v173
	v_or3_b32 v169, v33, v61, v39
	s_nop 0
	v_permlane16_swap_b32_e32 v164, v166
	v_permlane16_swap_b32_e32 v165, v167
	v_lshl_add_u64 v[170:171], v[174:175], 1, s[60:61]
	global_store_dwordx4 v[170:171], v[164:167], off
	v_permlane16_swap_b32_e32 v168, v169
	s_nop 0
	v_lshl_add_u64 v[164:165], s[72:73], 0, v[174:175]
	global_store_dwordx2 v[164:165], v[168:169], off
	v_pk_mul_f32 v[164:165], v[156:157], v[120:121]
	v_mov_b32_e32 v120, v99
	v_mov_b32_e32 v121, v99
	v_pk_mul_f32 v[122:123], v[120:121], v[122:123]
	v_pk_fma_f32 v[164:165], v[164:165], v[0:1], v[4:5]
	v_pk_fma_f32 v[122:123], v[122:123], v[2:3], v[6:7]
	v_cndmask_b32_e64 v167, v165, v232, s[6:7]
	v_cndmask_b32_e64 v166, v164, v232, s[6:7]
	v_cndmask_b32_e64 v165, v123, v232, s[6:7]
	v_cndmask_b32_e64 v164, v122, v232, s[6:7]
	v_mov_b32_e32 v122, v148
	v_mov_b32_e32 v123, v148
	v_pk_mul_f32 v[170:171], v[148:149], v[166:167]
	v_pk_mul_f32 v[168:169], v[122:123], v[164:165]
	v_rndne_f32_e32 v39, v171
	v_rndne_f32_e32 v33, v170
	v_cvt_i32_f32_e32 v39, v39
	v_rndne_f32_e32 v61, v168
	v_rndne_f32_e32 v99, v169
	v_sub_f32_e32 v171, v105, v46
	v_sub_f32_e32 v170, v104, v46
	v_cvt_i32_f32_e32 v33, v33
	v_cvt_i32_f32_sdwa v61, v61 dst_sel:WORD_1 dst_unused:UNUSED_PAD src0_sel:DWORD
	v_cvt_i32_f32_e32 v99, v99
	v_mov_b32_e32 v104, v47
	v_mov_b32_e32 v105, v47
	v_pk_mul_f32 v[170:171], v[154:155], v[170:171]
	v_pk_mul_f32 v[106:107], v[104:105], v[106:107]
	v_pk_fma_f32 v[170:171], v[170:171], v[0:1], v[4:5]
	v_pk_fma_f32 v[106:107], v[106:107], v[2:3], v[6:7]
	v_cndmask_b32_e64 v171, v171, v232, s[6:7]
	v_cndmask_b32_e64 v170, v170, v232, s[6:7]
	v_lshlrev_b32_e32 v39, 8, v39
	v_cndmask_b32_e64 v173, v107, v232, s[6:7]
	v_cndmask_b32_e64 v172, v106, v232, s[6:7]
	v_pk_mul_f32 v[174:175], v[108:109], v[170:171]
	v_mov_b32_e32 v106, v108
	v_mov_b32_e32 v107, v108
	v_and_b32_e32 v39, 0xff00, v39
	v_and_b32_e32 v61, 0xff0000, v61
	v_perm_b32 v33, v99, v33, s85
	v_pk_mul_f32 v[176:177], v[106:107], v[172:173]
	v_rndne_f32_e32 v47, v175
	v_or3_b32 v168, v33, v39, v61
	v_rndne_f32_e32 v33, v177
	v_rndne_f32_e32 v39, v176
	v_cvt_i32_f32_e32 v47, v47
	v_rndne_f32_e32 v61, v174
	v_cvt_i32_f32_e32 v33, v33
	v_cvt_i32_f32_sdwa v39, v39 dst_sel:WORD_1 dst_unused:UNUSED_PAD src0_sel:DWORD
	v_cvt_i32_f32_e32 v61, v61
	v_lshlrev_b32_e32 v47, 8, v47
	v_and_b32_e32 v47, 0xff00, v47
	v_and_b32_e32 v39, 0xff0000, v39
	v_perm_b32 v33, v33, v61, s85
	v_lshl_add_u64 v[174:175], v[124:125], 0, v[162:163]
	v_cvt_pk_f16_f32 v165, v164, v165
	v_cvt_pk_f16_f32 v164, v166, v167
	v_cvt_pk_f16_f32 v167, v172, v173
	v_cvt_pk_f16_f32 v166, v170, v171
	v_or3_b32 v169, v33, v47, v39
	s_nop 0
	v_permlane16_swap_b32_e32 v164, v166
	v_permlane16_swap_b32_e32 v165, v167
	v_lshl_add_u64 v[170:171], v[174:175], 1, s[60:61]
	global_store_dwordx4 v[170:171], v[164:167], off
	v_permlane16_swap_b32_e32 v168, v169
	s_nop 0
	v_lshl_add_u64 v[164:165], s[72:73], 0, v[174:175]
	global_store_dwordx2 v[164:165], v[168:169], off
	v_pk_mul_f32 v[164:165], v[152:153], v[88:89]
	v_mov_b32_e32 v88, v127
	v_mov_b32_e32 v89, v127
	v_pk_mul_f32 v[90:91], v[88:89], v[90:91]
	v_pk_fma_f32 v[164:165], v[164:165], v[0:1], v[4:5]
	v_pk_fma_f32 v[90:91], v[90:91], v[2:3], v[6:7]
	v_cndmask_b32_e64 v167, v165, v232, s[6:7]
	v_cndmask_b32_e64 v166, v164, v232, s[6:7]
	v_cndmask_b32_e64 v165, v91, v232, s[6:7]
	v_cndmask_b32_e64 v164, v90, v232, s[6:7]
	v_mov_b32_e32 v90, v150
	v_mov_b32_e32 v91, v150
	v_pk_mul_f32 v[170:171], v[150:151], v[166:167]
	v_pk_mul_f32 v[168:169], v[90:91], v[164:165]
	v_rndne_f32_e32 v39, v171
	v_rndne_f32_e32 v33, v170
	v_cvt_i32_f32_e32 v39, v39
	v_rndne_f32_e32 v47, v168
	v_rndne_f32_e32 v61, v169
	v_cvt_i32_f32_e32 v33, v33
	v_cvt_i32_f32_sdwa v47, v47 dst_sel:WORD_1 dst_unused:UNUSED_PAD src0_sel:DWORD
	v_cvt_i32_f32_e32 v61, v61
	v_sub_f32_e32 v171, v73, v110
	v_sub_f32_e32 v170, v72, v110
	v_mov_b32_e32 v72, v111
	v_mov_b32_e32 v73, v111
	v_pk_mul_f32 v[170:171], v[130:131], v[170:171]
	v_pk_mul_f32 v[74:75], v[72:73], v[74:75]
	v_pk_fma_f32 v[170:171], v[170:171], v[0:1], v[4:5]
	v_lshlrev_b32_e32 v39, 8, v39
	v_pk_fma_f32 v[74:75], v[74:75], v[2:3], v[6:7]
	v_cndmask_b32_e64 v171, v171, v232, s[6:7]
	v_cndmask_b32_e64 v170, v170, v232, s[6:7]
	v_and_b32_e32 v39, 0xff00, v39
	v_and_b32_e32 v47, 0xff0000, v47
	v_perm_b32 v33, v61, v33, s85
	v_cndmask_b32_e64 v173, v75, v232, s[6:7]
	v_cndmask_b32_e64 v172, v74, v232, s[6:7]
	v_pk_mul_f32 v[174:175], v[76:77], v[170:171]
	v_mov_b32_e32 v74, v76
	v_mov_b32_e32 v75, v76
	v_or3_b32 v168, v33, v39, v47
	v_pk_mul_f32 v[176:177], v[74:75], v[172:173]
	v_rndne_f32_e32 v47, v175
	v_rndne_f32_e32 v33, v177
	v_rndne_f32_e32 v39, v176
	v_cvt_i32_f32_e32 v47, v47
	v_rndne_f32_e32 v61, v174
	v_cvt_i32_f32_e32 v33, v33
	v_cvt_i32_f32_sdwa v39, v39 dst_sel:WORD_1 dst_unused:UNUSED_PAD src0_sel:DWORD
	v_cvt_i32_f32_e32 v61, v61
	v_lshlrev_b32_e32 v47, 8, v47
	v_pk_fma_f32 v[56:57], v[56:57], v[0:1], v[4:5]
	v_pk_fma_f32 v[0:1], v[40:41], v[0:1], v[4:5]
	v_and_b32_e32 v39, 0xff0000, v39
	v_and_b32_e32 v47, 0xff00, v47
	v_perm_b32 v33, v33, v61, s85
	v_lshl_add_u64 v[174:175], v[92:93], 0, v[162:163]
	v_cvt_pk_f16_f32 v165, v164, v165
	v_cvt_pk_f16_f32 v164, v166, v167
	v_cvt_pk_f16_f32 v167, v172, v173
	v_cvt_pk_f16_f32 v166, v170, v171
	v_pk_fma_f32 v[58:59], v[58:59], v[2:3], v[6:7]
	v_pk_fma_f32 v[2:3], v[42:43], v[2:3], v[6:7]
	v_cndmask_b32_e64 v5, v1, v232, s[6:7]
	v_cndmask_b32_e64 v4, v0, v232, s[6:7]
	v_or3_b32 v169, v33, v47, v39
	v_permlane16_swap_b32_e32 v164, v166
	v_permlane16_swap_b32_e32 v165, v167
	v_lshl_add_u64 v[170:171], v[174:175], 1, s[60:61]
	v_cndmask_b32_e64 v57, v57, v232, s[6:7]
	v_cndmask_b32_e64 v56, v56, v232, s[6:7]
	v_cndmask_b32_e64 v3, v3, v232, s[6:7]
	v_cndmask_b32_e64 v2, v2, v232, s[6:7]
	v_pk_mul_f32 v[0:1], v[128:129], v[4:5] op_sel_hi:[0,1]
	global_store_dwordx4 v[170:171], v[164:167], off
	v_permlane16_swap_b32_e32 v168, v169
	s_nop 0
	v_lshl_add_u64 v[164:165], s[72:73], 0, v[174:175]
	v_cndmask_b32_e64 v59, v59, v232, s[6:7]
	v_cndmask_b32_e64 v58, v58, v232, s[6:7]
	v_pk_mul_f32 v[166:167], v[60:61], v[56:57] op_sel_hi:[0,1]
	v_pk_mul_f32 v[6:7], v[128:129], v[2:3] op_sel_hi:[0,1]
	v_rndne_f32_e32 v1, v1
	global_store_dwordx2 v[164:165], v[168:169], off
	v_pk_mul_f32 v[164:165], v[60:61], v[58:59] op_sel_hi:[0,1]
	v_rndne_f32_e32 v39, v167
	v_rndne_f32_e32 v7, v7
	v_rndne_f32_e32 v6, v6
	v_cvt_i32_f32_e32 v1, v1
	v_rndne_f32_e32 v0, v0
	v_rndne_f32_e32 v33, v166
	v_cvt_i32_f32_e32 v39, v39
	v_rndne_f32_e32 v47, v164
	v_rndne_f32_e32 v61, v165
	v_cvt_i32_f32_e32 v7, v7
	v_cvt_i32_f32_sdwa v6, v6 dst_sel:WORD_1 dst_unused:UNUSED_PAD src0_sel:DWORD
	v_cvt_i32_f32_e32 v0, v0
	v_cvt_i32_f32_e32 v33, v33
	v_cvt_i32_f32_sdwa v47, v47 dst_sel:WORD_1 dst_unused:UNUSED_PAD src0_sel:DWORD
	v_cvt_i32_f32_e32 v61, v61
	v_lshlrev_b32_e32 v1, 8, v1
	v_lshlrev_b32_e32 v39, 8, v39
	v_and_b32_e32 v6, 0xff0000, v6
	v_and_b32_e32 v1, 0xff00, v1
	v_perm_b32 v0, v7, v0, s85
	v_and_b32_e32 v39, 0xff00, v39
	v_and_b32_e32 v47, 0xff0000, v47
	v_perm_b32 v33, v61, v33, s85
	v_or3_b32 v165, v0, v1, v6
	v_lshl_add_u64 v[6:7], v[62:63], 0, v[162:163]
	v_cvt_pk_f16_f32 v1, v58, v59
	v_cvt_pk_f16_f32 v0, v56, v57
	v_cvt_pk_f16_f32 v3, v2, v3
	v_cvt_pk_f16_f32 v2, v4, v5
	v_or3_b32 v164, v33, v39, v47
	s_nop 0
	v_permlane16_swap_b32_e32 v0, v2
	v_permlane16_swap_b32_e32 v1, v3
	v_lshl_add_u64 v[4:5], v[6:7], 1, s[60:61]
	global_store_dwordx4 v[4:5], v[0:3], off
	v_permlane16_swap_b32_e32 v164, v165
	s_nop 0
	v_lshl_add_u64 v[0:1], s[72:73], 0, v[6:7]
	global_store_dwordx2 v[0:1], v[164:165], off
	v_mov_b32_e32 v0, v188
	v_mov_b32_e32 v1, v189
	v_mov_b32_e32 v2, v190
	v_mov_b32_e32 v3, v191
	v_mov_b32_e32 v4, v192
	v_mov_b32_e32 v5, v193
	v_mov_b32_e32 v6, v194
	v_mov_b32_e32 v7, v195
	v_sub_f32_e32 v43, v137, v38
	v_sub_f32_e32 v42, v136, v38
	v_sub_f32_e32 v57, v139, v38
	v_sub_f32_e32 v56, v138, v38
	v_pk_mul_f32 v[56:57], v[160:161], v[56:57]
	v_pk_mul_f32 v[42:43], v[140:141], v[42:43]
	v_lshl_add_u64 v[40:41], v[112:113], 0, s[96:97]
	v_pk_mul_f32 v[20:21], v[144:145], v[20:21]
	v_pk_fma_f32 v[42:43], v[42:43], v[2:3], v[6:7]
	v_pk_fma_f32 v[56:57], v[56:57], v[0:1], v[4:5]
	v_cndmask_b32_e64 v43, v43, v232, s[6:7]
	v_cndmask_b32_e64 v59, v57, v232, s[6:7]
	v_cndmask_b32_e64 v58, v56, v232, s[6:7]
	v_cndmask_b32_e64 v42, v42, v232, s[6:7]
	v_pk_mul_f32 v[56:57], v[142:143], v[42:43]
	v_pk_mul_f32 v[136:137], v[114:115], v[58:59]
	v_rndne_f32_e32 v47, v56
	v_rndne_f32_e32 v33, v136
	v_rndne_f32_e32 v56, v57
	v_cvt_i32_f32_e32 v33, v33
	v_cvt_i32_f32_e32 v56, v56
	v_rndne_f32_e32 v39, v137
	v_cvt_i32_f32_e32 v39, v39
	v_cvt_i32_f32_sdwa v47, v47 dst_sel:WORD_1 dst_unused:UNUSED_PAD src0_sel:DWORD
	v_perm_b32 v33, v56, v33, s85
	v_sub_f32_e32 v57, v133, v32
	v_sub_f32_e32 v56, v132, v32
	v_sub_f32_e32 v133, v135, v32
	v_sub_f32_e32 v132, v134, v32
	v_pk_mul_f32 v[56:57], v[158:159], v[56:57]
	v_pk_mul_f32 v[132:133], v[144:145], v[132:133]
	v_pk_fma_f32 v[56:57], v[56:57], v[0:1], v[4:5]
	v_lshlrev_b32_e32 v39, 8, v39
	v_pk_fma_f32 v[132:133], v[132:133], v[2:3], v[6:7]
	v_cndmask_b32_e64 v135, v57, v232, s[6:7]
	v_cndmask_b32_e64 v134, v56, v232, s[6:7]
	v_and_b32_e32 v39, 0xff00, v39
	v_and_b32_e32 v47, 0xff0000, v47
	v_cndmask_b32_e64 v133, v133, v232, s[6:7]
	v_cndmask_b32_e64 v132, v132, v232, s[6:7]
	v_pk_mul_f32 v[56:57], v[44:45], v[134:135]
	v_or3_b32 v136, v33, v39, v47
	v_pk_mul_f32 v[138:139], v[146:147], v[132:133]
	v_rndne_f32_e32 v47, v57
	v_rndne_f32_e32 v33, v139
	v_rndne_f32_e32 v39, v138
	v_cvt_i32_f32_e32 v47, v47
	v_rndne_f32_e32 v56, v56
	v_cvt_i32_f32_e32 v33, v33
	v_cvt_i32_f32_sdwa v39, v39 dst_sel:WORD_1 dst_unused:UNUSED_PAD src0_sel:DWORD
	v_cvt_i32_f32_e32 v56, v56
	v_lshlrev_b32_e32 v47, 8, v47
	v_and_b32_e32 v47, 0xff00, v47
	v_and_b32_e32 v39, 0xff0000, v39
	v_perm_b32 v33, v33, v56, s85
	v_lshl_add_u64 v[138:139], v[96:97], 0, v[40:41]
	v_cvt_pk_f16_f32 v57, v42, v43
	v_cvt_pk_f16_f32 v56, v58, v59
	v_cvt_pk_f16_f32 v59, v132, v133
	v_cvt_pk_f16_f32 v58, v134, v135
	v_or3_b32 v137, v33, v47, v39
	s_nop 0
	v_permlane16_swap_b32_e32 v56, v58
	v_permlane16_swap_b32_e32 v57, v59
	v_lshl_add_u64 v[42:43], v[138:139], 1, s[60:61]
	global_store_dwordx4 v[42:43], v[56:59], off
	v_permlane16_swap_b32_e32 v136, v137
	v_lshl_add_u64 v[42:43], s[72:73], 0, v[138:139]
	global_store_dwordx2 v[42:43], v[136:137], off
	v_sub_f32_e32 v43, v119, v98
	v_sub_f32_e32 v42, v118, v98
	v_sub_f32_e32 v57, v117, v98
	v_sub_f32_e32 v56, v116, v98
	v_pk_mul_f32 v[56:57], v[156:157], v[56:57]
	v_pk_mul_f32 v[42:43], v[120:121], v[42:43]
	v_pk_fma_f32 v[56:57], v[56:57], v[0:1], v[4:5]
	v_pk_fma_f32 v[42:43], v[42:43], v[2:3], v[6:7]
	v_cndmask_b32_e64 v59, v57, v232, s[6:7]
	v_cndmask_b32_e64 v58, v56, v232, s[6:7]
	v_cndmask_b32_e64 v43, v43, v232, s[6:7]
	v_cndmask_b32_e64 v42, v42, v232, s[6:7]
	v_pk_mul_f32 v[56:57], v[122:123], v[42:43]
	v_pk_mul_f32 v[116:117], v[148:149], v[58:59]
	v_rndne_f32_e32 v47, v56
	v_rndne_f32_e32 v33, v116
	v_rndne_f32_e32 v56, v57
	v_cvt_i32_f32_e32 v33, v33
	v_cvt_i32_f32_e32 v56, v56
	v_rndne_f32_e32 v39, v117
	v_cvt_i32_f32_e32 v39, v39
	v_cvt_i32_f32_sdwa v47, v47 dst_sel:WORD_1 dst_unused:UNUSED_PAD src0_sel:DWORD
	v_perm_b32 v33, v56, v33, s85
	v_sub_f32_e32 v57, v101, v46
	v_sub_f32_e32 v56, v100, v46
	v_sub_f32_e32 v101, v103, v46
	v_sub_f32_e32 v100, v102, v46
	v_pk_mul_f32 v[56:57], v[154:155], v[56:57]
	v_pk_mul_f32 v[100:101], v[104:105], v[100:101]
	v_pk_fma_f32 v[56:57], v[56:57], v[0:1], v[4:5]
	v_lshlrev_b32_e32 v39, 8, v39
	v_pk_fma_f32 v[100:101], v[100:101], v[2:3], v[6:7]
	v_cndmask_b32_e64 v103, v57, v232, s[6:7]
	v_cndmask_b32_e64 v102, v56, v232, s[6:7]
	v_and_b32_e32 v39, 0xff00, v39
	v_and_b32_e32 v47, 0xff0000, v47
	v_cndmask_b32_e64 v101, v101, v232, s[6:7]
	v_cndmask_b32_e64 v100, v100, v232, s[6:7]
	v_pk_mul_f32 v[56:57], v[108:109], v[102:103]
	v_or3_b32 v116, v33, v39, v47
	v_pk_mul_f32 v[118:119], v[106:107], v[100:101]
	v_rndne_f32_e32 v47, v57
	v_rndne_f32_e32 v33, v119
	v_rndne_f32_e32 v39, v118
	v_cvt_i32_f32_e32 v47, v47
	v_rndne_f32_e32 v56, v56
	v_cvt_i32_f32_e32 v33, v33
	v_cvt_i32_f32_sdwa v39, v39 dst_sel:WORD_1 dst_unused:UNUSED_PAD src0_sel:DWORD
	v_cvt_i32_f32_e32 v56, v56
	v_lshlrev_b32_e32 v47, 8, v47
	v_and_b32_e32 v47, 0xff00, v47
	v_and_b32_e32 v39, 0xff0000, v39
	v_perm_b32 v33, v33, v56, s85
	v_lshl_add_u64 v[118:119], v[124:125], 0, v[40:41]
	v_cvt_pk_f16_f32 v57, v42, v43
	v_cvt_pk_f16_f32 v56, v58, v59
	v_cvt_pk_f16_f32 v59, v100, v101
	v_cvt_pk_f16_f32 v58, v102, v103
	v_or3_b32 v117, v33, v47, v39
	s_nop 0
	v_permlane16_swap_b32_e32 v56, v58
	v_permlane16_swap_b32_e32 v57, v59
	v_lshl_add_u64 v[42:43], v[118:119], 1, s[60:61]
	global_store_dwordx4 v[42:43], v[56:59], off
	v_permlane16_swap_b32_e32 v116, v117
	v_lshl_add_u64 v[42:43], s[72:73], 0, v[118:119]
	global_store_dwordx2 v[42:43], v[116:117], off
	v_sub_f32_e32 v43, v87, v126
	v_sub_f32_e32 v42, v86, v126
	v_sub_f32_e32 v57, v85, v126
	v_sub_f32_e32 v56, v84, v126
	v_pk_mul_f32 v[56:57], v[152:153], v[56:57]
	v_pk_mul_f32 v[42:43], v[88:89], v[42:43]
	v_pk_fma_f32 v[56:57], v[56:57], v[0:1], v[4:5]
	v_pk_fma_f32 v[42:43], v[42:43], v[2:3], v[6:7]
	v_cndmask_b32_e64 v59, v57, v232, s[6:7]
	v_cndmask_b32_e64 v58, v56, v232, s[6:7]
	v_cndmask_b32_e64 v43, v43, v232, s[6:7]
	v_cndmask_b32_e64 v42, v42, v232, s[6:7]
	v_pk_mul_f32 v[56:57], v[90:91], v[42:43]
	v_pk_mul_f32 v[84:85], v[150:151], v[58:59]
	v_rndne_f32_e32 v47, v56
	v_rndne_f32_e32 v33, v84
	v_rndne_f32_e32 v56, v57
	v_cvt_i32_f32_e32 v33, v33
	v_cvt_i32_f32_e32 v56, v56
	v_rndne_f32_e32 v39, v85
	v_cvt_i32_f32_e32 v39, v39
	v_cvt_i32_f32_sdwa v47, v47 dst_sel:WORD_1 dst_unused:UNUSED_PAD src0_sel:DWORD
	v_perm_b32 v33, v56, v33, s85
	v_sub_f32_e32 v57, v69, v110
	v_sub_f32_e32 v56, v68, v110
	v_sub_f32_e32 v69, v71, v110
	v_sub_f32_e32 v68, v70, v110
	v_pk_mul_f32 v[56:57], v[130:131], v[56:57]
	v_pk_mul_f32 v[68:69], v[72:73], v[68:69]
	v_pk_fma_f32 v[56:57], v[56:57], v[0:1], v[4:5]
	v_lshlrev_b32_e32 v39, 8, v39
	v_pk_fma_f32 v[68:69], v[68:69], v[2:3], v[6:7]
	v_cndmask_b32_e64 v71, v57, v232, s[6:7]
	v_cndmask_b32_e64 v70, v56, v232, s[6:7]
	v_and_b32_e32 v39, 0xff00, v39
	v_and_b32_e32 v47, 0xff0000, v47
	v_cndmask_b32_e64 v69, v69, v232, s[6:7]
	v_cndmask_b32_e64 v68, v68, v232, s[6:7]
	v_pk_mul_f32 v[56:57], v[76:77], v[70:71]
	v_or3_b32 v84, v33, v39, v47
	v_pk_mul_f32 v[86:87], v[74:75], v[68:69]
	v_rndne_f32_e32 v47, v57
	v_rndne_f32_e32 v33, v87
	v_rndne_f32_e32 v39, v86
	v_cvt_i32_f32_e32 v47, v47
	v_rndne_f32_e32 v56, v56
	v_cvt_i32_f32_e32 v33, v33
	v_cvt_i32_f32_sdwa v39, v39 dst_sel:WORD_1 dst_unused:UNUSED_PAD src0_sel:DWORD
	v_cvt_i32_f32_e32 v56, v56
	v_lshlrev_b32_e32 v47, 8, v47
	v_and_b32_e32 v47, 0xff00, v47
	v_and_b32_e32 v39, 0xff0000, v39
	v_perm_b32 v33, v33, v56, s85
	v_lshl_add_u64 v[86:87], v[92:93], 0, v[40:41]
	v_cvt_pk_f16_f32 v57, v42, v43
	v_cvt_pk_f16_f32 v56, v58, v59
	v_cvt_pk_f16_f32 v59, v68, v69
	v_cvt_pk_f16_f32 v58, v70, v71
	v_or3_b32 v85, v33, v47, v39
	s_nop 0
	v_permlane16_swap_b32_e32 v56, v58
	v_permlane16_swap_b32_e32 v57, v59
	v_lshl_add_u64 v[42:43], v[86:87], 1, s[60:61]
	global_store_dwordx4 v[42:43], v[56:59], off
	v_permlane16_swap_b32_e32 v84, v85
	v_lshl_add_u64 v[42:43], s[72:73], 0, v[86:87]
	global_store_dwordx2 v[42:43], v[84:85], off
	v_sub_f32_e32 v43, v55, v78
	v_sub_f32_e32 v42, v54, v78
	v_pk_mul_f32 v[42:43], v[78:79], v[42:43] op_sel:[1,0]
	v_pk_fma_f32 v[52:53], v[52:53], v[0:1], v[4:5]
	v_pk_fma_f32 v[0:1], v[12:13], v[0:1], v[4:5]
	v_pk_fma_f32 v[42:43], v[42:43], v[2:3], v[6:7]
	v_pk_fma_f32 v[2:3], v[14:15], v[2:3], v[6:7]
	v_cndmask_b32_e64 v5, v1, v232, s[6:7]
	v_cndmask_b32_e64 v4, v0, v232, s[6:7]
	v_cndmask_b32_e64 v53, v53, v232, s[6:7]
	v_cndmask_b32_e64 v52, v52, v232, s[6:7]
	v_cndmask_b32_e64 v3, v3, v232, s[6:7]
	v_cndmask_b32_e64 v2, v2, v232, s[6:7]
	v_pk_mul_f32 v[0:1], v[128:129], v[4:5] op_sel_hi:[0,1]
	v_cndmask_b32_e64 v43, v43, v232, s[6:7]
	v_cndmask_b32_e64 v42, v42, v232, s[6:7]
	v_pk_mul_f32 v[56:57], v[60:61], v[52:53] op_sel_hi:[0,1]
	v_pk_mul_f32 v[6:7], v[128:129], v[2:3] op_sel_hi:[0,1]
	v_rndne_f32_e32 v1, v1
	v_pk_mul_f32 v[54:55], v[60:61], v[42:43] op_sel_hi:[0,1]
	v_rndne_f32_e32 v39, v57
	v_rndne_f32_e32 v7, v7
	v_rndne_f32_e32 v6, v6
	v_cvt_i32_f32_e32 v1, v1
	v_rndne_f32_e32 v0, v0
	v_rndne_f32_e32 v33, v56
	v_cvt_i32_f32_e32 v39, v39
	v_rndne_f32_e32 v47, v54
	v_rndne_f32_e32 v54, v55
	v_cvt_i32_f32_e32 v7, v7
	v_cvt_i32_f32_sdwa v6, v6 dst_sel:WORD_1 dst_unused:UNUSED_PAD src0_sel:DWORD
	v_cvt_i32_f32_e32 v0, v0
	v_cvt_i32_f32_e32 v33, v33
	v_cvt_i32_f32_sdwa v47, v47 dst_sel:WORD_1 dst_unused:UNUSED_PAD src0_sel:DWORD
	v_cvt_i32_f32_e32 v54, v54
	v_lshlrev_b32_e32 v1, 8, v1
	v_lshlrev_b32_e32 v39, 8, v39
	v_and_b32_e32 v6, 0xff0000, v6
	v_and_b32_e32 v1, 0xff00, v1
	v_perm_b32 v0, v7, v0, s85
	v_and_b32_e32 v39, 0xff00, v39
	v_and_b32_e32 v47, 0xff0000, v47
	v_perm_b32 v33, v54, v33, s85
	v_or3_b32 v55, v0, v1, v6
	v_lshl_add_u64 v[6:7], v[62:63], 0, v[40:41]
	v_cvt_pk_f16_f32 v1, v42, v43
	v_cvt_pk_f16_f32 v0, v52, v53
	v_cvt_pk_f16_f32 v3, v2, v3
	v_cvt_pk_f16_f32 v2, v4, v5
	v_or3_b32 v54, v33, v39, v47
	s_nop 0
	v_permlane16_swap_b32_e32 v0, v2
	v_permlane16_swap_b32_e32 v1, v3
	v_lshl_add_u64 v[4:5], v[6:7], 1, s[60:61]
	global_store_dwordx4 v[4:5], v[0:3], off
	v_permlane16_swap_b32_e32 v54, v55
	s_nop 0
	v_lshl_add_u64 v[0:1], s[72:73], 0, v[6:7]
	global_store_dwordx2 v[0:1], v[54:55], off
	v_mov_b32_e32 v0, v196
	v_mov_b32_e32 v1, v197
	v_mov_b32_e32 v2, v198
	v_mov_b32_e32 v3, v199
	v_mov_b32_e32 v4, v200
	v_mov_b32_e32 v5, v201
	v_mov_b32_e32 v6, v202
	v_mov_b32_e32 v7, v203
	v_sub_f32_e32 v15, v17, v38
	v_sub_f32_e32 v14, v16, v38
	v_sub_f32_e32 v17, v19, v38
	v_sub_f32_e32 v16, v18, v38
	v_pk_mul_f32 v[16:17], v[160:161], v[16:17]
	v_pk_mul_f32 v[14:15], v[140:141], v[14:15]
	v_lshl_add_u64 v[12:13], v[112:113], 0, s[4:5]
	v_pk_fma_f32 v[16:17], v[16:17], v[0:1], v[4:5]
	v_pk_fma_f32 v[14:15], v[14:15], v[2:3], v[6:7]
	v_cndmask_b32_e64 v17, v17, v232, s[6:7]
	v_cndmask_b32_e64 v16, v16, v232, s[6:7]
	v_cndmask_b32_e64 v15, v15, v232, s[6:7]
	v_cndmask_b32_e64 v14, v14, v232, s[6:7]
	v_pk_mul_f32 v[34:35], v[114:115], v[16:17]
	v_pk_mul_f32 v[18:19], v[142:143], v[14:15]
	v_rndne_f32_e32 v33, v34
	v_rndne_f32_e32 v34, v35
	v_cvt_i32_f32_e32 v34, v34
	v_rndne_f32_e32 v18, v18
	v_rndne_f32_e32 v19, v19
	v_cvt_i32_f32_e32 v33, v33
	v_cvt_i32_f32_sdwa v18, v18 dst_sel:WORD_1 dst_unused:UNUSED_PAD src0_sel:DWORD
	v_cvt_i32_f32_e32 v19, v19
	v_pk_fma_f32 v[22:23], v[22:23], v[0:1], v[4:5]
	v_lshlrev_b32_e32 v34, 8, v34
	v_pk_fma_f32 v[20:21], v[20:21], v[2:3], v[6:7]
	v_cndmask_b32_e64 v23, v23, v232, s[6:7]
	v_cndmask_b32_e64 v22, v22, v232, s[6:7]
	v_and_b32_e32 v34, 0xff00, v34
	v_and_b32_e32 v18, 0xff0000, v18
	v_perm_b32 v19, v19, v33, s85
	v_cndmask_b32_e64 v21, v21, v232, s[6:7]
	v_cndmask_b32_e64 v20, v20, v232, s[6:7]
	v_pk_mul_f32 v[32:33], v[44:45], v[22:23]
	v_or3_b32 v18, v19, v34, v18
	v_pk_mul_f32 v[34:35], v[146:147], v[20:21]
	v_rndne_f32_e32 v33, v33
	v_rndne_f32_e32 v19, v35
	v_rndne_f32_e32 v34, v34
	v_cvt_i32_f32_e32 v33, v33
	v_rndne_f32_e32 v32, v32
	v_cvt_i32_f32_e32 v19, v19
	v_cvt_i32_f32_sdwa v34, v34 dst_sel:WORD_1 dst_unused:UNUSED_PAD src0_sel:DWORD
	v_cvt_i32_f32_e32 v32, v32
	v_lshlrev_b32_e32 v33, 8, v33
	v_and_b32_e32 v33, 0xff00, v33
	v_and_b32_e32 v34, 0xff0000, v34
	v_perm_b32 v19, v19, v32, s85
	v_or3_b32 v19, v19, v33, v34
	v_lshl_add_u64 v[32:33], v[96:97], 0, v[12:13]
	v_cvt_pk_f16_f32 v15, v14, v15
	v_cvt_pk_f16_f32 v14, v16, v17
	v_cvt_pk_f16_f32 v17, v20, v21
	v_cvt_pk_f16_f32 v16, v22, v23
	s_nop 1
	v_permlane16_swap_b32_e32 v14, v16
	v_permlane16_swap_b32_e32 v15, v17
	v_lshl_add_u64 v[20:21], v[32:33], 1, s[60:61]
	global_store_dwordx4 v[20:21], v[14:17], off
	v_permlane16_swap_b32_e32 v18, v19
	s_nop 0
	v_lshl_add_u64 v[14:15], s[72:73], 0, v[32:33]
	v_sub_f32_e32 v17, v25, v98
	v_sub_f32_e32 v16, v24, v98
	global_store_dwordx2 v[14:15], v[18:19], off
	v_sub_f32_e32 v15, v27, v98
	v_sub_f32_e32 v14, v26, v98
	v_pk_mul_f32 v[16:17], v[156:157], v[16:17]
	v_pk_mul_f32 v[14:15], v[120:121], v[14:15]
	v_pk_fma_f32 v[16:17], v[16:17], v[0:1], v[4:5]
	v_pk_fma_f32 v[14:15], v[14:15], v[2:3], v[6:7]
	v_cndmask_b32_e64 v17, v17, v232, s[6:7]
	v_cndmask_b32_e64 v16, v16, v232, s[6:7]
	v_cndmask_b32_e64 v15, v15, v232, s[6:7]
	v_cndmask_b32_e64 v14, v14, v232, s[6:7]
	v_pk_mul_f32 v[20:21], v[148:149], v[16:17]
	v_pk_mul_f32 v[18:19], v[122:123], v[14:15]
	v_rndne_f32_e32 v21, v21
	v_rndne_f32_e32 v20, v20
	v_cvt_i32_f32_e32 v21, v21
	v_rndne_f32_e32 v18, v18
	v_rndne_f32_e32 v19, v19
	v_cvt_i32_f32_e32 v20, v20
	v_cvt_i32_f32_sdwa v18, v18 dst_sel:WORD_1 dst_unused:UNUSED_PAD src0_sel:DWORD
	v_cvt_i32_f32_e32 v19, v19
	v_lshlrev_b32_e32 v21, 8, v21
	v_and_b32_e32 v21, 0xff00, v21
	v_and_b32_e32 v18, 0xff0000, v18
	v_perm_b32 v19, v19, v20, s85
	v_or3_b32 v18, v19, v21, v18
	v_sub_f32_e32 v21, v31, v46
	v_sub_f32_e32 v20, v30, v46
	v_sub_f32_e32 v23, v29, v46
	v_sub_f32_e32 v22, v28, v46
	v_pk_mul_f32 v[20:21], v[154:155], v[20:21]
	v_pk_mul_f32 v[22:23], v[104:105], v[22:23]
	v_pk_fma_f32 v[20:21], v[20:21], v[0:1], v[4:5]
	v_pk_fma_f32 v[22:23], v[22:23], v[2:3], v[6:7]
	v_cndmask_b32_e64 v21, v21, v232, s[6:7]
	v_cndmask_b32_e64 v20, v20, v232, s[6:7]
	v_cndmask_b32_e64 v23, v23, v232, s[6:7]
	v_cndmask_b32_e64 v22, v22, v232, s[6:7]
	v_pk_mul_f32 v[24:25], v[108:109], v[20:21]
	v_pk_mul_f32 v[26:27], v[106:107], v[22:23]
	v_rndne_f32_e32 v25, v25
	v_rndne_f32_e32 v19, v27
	v_rndne_f32_e32 v26, v26
	v_cvt_i32_f32_e32 v25, v25
	v_rndne_f32_e32 v24, v24
	v_cvt_i32_f32_e32 v19, v19
	v_cvt_i32_f32_sdwa v26, v26 dst_sel:WORD_1 dst_unused:UNUSED_PAD src0_sel:DWORD
	v_cvt_i32_f32_e32 v24, v24
	v_lshlrev_b32_e32 v25, 8, v25
	v_and_b32_e32 v25, 0xff00, v25
	v_and_b32_e32 v26, 0xff0000, v26
	v_perm_b32 v19, v19, v24, s85
	v_or3_b32 v19, v19, v25, v26
	v_lshl_add_u64 v[24:25], v[124:125], 0, v[12:13]
	v_cvt_pk_f16_f32 v15, v14, v15
	v_cvt_pk_f16_f32 v14, v16, v17
	v_cvt_pk_f16_f32 v17, v22, v23
	v_cvt_pk_f16_f32 v16, v20, v21
	s_nop 1
	v_permlane16_swap_b32_e32 v14, v16
	v_permlane16_swap_b32_e32 v15, v17
	v_lshl_add_u64 v[20:21], v[24:25], 1, s[60:61]
	global_store_dwordx4 v[20:21], v[14:17], off
	v_permlane16_swap_b32_e32 v18, v19
	s_nop 0
	v_lshl_add_u64 v[14:15], s[72:73], 0, v[24:25]
	v_sub_f32_e32 v17, v81, v126
	v_sub_f32_e32 v16, v80, v126
	global_store_dwordx2 v[14:15], v[18:19], off
	v_sub_f32_e32 v15, v83, v126
	v_sub_f32_e32 v14, v82, v126
	v_pk_mul_f32 v[16:17], v[152:153], v[16:17]
	v_pk_mul_f32 v[14:15], v[88:89], v[14:15]
	v_pk_fma_f32 v[16:17], v[16:17], v[0:1], v[4:5]
	v_pk_fma_f32 v[14:15], v[14:15], v[2:3], v[6:7]
	v_cndmask_b32_e64 v17, v17, v232, s[6:7]
	v_cndmask_b32_e64 v16, v16, v232, s[6:7]
	v_cndmask_b32_e64 v15, v15, v232, s[6:7]
	v_cndmask_b32_e64 v14, v14, v232, s[6:7]
	v_pk_mul_f32 v[20:21], v[150:151], v[16:17]
	v_pk_mul_f32 v[18:19], v[90:91], v[14:15]
	v_rndne_f32_e32 v21, v21
	v_rndne_f32_e32 v20, v20
	v_cvt_i32_f32_e32 v21, v21
	v_rndne_f32_e32 v18, v18
	v_rndne_f32_e32 v19, v19
	v_cvt_i32_f32_e32 v20, v20
	v_cvt_i32_f32_sdwa v18, v18 dst_sel:WORD_1 dst_unused:UNUSED_PAD src0_sel:DWORD
	v_cvt_i32_f32_e32 v19, v19
	v_lshlrev_b32_e32 v21, 8, v21
	v_and_b32_e32 v21, 0xff00, v21
	v_and_b32_e32 v18, 0xff0000, v18
	v_perm_b32 v19, v19, v20, s85
	v_or3_b32 v18, v19, v21, v18
	v_sub_f32_e32 v21, v65, v110
	v_sub_f32_e32 v20, v64, v110
	v_sub_f32_e32 v23, v67, v110
	v_sub_f32_e32 v22, v66, v110
	v_pk_mul_f32 v[20:21], v[130:131], v[20:21]
	v_pk_mul_f32 v[22:23], v[72:73], v[22:23]
	v_pk_fma_f32 v[20:21], v[20:21], v[0:1], v[4:5]
	v_pk_fma_f32 v[22:23], v[22:23], v[2:3], v[6:7]
	v_cndmask_b32_e64 v21, v21, v232, s[6:7]
	v_cndmask_b32_e64 v20, v20, v232, s[6:7]
	v_cndmask_b32_e64 v23, v23, v232, s[6:7]
	v_cndmask_b32_e64 v22, v22, v232, s[6:7]
	v_pk_mul_f32 v[24:25], v[76:77], v[20:21]
	v_pk_mul_f32 v[26:27], v[74:75], v[22:23]
	v_rndne_f32_e32 v25, v25
	v_rndne_f32_e32 v19, v27
	v_rndne_f32_e32 v26, v26
	v_cvt_i32_f32_e32 v25, v25
	v_rndne_f32_e32 v24, v24
	v_cvt_i32_f32_e32 v19, v19
	v_cvt_i32_f32_sdwa v26, v26 dst_sel:WORD_1 dst_unused:UNUSED_PAD src0_sel:DWORD
	v_cvt_i32_f32_e32 v24, v24
	v_lshlrev_b32_e32 v25, 8, v25
	v_and_b32_e32 v25, 0xff00, v25
	v_and_b32_e32 v26, 0xff0000, v26
	v_perm_b32 v19, v19, v24, s85
	v_or3_b32 v19, v19, v25, v26
	v_lshl_add_u64 v[24:25], v[92:93], 0, v[12:13]
	v_cvt_pk_f16_f32 v15, v14, v15
	v_cvt_pk_f16_f32 v14, v16, v17
	v_cvt_pk_f16_f32 v17, v22, v23
	v_cvt_pk_f16_f32 v16, v20, v21
	s_nop 1
	v_permlane16_swap_b32_e32 v14, v16
	v_permlane16_swap_b32_e32 v15, v17
	v_lshl_add_u64 v[20:21], v[24:25], 1, s[60:61]
	v_pk_fma_f32 v[8:9], v[8:9], v[0:1], v[4:5]
	global_store_dwordx4 v[20:21], v[14:17], off
	v_permlane16_swap_b32_e32 v18, v19
	s_nop 0
	v_lshl_add_u64 v[14:15], s[72:73], 0, v[24:25]
	v_pk_fma_f32 v[10:11], v[10:11], v[2:3], v[6:7]
	v_cndmask_b32_e64 v9, v9, v232, s[6:7]
	v_cndmask_b32_e64 v8, v8, v232, s[6:7]
	global_store_dwordx2 v[14:15], v[18:19], off
	v_cndmask_b32_e64 v11, v11, v232, s[6:7]
	v_cndmask_b32_e64 v10, v10, v232, s[6:7]
	v_pk_mul_f32 v[14:15], v[128:129], v[8:9] op_sel_hi:[0,1]
	v_pk_mul_f32 v[16:17], v[128:129], v[10:11] op_sel_hi:[0,1]
	v_rndne_f32_e32 v15, v15
	v_rndne_f32_e32 v17, v17
	v_rndne_f32_e32 v16, v16
	v_cvt_i32_f32_e32 v15, v15
	v_rndne_f32_e32 v14, v14
	v_cvt_i32_f32_e32 v17, v17
	v_cvt_i32_f32_sdwa v16, v16 dst_sel:WORD_1 dst_unused:UNUSED_PAD src0_sel:DWORD
	v_cvt_i32_f32_e32 v14, v14
	v_lshlrev_b32_e32 v15, 8, v15
	v_and_b32_e32 v15, 0xff00, v15
	v_and_b32_e32 v16, 0xff0000, v16
	v_perm_b32 v14, v17, v14, s85
	v_or3_b32 v15, v14, v15, v16
	v_sub_f32_e32 v17, v49, v78
	v_sub_f32_e32 v16, v48, v78
	v_sub_f32_e32 v19, v51, v78
	v_sub_f32_e32 v18, v50, v78
	v_pk_mul_f32 v[16:17], v[78:79], v[16:17] op_sel:[1,0]
	v_pk_mul_f32 v[18:19], v[78:79], v[18:19] op_sel:[1,0]
	v_pk_fma_f32 v[0:1], v[16:17], v[0:1], v[4:5]
	v_pk_fma_f32 v[2:3], v[18:19], v[2:3], v[6:7]
	v_cndmask_b32_e64 v5, v1, v232, s[6:7]
	v_cndmask_b32_e64 v4, v0, v232, s[6:7]
	v_cndmask_b32_e64 v3, v3, v232, s[6:7]
	v_cndmask_b32_e64 v2, v2, v232, s[6:7]
	v_pk_mul_f32 v[0:1], v[60:61], v[4:5] op_sel_hi:[0,1]
	v_pk_mul_f32 v[6:7], v[60:61], v[2:3] op_sel_hi:[0,1]
	v_rndne_f32_e32 v1, v1
	v_rndne_f32_e32 v7, v7
	v_rndne_f32_e32 v6, v6
	v_cvt_i32_f32_e32 v1, v1
	v_rndne_f32_e32 v0, v0
	v_cvt_i32_f32_e32 v7, v7
	v_cvt_i32_f32_sdwa v6, v6 dst_sel:WORD_1 dst_unused:UNUSED_PAD src0_sel:DWORD
	v_cvt_i32_f32_e32 v0, v0
	v_lshlrev_b32_e32 v1, 8, v1
	v_and_b32_e32 v1, 0xff00, v1
	v_and_b32_e32 v6, 0xff0000, v6
	v_perm_b32 v0, v7, v0, s85
	v_or3_b32 v14, v0, v1, v6
	v_lshl_add_u64 v[6:7], v[62:63], 0, v[12:13]
	v_cvt_pk_f16_f32 v1, v2, v3
	v_cvt_pk_f16_f32 v0, v4, v5
	v_cvt_pk_f16_f32 v3, v10, v11
	v_cvt_pk_f16_f32 v2, v8, v9
	s_nop 1
	v_permlane16_swap_b32_e32 v0, v2
	v_permlane16_swap_b32_e32 v1, v3
	v_lshl_add_u64 v[4:5], v[6:7], 1, s[60:61]
	global_store_dwordx4 v[4:5], v[0:3], off
	v_permlane16_swap_b32_e32 v14, v15
	s_nop 0
	v_lshl_add_u64 v[0:1], s[72:73], 0, v[6:7]
	global_store_dwordx2 v[0:1], v[14:15], off
